# K-loop: MFMA blocks at priority 2, closing barrier 1 MFMA early with the trailing MFMA at priority 3
# baseline (speedup 1.0000x reference)
; #define PG8_STAGE(bufoff, gbase, voff) do { _Pragma("unroll") for (int _i = 0; _i < 2; ++_i) \
;         __builtin_amdgcn_global_load_lds((const unsigned*)((const char*)(gbase) + (voff)[_i]), (PG8_LAS unsigned*)(lds + (bufoff) + ldsw + _i * 8192), 16, 0, 0); } while (0)
; #define PG8_LDA(dst, b, h) do { _Pragma("unroll") for (int m = 0; m < 4; ++m) _Pragma("unroll") for (int k = 0; k < 2; ++k) dst[m][k] = *(const PG8_LAS bf16x8*)(lds + PG8_SA(b, h) + aoff + m * 2048 + k * 1024); } while (0)
; #define PG8_LDB(dst, b, h) do { _Pragma("unroll") for (int n = 0; n < 2; ++n) _Pragma("unroll") for (int k = 0; k < 2; ++k) dst[n][k] = *(const PG8_LAS bf16x8*)(lds + PG8_SB(b, h) + boff + n * 2048 + k * 1024); } while (0)
; #define PG8_MMA(ai, bj, At, Bt) do { __builtin_amdgcn_s_setprio(1); _Pragma("unroll") for (int m = 0; m < 4; ++m) _Pragma("unroll") for (int n = 0; n < 2; ++n) _Pragma("unroll") for (int k = 0; k < 2; ++k) \
;         acc[ai][bj][m][n] = __builtin_amdgcn_mfma_f32_16x16x32_bf16(Bt[n][k], At[m][k], acc[ai][bj][m][n], 0, 0, 0); __builtin_amdgcn_s_setprio(0); } while (0)
; #define PG8_WAIT_V(n) asm volatile("s_waitcnt vmcnt(" #n ")" ::: "memory")
; #define PG8_WAIT_L(n) asm volatile("s_waitcnt lgkmcnt(" #n ")" ::: "memory")
; template <class Epi, class Sched, bool ALIGN_EPI = false, bool SP2 = false>
; __device__ __forceinline__ void gemm_phase(PG8_LAS unsigned char* lds, const Gemm g, const Sched& S, const Epi& E, const int wv  ) {
;     ...
;             const bool last = (t == nt - 2);
;             const char* a1 = cA + (size_t)(t + 1) * kstep;
;             const char* a2 = last ? nA : cA + (size_t)(t + 2) * kstep; const char* b2 = last ? nB : cB + (size_t)(t + 2) * kstep;
;             const char* a3 = a2 + kstep; const char* b3 = b2 + kstep;
;             if (last && has_next) S.a_ready(nxt);
;             if constexpr (SP2) {
;             PG8_LDB(B0, 0, 0); PG8_LDB(B1, 0, 1); PG8_SCHED; PG8_LDA(At, 0, 0); PG8_STAGE(PG8_SA(1, 1), a1 + hstepA, voffA);
;             PG8_WAIT_V(8); PG8_WAIT_L(0); PG8_BAR; PG8_MMA(0, 0, At, B0); PG8_MMA(0, 1, At, B1); PG8_BAR; PG8_SCHED;
;             PG8_LDA(At, 0, 1); PG8_STAGE(PG8_SB(0, 0), b2, voffB); PG8_STAGE(PG8_SB(0, 1), b2 + hstepB, voffB); PG8_STAGE(PG8_SA(0, 0), a2, voffA);
;             PG8_WAIT_V(8); PG8_WAIT_L(0); PG8_BAR; PG8_MMA(1, 0, At, B0); PG8_MMA(1, 1, At, B1); PG8_BAR; PG8_SCHED;
.LBB0_121:
	ds_read_b128 v[146:149], v152
	ds_read_b128 v[156:159], v152 offset:1024
	ds_read_b128 v[160:163], v152 offset:2048
	ds_read_b128 v[164:167], v152 offset:3072
	ds_read_b128 v[168:171], v153
	ds_read_b128 v[172:175], v153 offset:1024
	ds_read_b128 v[176:179], v153 offset:2048
	ds_read_b128 v[180:183], v153 offset:3072
	s_add_u32 s66, s64, 0xfff00080
	s_addc_u32 s67, s65, -1
	s_cmp_eq_u32 s96, 60
	s_cselect_b32 s69, s57, s67
	s_cselect_b32 s68, s92, s66
	s_cselect_b32 s67, s55, s95
	s_cselect_b32 s66, s93, s94
	v_lshl_add_u64 v[216:217], s[64:65], 0, v[138:139]
	s_add_i32 m0, s75, 0xc000
	ds_read_b128 v[184:187], v154
	ds_read_b128 v[188:191], v154 offset:1024
	ds_read_b128 v[192:195], v154 offset:2048
	ds_read_b128 v[196:199], v154 offset:3072
	ds_read_b128 v[200:203], v154 offset:4096
	ds_read_b128 v[204:207], v154 offset:5120
	ds_read_b128 v[208:211], v154 offset:6144
	ds_read_b128 v[212:215], v154 offset:7168
	global_load_lds_dwordx4 v[216:217], off
	v_lshl_add_u64 v[216:217], s[64:65], 0, v[140:141]
	s_add_i32 m0, s75, 0xe000
	s_nop 0
	global_load_lds_dwordx4 v[216:217], off
	s_waitcnt vmcnt(8)
	s_waitcnt lgkmcnt(0)
	s_barrier
	s_setprio 2
	s_waitcnt lgkmcnt(0)
	v_mfma_f32_16x16x32_bf16 v[76:79], v[146:149], v[184:187], v[76:79]
	v_mfma_f32_16x16x32_bf16 v[72:75], v[160:163], v[184:187], v[72:75]
	v_mfma_f32_16x16x32_bf16 v[68:71], v[146:149], v[192:195], v[68:71]
	v_mfma_f32_16x16x32_bf16 v[64:67], v[160:163], v[192:195], v[64:67]
	v_mfma_f32_16x16x32_bf16 v[56:59], v[146:149], v[200:203], v[56:59]
	v_mfma_f32_16x16x32_bf16 v[52:55], v[160:163], v[200:203], v[52:55]
	v_mfma_f32_16x16x32_bf16 v[44:47], v[146:149], v[208:211], v[44:47]
	v_mfma_f32_16x16x32_bf16 v[40:43], v[160:163], v[208:211], v[40:43]
	v_mfma_f32_16x16x32_bf16 v[76:79], v[156:159], v[188:191], v[76:79]
	v_mfma_f32_16x16x32_bf16 v[72:75], v[164:167], v[188:191], v[72:75]
	v_mfma_f32_16x16x32_bf16 v[68:71], v[156:159], v[196:199], v[68:71]
	v_mfma_f32_16x16x32_bf16 v[64:67], v[164:167], v[196:199], v[64:67]
	v_mfma_f32_16x16x32_bf16 v[56:59], v[156:159], v[204:207], v[56:59]
	v_mfma_f32_16x16x32_bf16 v[52:55], v[164:167], v[204:207], v[52:55]
	v_mfma_f32_16x16x32_bf16 v[44:47], v[156:159], v[212:215], v[44:47]
	v_mfma_f32_16x16x32_bf16 v[40:43], v[164:167], v[212:215], v[40:43]
	s_setprio 0
	s_setprio 2
	v_mfma_f32_16x16x32_bf16 v[124:127], v[168:171], v[184:187], v[124:127]
	v_mfma_f32_16x16x32_bf16 v[120:123], v[176:179], v[184:187], v[120:123]
	v_mfma_f32_16x16x32_bf16 v[116:119], v[168:171], v[192:195], v[116:119]
	v_mfma_f32_16x16x32_bf16 v[112:115], v[176:179], v[192:195], v[112:115]
	v_mfma_f32_16x16x32_bf16 v[108:111], v[168:171], v[200:203], v[108:111]
	v_mfma_f32_16x16x32_bf16 v[104:107], v[176:179], v[200:203], v[104:107]
	v_mfma_f32_16x16x32_bf16 v[100:103], v[168:171], v[208:211], v[100:103]
	v_mfma_f32_16x16x32_bf16 v[96:99], v[176:179], v[208:211], v[96:99]
	v_mfma_f32_16x16x32_bf16 v[124:127], v[172:175], v[188:191], v[124:127]
	v_mfma_f32_16x16x32_bf16 v[120:123], v[180:183], v[188:191], v[120:123]
	v_mfma_f32_16x16x32_bf16 v[116:119], v[172:175], v[196:199], v[116:119]
	v_mfma_f32_16x16x32_bf16 v[112:115], v[180:183], v[196:199], v[112:115]
	v_mfma_f32_16x16x32_bf16 v[108:111], v[172:175], v[204:207], v[108:111]
	v_mfma_f32_16x16x32_bf16 v[104:107], v[180:183], v[204:207], v[104:107]
	v_mfma_f32_16x16x32_bf16 v[100:103], v[172:175], v[212:215], v[100:103]
	s_setprio 3
	s_barrier
	v_mfma_f32_16x16x32_bf16 v[96:99], v[180:183], v[212:215], v[96:99]
	s_setprio 0
	s_add_i32 s97, s84, s74
	v_lshl_add_u64 v[216:217], s[66:67], 0, v[130:131]
	s_mov_b32 m0, s97
	ds_read_b128 v[184:187], v154 offset:16384
	ds_read_b128 v[188:191], v154 offset:17408
	ds_read_b128 v[192:195], v154 offset:18432
	ds_read_b128 v[196:199], v154 offset:19456
	ds_read_b128 v[200:203], v154 offset:20480
	ds_read_b128 v[204:207], v154 offset:21504
	ds_read_b128 v[208:211], v154 offset:22528
	ds_read_b128 v[212:215], v154 offset:23552
	global_load_lds_dwordx4 v[216:217], off
	s_add_i32 m0, s97, 0x2000
	s_add_u32 vcc_lo, s66, 0x100000
	v_lshl_add_u64 v[218:219], s[66:67], 0, v[134:135]
	s_addc_u32 vcc_hi, s67, 0
	s_add_i32 s97, s85, s74
	global_load_lds_dwordx4 v[218:219], off
	v_lshl_add_u64 v[220:221], vcc, 0, v[130:131]
	s_mov_b32 m0, s97
	v_lshl_add_u64 v[222:223], s[68:69], 0, v[132:133]
	global_load_lds_dwordx4 v[220:221], off
	v_lshl_add_u64 v[220:221], vcc, 0, v[134:135]
	s_add_i32 m0, s97, 0x2000
	s_nop 0
	global_load_lds_dwordx4 v[220:221], off
	v_lshl_add_u64 v[220:221], s[68:69], 0, v[128:129]
	s_mov_b32 m0, s75
	s_nop 0
	global_load_lds_dwordx4 v[220:221], off
	s_mov_b32 m0, s76
	s_nop 0
	global_load_lds_dwordx4 v[222:223], off
	s_waitcnt vmcnt(8)
	s_waitcnt lgkmcnt(0)
	s_barrier
; #define PG8_STAGE(bufoff, gbase, voff) do { _Pragma("unroll") for (int _i = 0; _i < 2; ++_i) \
;         __builtin_amdgcn_global_load_lds((const unsigned*)((const char*)(gbase) + (voff)[_i]), (PG8_LAS unsigned*)(lds + (bufoff) + ldsw + _i * 8192), 16, 0, 0); } while (0)
; #define PG8_LDA(dst, b, h) do { _Pragma("unroll") for (int m = 0; m < 4; ++m) _Pragma("unroll") for (int k = 0; k < 2; ++k) dst[m][k] = *(const PG8_LAS bf16x8*)(lds + PG8_SA(b, h) + aoff + m * 2048 + k * 1024); } while (0)
; #define PG8_LDB(dst, b, h) do { _Pragma("unroll") for (int n = 0; n < 2; ++n) _Pragma("unroll") for (int k = 0; k < 2; ++k) dst[n][k] = *(const PG8_LAS bf16x8*)(lds + PG8_SB(b, h) + boff + n * 2048 + k * 1024); } while (0)
; #define PG8_MMA(ai, bj, At, Bt) do { __builtin_amdgcn_s_setprio(1); _Pragma("unroll") for (int m = 0; m < 4; ++m) _Pragma("unroll") for (int n = 0; n < 2; ++n) _Pragma("unroll") for (int k = 0; k < 2; ++k) \
;         acc[ai][bj][m][n] = __builtin_amdgcn_mfma_f32_16x16x32_bf16(Bt[n][k], At[m][k], acc[ai][bj][m][n], 0, 0, 0); __builtin_amdgcn_s_setprio(0); } while (0)
; #define PG8_WAIT_V(n) asm volatile("s_waitcnt vmcnt(" #n ")" ::: "memory")
; #define PG8_WAIT_L(n) asm volatile("s_waitcnt lgkmcnt(" #n ")" ::: "memory")
; #define PG8_BAR __builtin_amdgcn_s_barrier()
; #define PG8_SCHED __builtin_amdgcn_sched_barrier(0)
; template <class Epi, class Sched, bool ALIGN_EPI = false, bool SP2 = false>
; __device__ __forceinline__ void gemm_phase(PG8_LAS unsigned char* lds, const Gemm g, const Sched& S, const Epi& E, const int wv  ) {
;     ...
;             PG8_WAIT_V(8); PG8_WAIT_L(0); PG8_BAR; PG8_MMA(1, 0, At, B0); PG8_MMA(1, 1, At, B1); PG8_BAR; PG8_SCHED;
;             PG8_LDB(B0, 1, 0); PG8_LDB(B1, 1, 1); PG8_SCHED; PG8_LDA(At, 1, 0); PG8_STAGE(PG8_SA(0, 1), a2 + hstepA, voffA);
;             PG8_WAIT_V(8); PG8_WAIT_L(0); PG8_BAR; PG8_MMA(0, 0, At, B0); PG8_MMA(0, 1, At, B1); PG8_BAR; PG8_SCHED;
	s_setprio 2
	s_waitcnt lgkmcnt(0)
	v_mfma_f32_16x16x32_bf16 v[28:31], v[146:149], v[184:187], v[28:31]
	v_mfma_f32_16x16x32_bf16 v[24:27], v[160:163], v[184:187], v[24:27]
	v_mfma_f32_16x16x32_bf16 v[20:23], v[146:149], v[192:195], v[20:23]
	v_mfma_f32_16x16x32_bf16 v[16:19], v[160:163], v[192:195], v[16:19]
	v_mfma_f32_16x16x32_bf16 v[12:15], v[146:149], v[200:203], v[12:15]
	v_mfma_f32_16x16x32_bf16 v[8:11], v[160:163], v[200:203], v[8:11]
	v_mfma_f32_16x16x32_bf16 v[4:7], v[146:149], v[208:211], v[4:7]
	v_mfma_f32_16x16x32_bf16 v[0:3], v[160:163], v[208:211], v[0:3]
	v_mfma_f32_16x16x32_bf16 v[28:31], v[156:159], v[188:191], v[28:31]
	v_mfma_f32_16x16x32_bf16 v[24:27], v[164:167], v[188:191], v[24:27]
	v_mfma_f32_16x16x32_bf16 v[20:23], v[156:159], v[196:199], v[20:23]
	v_mfma_f32_16x16x32_bf16 v[16:19], v[164:167], v[196:199], v[16:19]
	v_mfma_f32_16x16x32_bf16 v[12:15], v[156:159], v[204:207], v[12:15]
	v_mfma_f32_16x16x32_bf16 v[8:11], v[164:167], v[204:207], v[8:11]
	v_mfma_f32_16x16x32_bf16 v[4:7], v[156:159], v[212:215], v[4:7]
	v_mfma_f32_16x16x32_bf16 v[0:3], v[164:167], v[212:215], v[0:3]
	s_setprio 0
	s_setprio 2
	v_mfma_f32_16x16x32_bf16 v[92:95], v[168:171], v[184:187], v[92:95]
	v_mfma_f32_16x16x32_bf16 v[88:91], v[176:179], v[184:187], v[88:91]
	v_mfma_f32_16x16x32_bf16 v[84:87], v[168:171], v[192:195], v[84:87]
	v_mfma_f32_16x16x32_bf16 v[80:83], v[176:179], v[192:195], v[80:83]
	v_mfma_f32_16x16x32_bf16 v[60:63], v[168:171], v[200:203], v[60:63]
	v_mfma_f32_16x16x32_bf16 v[48:51], v[176:179], v[200:203], v[48:51]
	v_mfma_f32_16x16x32_bf16 v[36:39], v[168:171], v[208:211], v[36:39]
	v_mfma_f32_16x16x32_bf16 v[32:35], v[176:179], v[208:211], v[32:35]
	v_mfma_f32_16x16x32_bf16 v[92:95], v[172:175], v[188:191], v[92:95]
	v_mfma_f32_16x16x32_bf16 v[88:91], v[180:183], v[188:191], v[88:91]
	v_mfma_f32_16x16x32_bf16 v[84:87], v[172:175], v[196:199], v[84:87]
	v_mfma_f32_16x16x32_bf16 v[80:83], v[180:183], v[196:199], v[80:83]
	v_mfma_f32_16x16x32_bf16 v[60:63], v[172:175], v[204:207], v[60:63]
	v_mfma_f32_16x16x32_bf16 v[48:51], v[180:183], v[204:207], v[48:51]
	v_mfma_f32_16x16x32_bf16 v[36:39], v[172:175], v[212:215], v[36:39]
	s_setprio 3
	s_barrier
	v_mfma_f32_16x16x32_bf16 v[32:35], v[180:183], v[212:215], v[32:35]
	s_setprio 0
	s_add_i32 s97, 0, 0x18000
	v_add_u32_e32 v155, s97, v150
	s_add_i32 vcc_lo, 0, 0x1c000
	ds_read_b128 v[146:149], v155
	ds_read_b128 v[156:159], v155 offset:1024
	ds_read_b128 v[160:163], v155 offset:2048
	ds_read_b128 v[164:167], v155 offset:3072
	v_add_u32_e32 v155, vcc_lo, v150
	ds_read_b128 v[168:171], v155
	ds_read_b128 v[172:175], v155 offset:1024
	ds_read_b128 v[176:179], v155 offset:2048
	ds_read_b128 v[180:183], v155 offset:3072
	s_add_u32 s68, s68, 0x100000
	s_addc_u32 s69, s69, 0
	s_mov_b32 m0, s77
	v_lshl_add_u64 v[224:225], s[68:69], 0, v[128:129]
	ds_read_b128 v[184:187], v154 offset:32768
	ds_read_b128 v[188:191], v154 offset:33792
	ds_read_b128 v[192:195], v154 offset:34816
	ds_read_b128 v[196:199], v154 offset:35840
	ds_read_b128 v[200:203], v154 offset:36864
	ds_read_b128 v[204:207], v154 offset:37888
	ds_read_b128 v[208:211], v154 offset:38912
	ds_read_b128 v[212:215], v154 offset:39936
	global_load_lds_dwordx4 v[224:225], off
	v_lshl_add_u64 v[224:225], s[68:69], 0, v[132:133]
	s_mov_b32 m0, s78
	s_nop 0
	global_load_lds_dwordx4 v[224:225], off
	s_waitcnt vmcnt(8)
	s_waitcnt lgkmcnt(0)
	s_barrier
	s_setprio 2
	s_waitcnt lgkmcnt(0)
	v_mfma_f32_16x16x32_bf16 v[76:79], v[146:149], v[184:187], v[76:79]
	v_mfma_f32_16x16x32_bf16 v[72:75], v[160:163], v[184:187], v[72:75]
	v_mfma_f32_16x16x32_bf16 v[68:71], v[146:149], v[192:195], v[68:71]
	v_mfma_f32_16x16x32_bf16 v[64:67], v[160:163], v[192:195], v[64:67]
	v_mfma_f32_16x16x32_bf16 v[56:59], v[146:149], v[200:203], v[56:59]
	v_mfma_f32_16x16x32_bf16 v[52:55], v[160:163], v[200:203], v[52:55]
	v_mfma_f32_16x16x32_bf16 v[44:47], v[146:149], v[208:211], v[44:47]
	v_mfma_f32_16x16x32_bf16 v[40:43], v[160:163], v[208:211], v[40:43]
	v_mfma_f32_16x16x32_bf16 v[76:79], v[156:159], v[188:191], v[76:79]
	v_mfma_f32_16x16x32_bf16 v[72:75], v[164:167], v[188:191], v[72:75]
	v_mfma_f32_16x16x32_bf16 v[68:71], v[156:159], v[196:199], v[68:71]
	v_mfma_f32_16x16x32_bf16 v[64:67], v[164:167], v[196:199], v[64:67]
	v_mfma_f32_16x16x32_bf16 v[56:59], v[156:159], v[204:207], v[56:59]
	v_mfma_f32_16x16x32_bf16 v[52:55], v[164:167], v[204:207], v[52:55]
	v_mfma_f32_16x16x32_bf16 v[44:47], v[156:159], v[212:215], v[44:47]
	v_mfma_f32_16x16x32_bf16 v[40:43], v[164:167], v[212:215], v[40:43]
	s_setprio 0
	s_setprio 2
	v_mfma_f32_16x16x32_bf16 v[124:127], v[168:171], v[184:187], v[124:127]
	v_mfma_f32_16x16x32_bf16 v[120:123], v[176:179], v[184:187], v[120:123]
	v_mfma_f32_16x16x32_bf16 v[116:119], v[168:171], v[192:195], v[116:119]
	v_mfma_f32_16x16x32_bf16 v[112:115], v[176:179], v[192:195], v[112:115]
	v_mfma_f32_16x16x32_bf16 v[108:111], v[168:171], v[200:203], v[108:111]
	v_mfma_f32_16x16x32_bf16 v[104:107], v[176:179], v[200:203], v[104:107]
	v_mfma_f32_16x16x32_bf16 v[100:103], v[168:171], v[208:211], v[100:103]
	v_mfma_f32_16x16x32_bf16 v[96:99], v[176:179], v[208:211], v[96:99]
	v_mfma_f32_16x16x32_bf16 v[124:127], v[172:175], v[188:191], v[124:127]
	v_mfma_f32_16x16x32_bf16 v[120:123], v[180:183], v[188:191], v[120:123]
	v_mfma_f32_16x16x32_bf16 v[116:119], v[172:175], v[196:199], v[116:119]
	v_mfma_f32_16x16x32_bf16 v[112:115], v[180:183], v[196:199], v[112:115]
	v_mfma_f32_16x16x32_bf16 v[108:111], v[172:175], v[204:207], v[108:111]
	v_mfma_f32_16x16x32_bf16 v[104:107], v[180:183], v[204:207], v[104:107]
	v_mfma_f32_16x16x32_bf16 v[100:103], v[172:175], v[212:215], v[100:103]
	s_setprio 3
	s_barrier
; #define PG8_STAGE(bufoff, gbase, voff) do { _Pragma("unroll") for (int _i = 0; _i < 2; ++_i) \
;         __builtin_amdgcn_global_load_lds((const unsigned*)((const char*)(gbase) + (voff)[_i]), (PG8_LAS unsigned*)(lds + (bufoff) + ldsw + _i * 8192), 16, 0, 0); } while (0)
; #define PG8_LDA(dst, b, h) do { _Pragma("unroll") for (int m = 0; m < 4; ++m) _Pragma("unroll") for (int k = 0; k < 2; ++k) dst[m][k] = *(const PG8_LAS bf16x8*)(lds + PG8_SA(b, h) + aoff + m * 2048 + k * 1024); } while (0)
; #define PG8_MMA(ai, bj, At, Bt) do { __builtin_amdgcn_s_setprio(1); _Pragma("unroll") for (int m = 0; m < 4; ++m) _Pragma("unroll") for (int n = 0; n < 2; ++n) _Pragma("unroll") for (int k = 0; k < 2; ++k) \
;         acc[ai][bj][m][n] = __builtin_amdgcn_mfma_f32_16x16x32_bf16(Bt[n][k], At[m][k], acc[ai][bj][m][n], 0, 0, 0); __builtin_amdgcn_s_setprio(0); } while (0)
; #define PG8_WAIT_V(n) asm volatile("s_waitcnt vmcnt(" #n ")" ::: "memory")
; #define PG8_WAIT_L(n) asm volatile("s_waitcnt lgkmcnt(" #n ")" ::: "memory")
; #define PG8_BAR __builtin_amdgcn_s_barrier()
; #define PG8_SCHED __builtin_amdgcn_sched_barrier(0)
; template <class Epi, class Sched, bool ALIGN_EPI = false, bool SP2 = false>
; __device__ __forceinline__ void gemm_phase(PG8_LAS unsigned char* lds, const Gemm g, const Sched& S, const Epi& E, const int wv  ) {
;     ...
;         for (int t = 0; t < nt; t += 2) {
;             const bool last = (t == nt - 2);
;     ...
;             PG8_WAIT_V(8); PG8_WAIT_L(0); PG8_BAR; PG8_MMA(0, 0, At, B0); PG8_MMA(0, 1, At, B1); PG8_BAR; PG8_SCHED;
;             PG8_LDA(At, 1, 1); PG8_STAGE(PG8_SB(1, 0), b3, voffB); PG8_STAGE(PG8_SB(1, 1), b3 + hstepB, voffB); PG8_STAGE(PG8_SA(1, 0), a3, voffA);
;             PG8_WAIT_V(8); PG8_WAIT_L(0); PG8_BAR; PG8_MMA(1, 0, At, B0); PG8_MMA(1, 1, At, B1); PG8_BAR; PG8_SCHED;
	v_mfma_f32_16x16x32_bf16 v[96:99], v[180:183], v[212:215], v[96:99]
	s_setprio 0
	s_add_i32 s68, s97, s74
	v_lshl_add_u64 v[216:217], v[216:217], 0, s[18:19]
	s_mov_b32 m0, s68
	ds_read_b128 v[184:187], v154 offset:49152
	ds_read_b128 v[188:191], v154 offset:50176
	ds_read_b128 v[192:195], v154 offset:51200
	ds_read_b128 v[196:199], v154 offset:52224
	ds_read_b128 v[200:203], v154 offset:53248
	ds_read_b128 v[204:207], v154 offset:54272
	ds_read_b128 v[208:211], v154 offset:55296
	ds_read_b128 v[212:215], v154 offset:56320
	global_load_lds_dwordx4 v[216:217], off
	s_add_i32 m0, s68, 0x2000
	s_add_u32 s66, s66, 0x100080
	v_lshl_add_u64 v[216:217], v[218:219], 0, s[18:19]
	s_addc_u32 s67, s67, 0
	s_add_i32 s68, vcc_lo, s74
	global_load_lds_dwordx4 v[216:217], off
	v_lshl_add_u64 v[216:217], s[66:67], 0, v[130:131]
	s_mov_b32 m0, s68
	s_nop 0
	global_load_lds_dwordx4 v[216:217], off
	v_lshl_add_u64 v[216:217], s[66:67], 0, v[134:135]
	s_add_i32 m0, s68, 0x2000
	s_nop 0
	global_load_lds_dwordx4 v[216:217], off
	v_lshl_add_u64 v[216:217], v[220:221], 0, s[18:19]
	s_mov_b32 m0, s81
	s_nop 0
	global_load_lds_dwordx4 v[216:217], off
	v_lshl_add_u64 v[216:217], v[222:223], 0, s[18:19]
	s_mov_b32 m0, s82
	s_nop 0
	global_load_lds_dwordx4 v[216:217], off
	s_waitcnt vmcnt(8)
	s_waitcnt lgkmcnt(0)
	s_barrier
	s_setprio 2
	s_waitcnt lgkmcnt(0)
	v_mfma_f32_16x16x32_bf16 v[28:31], v[146:149], v[184:187], v[28:31]
	v_mfma_f32_16x16x32_bf16 v[24:27], v[160:163], v[184:187], v[24:27]
	v_mfma_f32_16x16x32_bf16 v[20:23], v[146:149], v[192:195], v[20:23]
	v_mfma_f32_16x16x32_bf16 v[16:19], v[160:163], v[192:195], v[16:19]
	v_mfma_f32_16x16x32_bf16 v[12:15], v[146:149], v[200:203], v[12:15]
	v_mfma_f32_16x16x32_bf16 v[8:11], v[160:163], v[200:203], v[8:11]
	v_mfma_f32_16x16x32_bf16 v[4:7], v[146:149], v[208:211], v[4:7]
	v_mfma_f32_16x16x32_bf16 v[0:3], v[160:163], v[208:211], v[0:3]
	v_mfma_f32_16x16x32_bf16 v[28:31], v[156:159], v[188:191], v[28:31]
	v_mfma_f32_16x16x32_bf16 v[24:27], v[164:167], v[188:191], v[24:27]
	v_mfma_f32_16x16x32_bf16 v[20:23], v[156:159], v[196:199], v[20:23]
	v_mfma_f32_16x16x32_bf16 v[16:19], v[164:167], v[196:199], v[16:19]
	v_mfma_f32_16x16x32_bf16 v[12:15], v[156:159], v[204:207], v[12:15]
	v_mfma_f32_16x16x32_bf16 v[8:11], v[164:167], v[204:207], v[8:11]
	v_mfma_f32_16x16x32_bf16 v[4:7], v[156:159], v[212:215], v[4:7]
	v_mfma_f32_16x16x32_bf16 v[0:3], v[164:167], v[212:215], v[0:3]
	s_setprio 0
	s_setprio 2
	v_mfma_f32_16x16x32_bf16 v[92:95], v[168:171], v[184:187], v[92:95]
	v_mfma_f32_16x16x32_bf16 v[88:91], v[176:179], v[184:187], v[88:91]
	v_mfma_f32_16x16x32_bf16 v[84:87], v[168:171], v[192:195], v[84:87]
	v_mfma_f32_16x16x32_bf16 v[80:83], v[176:179], v[192:195], v[80:83]
	v_mfma_f32_16x16x32_bf16 v[60:63], v[168:171], v[200:203], v[60:63]
	v_mfma_f32_16x16x32_bf16 v[48:51], v[176:179], v[200:203], v[48:51]
	v_mfma_f32_16x16x32_bf16 v[36:39], v[168:171], v[208:211], v[36:39]
	v_mfma_f32_16x16x32_bf16 v[32:35], v[176:179], v[208:211], v[32:35]
	v_mfma_f32_16x16x32_bf16 v[92:95], v[172:175], v[188:191], v[92:95]
	v_mfma_f32_16x16x32_bf16 v[88:91], v[180:183], v[188:191], v[88:91]
	v_mfma_f32_16x16x32_bf16 v[84:87], v[172:175], v[196:199], v[84:87]
	v_mfma_f32_16x16x32_bf16 v[80:83], v[180:183], v[196:199], v[80:83]
	v_mfma_f32_16x16x32_bf16 v[60:63], v[172:175], v[204:207], v[60:63]
	v_mfma_f32_16x16x32_bf16 v[48:51], v[180:183], v[204:207], v[48:51]
	v_mfma_f32_16x16x32_bf16 v[36:39], v[172:175], v[212:215], v[36:39]
	s_setprio 3
	s_barrier
	v_mfma_f32_16x16x32_bf16 v[32:35], v[180:183], v[212:215], v[32:35]
	s_setprio 0
	s_add_i32 s96, s96, 2
	s_add_u32 s64, s64, 0x100
	s_addc_u32 s65, s65, 0
	s_add_u32 s94, s94, 0x100
	s_addc_u32 s95, s95, 0
	s_cmp_gt_u32 s96, 61
	s_cbranch_scc0 .LBB0_121
	s_and_b64 vcc, exec, s[20:21]
	s_cbranch_vccz .LBB0_124
	s_barrier

; #define PG8_STAGE(bufoff, gbase, voff) do { _Pragma("unroll") for (int _i = 0; _i < 2; ++_i) \
;         __builtin_amdgcn_global_load_lds((const unsigned*)((const char*)(gbase) + (voff)[_i]), (PG8_LAS unsigned*)(lds + (bufoff) + ldsw + _i * 8192), 16, 0, 0); } while (0)
; #define PG8_LDA(dst, b, h) do { _Pragma("unroll") for (int m = 0; m < 4; ++m) _Pragma("unroll") for (int k = 0; k < 2; ++k) dst[m][k] = *(const PG8_LAS bf16x8*)(lds + PG8_SA(b, h) + aoff + m * 2048 + k * 1024); } while (0)
; #define PG8_LDB(dst, b, h) do { _Pragma("unroll") for (int n = 0; n < 2; ++n) _Pragma("unroll") for (int k = 0; k < 2; ++k) dst[n][k] = *(const PG8_LAS bf16x8*)(lds + PG8_SB(b, h) + boff + n * 2048 + k * 1024); } while (0)
; #define PG8_MMA(ai, bj, At, Bt) do { __builtin_amdgcn_s_setprio(1); _Pragma("unroll") for (int m = 0; m < 4; ++m) _Pragma("unroll") for (int n = 0; n < 2; ++n) _Pragma("unroll") for (int k = 0; k < 2; ++k) \
;         acc[ai][bj][m][n] = __builtin_amdgcn_mfma_f32_16x16x32_bf16(Bt[n][k], At[m][k], acc[ai][bj][m][n], 0, 0, 0); __builtin_amdgcn_s_setprio(0); } while (0)
; #define PG8_WAIT_V(n) asm volatile("s_waitcnt vmcnt(" #n ")" ::: "memory")
; #define PG8_WAIT_L(n) asm volatile("s_waitcnt lgkmcnt(" #n ")" ::: "memory")
; template <class Epi, class Sched, bool ALIGN_EPI = false, bool SP2 = false>
; __device__ __forceinline__ void gemm_phase(PG8_LAS unsigned char* lds, const Gemm g, const Sched& S, const Epi& E, const int wv  ) {
;     ...
;             const bool last = (t == nt - 2);
;             const char* a1 = cA + (size_t)(t + 1) * kstep;
;             const char* a2 = last ? nA : cA + (size_t)(t + 2) * kstep; const char* b2 = last ? nB : cB + (size_t)(t + 2) * kstep;
;             const char* a3 = a2 + kstep; const char* b3 = b2 + kstep;
;             if (last && has_next) S.a_ready(nxt);
;             if constexpr (SP2) {
;             PG8_LDB(B0, 0, 0); PG8_LDB(B1, 0, 1); PG8_SCHED; PG8_LDA(At, 0, 0); PG8_STAGE(PG8_SA(1, 1), a1 + hstepA, voffA);
;             PG8_WAIT_V(8); PG8_WAIT_L(0); PG8_BAR; PG8_MMA(0, 0, At, B0); PG8_MMA(0, 1, At, B1); PG8_BAR; PG8_SCHED;
;             PG8_LDA(At, 0, 1); PG8_STAGE(PG8_SB(0, 0), b2, voffB); PG8_STAGE(PG8_SB(0, 1), b2 + hstepB, voffB); PG8_STAGE(PG8_SA(0, 0), a2, voffA);
;             PG8_WAIT_V(8); PG8_WAIT_L(0); PG8_BAR; PG8_MMA(1, 0, At, B0); PG8_MMA(1, 1, At, B1); PG8_BAR; PG8_SCHED;
.LBB0_706:
	ds_read_b128 v[146:149], v152
	ds_read_b128 v[156:159], v152 offset:1024
	ds_read_b128 v[160:163], v152 offset:2048
	ds_read_b128 v[164:167], v152 offset:3072
	ds_read_b128 v[168:171], v153
	ds_read_b128 v[172:175], v153 offset:1024
	ds_read_b128 v[176:179], v153 offset:2048
	ds_read_b128 v[180:183], v153 offset:3072
	s_add_u32 s60, s58, 0xfff00080
	s_addc_u32 s61, s59, -1
	s_cmp_eq_u32 s87, 60
	s_cselect_b32 s63, s51, s61
	s_cselect_b32 s62, s83, s60
	s_cselect_b32 s61, s49, s86
	s_cselect_b32 s60, s84, s85
	v_lshl_add_u64 v[216:217], s[58:59], 0, v[138:139]
	s_add_i32 m0, s68, 0xc000
	ds_read_b128 v[184:187], v154
	ds_read_b128 v[188:191], v154 offset:1024
	ds_read_b128 v[192:195], v154 offset:2048
	ds_read_b128 v[196:199], v154 offset:3072
	ds_read_b128 v[200:203], v154 offset:4096
	ds_read_b128 v[204:207], v154 offset:5120
	ds_read_b128 v[208:211], v154 offset:6144
	ds_read_b128 v[212:215], v154 offset:7168
	global_load_lds_dwordx4 v[216:217], off
	v_lshl_add_u64 v[216:217], s[58:59], 0, v[140:141]
	s_add_i32 m0, s68, 0xe000
	s_nop 0
	global_load_lds_dwordx4 v[216:217], off
	s_waitcnt vmcnt(8)
	s_waitcnt lgkmcnt(0)
	s_barrier
	s_setprio 2
	s_waitcnt lgkmcnt(0)
	v_mfma_f32_16x16x32_bf16 v[76:79], v[146:149], v[184:187], v[76:79]
	v_mfma_f32_16x16x32_bf16 v[72:75], v[160:163], v[184:187], v[72:75]
	v_mfma_f32_16x16x32_bf16 v[68:71], v[146:149], v[192:195], v[68:71]
	v_mfma_f32_16x16x32_bf16 v[64:67], v[160:163], v[192:195], v[64:67]
	v_mfma_f32_16x16x32_bf16 v[56:59], v[146:149], v[200:203], v[56:59]
	v_mfma_f32_16x16x32_bf16 v[52:55], v[160:163], v[200:203], v[52:55]
	v_mfma_f32_16x16x32_bf16 v[44:47], v[146:149], v[208:211], v[44:47]
	v_mfma_f32_16x16x32_bf16 v[40:43], v[160:163], v[208:211], v[40:43]
	v_mfma_f32_16x16x32_bf16 v[76:79], v[156:159], v[188:191], v[76:79]
	v_mfma_f32_16x16x32_bf16 v[72:75], v[164:167], v[188:191], v[72:75]
	v_mfma_f32_16x16x32_bf16 v[68:71], v[156:159], v[196:199], v[68:71]
	v_mfma_f32_16x16x32_bf16 v[64:67], v[164:167], v[196:199], v[64:67]
	v_mfma_f32_16x16x32_bf16 v[56:59], v[156:159], v[204:207], v[56:59]
	v_mfma_f32_16x16x32_bf16 v[52:55], v[164:167], v[204:207], v[52:55]
	v_mfma_f32_16x16x32_bf16 v[44:47], v[156:159], v[212:215], v[44:47]
	v_mfma_f32_16x16x32_bf16 v[40:43], v[164:167], v[212:215], v[40:43]
	s_setprio 0
	s_setprio 2
	v_mfma_f32_16x16x32_bf16 v[124:127], v[168:171], v[184:187], v[124:127]
	v_mfma_f32_16x16x32_bf16 v[120:123], v[176:179], v[184:187], v[120:123]
	v_mfma_f32_16x16x32_bf16 v[116:119], v[168:171], v[192:195], v[116:119]
	v_mfma_f32_16x16x32_bf16 v[112:115], v[176:179], v[192:195], v[112:115]
	v_mfma_f32_16x16x32_bf16 v[108:111], v[168:171], v[200:203], v[108:111]
	v_mfma_f32_16x16x32_bf16 v[104:107], v[176:179], v[200:203], v[104:107]
	v_mfma_f32_16x16x32_bf16 v[100:103], v[168:171], v[208:211], v[100:103]
	v_mfma_f32_16x16x32_bf16 v[96:99], v[176:179], v[208:211], v[96:99]
	v_mfma_f32_16x16x32_bf16 v[124:127], v[172:175], v[188:191], v[124:127]
	v_mfma_f32_16x16x32_bf16 v[120:123], v[180:183], v[188:191], v[120:123]
	v_mfma_f32_16x16x32_bf16 v[116:119], v[172:175], v[196:199], v[116:119]
	v_mfma_f32_16x16x32_bf16 v[112:115], v[180:183], v[196:199], v[112:115]
	v_mfma_f32_16x16x32_bf16 v[108:111], v[172:175], v[204:207], v[108:111]
	v_mfma_f32_16x16x32_bf16 v[104:107], v[180:183], v[204:207], v[104:107]
	v_mfma_f32_16x16x32_bf16 v[100:103], v[172:175], v[212:215], v[100:103]
	s_setprio 3
	s_barrier
	v_mfma_f32_16x16x32_bf16 v[96:99], v[180:183], v[212:215], v[96:99]
	s_setprio 0
	s_add_i32 s90, s77, s67
	v_lshl_add_u64 v[216:217], s[60:61], 0, v[130:131]
	s_mov_b32 m0, s90
	ds_read_b128 v[184:187], v154 offset:16384
	ds_read_b128 v[188:191], v154 offset:17408
	ds_read_b128 v[192:195], v154 offset:18432
	ds_read_b128 v[196:199], v154 offset:19456
	ds_read_b128 v[200:203], v154 offset:20480
	ds_read_b128 v[204:207], v154 offset:21504
	ds_read_b128 v[208:211], v154 offset:22528
	ds_read_b128 v[212:215], v154 offset:23552
	global_load_lds_dwordx4 v[216:217], off
	s_add_i32 m0, s90, 0x2000
	s_add_u32 s90, s60, 0x100000
	v_lshl_add_u64 v[218:219], s[60:61], 0, v[134:135]
	s_addc_u32 s91, s61, 0
	s_add_i32 s92, s78, s67
	global_load_lds_dwordx4 v[218:219], off
	v_lshl_add_u64 v[220:221], s[90:91], 0, v[130:131]
	s_mov_b32 m0, s92
	v_lshl_add_u64 v[222:223], s[62:63], 0, v[132:133]
	global_load_lds_dwordx4 v[220:221], off
	v_lshl_add_u64 v[220:221], s[90:91], 0, v[134:135]
	s_add_i32 m0, s92, 0x2000
	s_nop 0
	global_load_lds_dwordx4 v[220:221], off
	v_lshl_add_u64 v[220:221], s[62:63], 0, v[128:129]
	s_mov_b32 m0, s68
	s_nop 0
	global_load_lds_dwordx4 v[220:221], off
	s_mov_b32 m0, s69
	s_nop 0
	global_load_lds_dwordx4 v[222:223], off
	s_waitcnt vmcnt(8)
	s_waitcnt lgkmcnt(0)
	s_barrier
; #define PG8_STAGE(bufoff, gbase, voff) do { _Pragma("unroll") for (int _i = 0; _i < 2; ++_i) \
;         __builtin_amdgcn_global_load_lds((const unsigned*)((const char*)(gbase) + (voff)[_i]), (PG8_LAS unsigned*)(lds + (bufoff) + ldsw + _i * 8192), 16, 0, 0); } while (0)
; #define PG8_LDA(dst, b, h) do { _Pragma("unroll") for (int m = 0; m < 4; ++m) _Pragma("unroll") for (int k = 0; k < 2; ++k) dst[m][k] = *(const PG8_LAS bf16x8*)(lds + PG8_SA(b, h) + aoff + m * 2048 + k * 1024); } while (0)
; #define PG8_LDB(dst, b, h) do { _Pragma("unroll") for (int n = 0; n < 2; ++n) _Pragma("unroll") for (int k = 0; k < 2; ++k) dst[n][k] = *(const PG8_LAS bf16x8*)(lds + PG8_SB(b, h) + boff + n * 2048 + k * 1024); } while (0)
; #define PG8_MMA(ai, bj, At, Bt) do { __builtin_amdgcn_s_setprio(1); _Pragma("unroll") for (int m = 0; m < 4; ++m) _Pragma("unroll") for (int n = 0; n < 2; ++n) _Pragma("unroll") for (int k = 0; k < 2; ++k) \
;         acc[ai][bj][m][n] = __builtin_amdgcn_mfma_f32_16x16x32_bf16(Bt[n][k], At[m][k], acc[ai][bj][m][n], 0, 0, 0); __builtin_amdgcn_s_setprio(0); } while (0)
; #define PG8_WAIT_V(n) asm volatile("s_waitcnt vmcnt(" #n ")" ::: "memory")
; #define PG8_WAIT_L(n) asm volatile("s_waitcnt lgkmcnt(" #n ")" ::: "memory")
; #define PG8_BAR __builtin_amdgcn_s_barrier()
; #define PG8_SCHED __builtin_amdgcn_sched_barrier(0)
; template <class Epi, class Sched, bool ALIGN_EPI = false, bool SP2 = false>
; __device__ __forceinline__ void gemm_phase(PG8_LAS unsigned char* lds, const Gemm g, const Sched& S, const Epi& E, const int wv  ) {
;     ...
;             PG8_WAIT_V(8); PG8_WAIT_L(0); PG8_BAR; PG8_MMA(1, 0, At, B0); PG8_MMA(1, 1, At, B1); PG8_BAR; PG8_SCHED;
;             PG8_LDB(B0, 1, 0); PG8_LDB(B1, 1, 1); PG8_SCHED; PG8_LDA(At, 1, 0); PG8_STAGE(PG8_SA(0, 1), a2 + hstepA, voffA);
;             PG8_WAIT_V(8); PG8_WAIT_L(0); PG8_BAR; PG8_MMA(0, 0, At, B0); PG8_MMA(0, 1, At, B1); PG8_BAR; PG8_SCHED;
	s_setprio 2
	s_waitcnt lgkmcnt(0)
	v_mfma_f32_16x16x32_bf16 v[28:31], v[146:149], v[184:187], v[28:31]
	v_mfma_f32_16x16x32_bf16 v[24:27], v[160:163], v[184:187], v[24:27]
	v_mfma_f32_16x16x32_bf16 v[20:23], v[146:149], v[192:195], v[20:23]
	v_mfma_f32_16x16x32_bf16 v[16:19], v[160:163], v[192:195], v[16:19]
	v_mfma_f32_16x16x32_bf16 v[12:15], v[146:149], v[200:203], v[12:15]
	v_mfma_f32_16x16x32_bf16 v[8:11], v[160:163], v[200:203], v[8:11]
	v_mfma_f32_16x16x32_bf16 v[4:7], v[146:149], v[208:211], v[4:7]
	v_mfma_f32_16x16x32_bf16 v[0:3], v[160:163], v[208:211], v[0:3]
	v_mfma_f32_16x16x32_bf16 v[28:31], v[156:159], v[188:191], v[28:31]
	v_mfma_f32_16x16x32_bf16 v[24:27], v[164:167], v[188:191], v[24:27]
	v_mfma_f32_16x16x32_bf16 v[20:23], v[156:159], v[196:199], v[20:23]
	v_mfma_f32_16x16x32_bf16 v[16:19], v[164:167], v[196:199], v[16:19]
	v_mfma_f32_16x16x32_bf16 v[12:15], v[156:159], v[204:207], v[12:15]
	v_mfma_f32_16x16x32_bf16 v[8:11], v[164:167], v[204:207], v[8:11]
	v_mfma_f32_16x16x32_bf16 v[4:7], v[156:159], v[212:215], v[4:7]
	v_mfma_f32_16x16x32_bf16 v[0:3], v[164:167], v[212:215], v[0:3]
	s_setprio 0
	s_setprio 2
	v_mfma_f32_16x16x32_bf16 v[92:95], v[168:171], v[184:187], v[92:95]
	v_mfma_f32_16x16x32_bf16 v[88:91], v[176:179], v[184:187], v[88:91]
	v_mfma_f32_16x16x32_bf16 v[84:87], v[168:171], v[192:195], v[84:87]
	v_mfma_f32_16x16x32_bf16 v[80:83], v[176:179], v[192:195], v[80:83]
	v_mfma_f32_16x16x32_bf16 v[60:63], v[168:171], v[200:203], v[60:63]
	v_mfma_f32_16x16x32_bf16 v[48:51], v[176:179], v[200:203], v[48:51]
	v_mfma_f32_16x16x32_bf16 v[36:39], v[168:171], v[208:211], v[36:39]
	v_mfma_f32_16x16x32_bf16 v[32:35], v[176:179], v[208:211], v[32:35]
	v_mfma_f32_16x16x32_bf16 v[92:95], v[172:175], v[188:191], v[92:95]
	v_mfma_f32_16x16x32_bf16 v[88:91], v[180:183], v[188:191], v[88:91]
	v_mfma_f32_16x16x32_bf16 v[84:87], v[172:175], v[196:199], v[84:87]
	v_mfma_f32_16x16x32_bf16 v[80:83], v[180:183], v[196:199], v[80:83]
	v_mfma_f32_16x16x32_bf16 v[60:63], v[172:175], v[204:207], v[60:63]
	v_mfma_f32_16x16x32_bf16 v[48:51], v[180:183], v[204:207], v[48:51]
	v_mfma_f32_16x16x32_bf16 v[36:39], v[172:175], v[212:215], v[36:39]
	s_setprio 3
	s_barrier
	v_mfma_f32_16x16x32_bf16 v[32:35], v[180:183], v[212:215], v[32:35]
	s_setprio 0
	s_add_i32 s90, 0, 0x18000
	v_add_u32_e32 v155, s90, v150
	s_add_i32 s91, 0, 0x1c000
	ds_read_b128 v[146:149], v155
	ds_read_b128 v[156:159], v155 offset:1024
	ds_read_b128 v[160:163], v155 offset:2048
	ds_read_b128 v[164:167], v155 offset:3072
	v_add_u32_e32 v155, s91, v150
	ds_read_b128 v[168:171], v155
	ds_read_b128 v[172:175], v155 offset:1024
	ds_read_b128 v[176:179], v155 offset:2048
	ds_read_b128 v[180:183], v155 offset:3072
	s_add_u32 s62, s62, 0x100000
	s_addc_u32 s63, s63, 0
	s_mov_b32 m0, s70
	v_lshl_add_u64 v[224:225], s[62:63], 0, v[128:129]
	ds_read_b128 v[184:187], v154 offset:32768
	ds_read_b128 v[188:191], v154 offset:33792
	ds_read_b128 v[192:195], v154 offset:34816
	ds_read_b128 v[196:199], v154 offset:35840
	ds_read_b128 v[200:203], v154 offset:36864
	ds_read_b128 v[204:207], v154 offset:37888
	ds_read_b128 v[208:211], v154 offset:38912
	ds_read_b128 v[212:215], v154 offset:39936
	global_load_lds_dwordx4 v[224:225], off
	v_lshl_add_u64 v[224:225], s[62:63], 0, v[132:133]
	s_mov_b32 m0, s71
	s_nop 0
	global_load_lds_dwordx4 v[224:225], off
	s_waitcnt vmcnt(8)
	s_waitcnt lgkmcnt(0)
	s_barrier
	s_setprio 2
	s_waitcnt lgkmcnt(0)
	v_mfma_f32_16x16x32_bf16 v[76:79], v[146:149], v[184:187], v[76:79]
	v_mfma_f32_16x16x32_bf16 v[72:75], v[160:163], v[184:187], v[72:75]
	v_mfma_f32_16x16x32_bf16 v[68:71], v[146:149], v[192:195], v[68:71]
	v_mfma_f32_16x16x32_bf16 v[64:67], v[160:163], v[192:195], v[64:67]
	v_mfma_f32_16x16x32_bf16 v[56:59], v[146:149], v[200:203], v[56:59]
	v_mfma_f32_16x16x32_bf16 v[52:55], v[160:163], v[200:203], v[52:55]
	v_mfma_f32_16x16x32_bf16 v[44:47], v[146:149], v[208:211], v[44:47]
	v_mfma_f32_16x16x32_bf16 v[40:43], v[160:163], v[208:211], v[40:43]
	v_mfma_f32_16x16x32_bf16 v[76:79], v[156:159], v[188:191], v[76:79]
	v_mfma_f32_16x16x32_bf16 v[72:75], v[164:167], v[188:191], v[72:75]
	v_mfma_f32_16x16x32_bf16 v[68:71], v[156:159], v[196:199], v[68:71]
	v_mfma_f32_16x16x32_bf16 v[64:67], v[164:167], v[196:199], v[64:67]
	v_mfma_f32_16x16x32_bf16 v[56:59], v[156:159], v[204:207], v[56:59]
	v_mfma_f32_16x16x32_bf16 v[52:55], v[164:167], v[204:207], v[52:55]
	v_mfma_f32_16x16x32_bf16 v[44:47], v[156:159], v[212:215], v[44:47]
	v_mfma_f32_16x16x32_bf16 v[40:43], v[164:167], v[212:215], v[40:43]
	s_setprio 0
	s_setprio 2
	v_mfma_f32_16x16x32_bf16 v[124:127], v[168:171], v[184:187], v[124:127]
	v_mfma_f32_16x16x32_bf16 v[120:123], v[176:179], v[184:187], v[120:123]
	v_mfma_f32_16x16x32_bf16 v[116:119], v[168:171], v[192:195], v[116:119]
	v_mfma_f32_16x16x32_bf16 v[112:115], v[176:179], v[192:195], v[112:115]
	v_mfma_f32_16x16x32_bf16 v[108:111], v[168:171], v[200:203], v[108:111]
	v_mfma_f32_16x16x32_bf16 v[104:107], v[176:179], v[200:203], v[104:107]
	v_mfma_f32_16x16x32_bf16 v[100:103], v[168:171], v[208:211], v[100:103]
	v_mfma_f32_16x16x32_bf16 v[96:99], v[176:179], v[208:211], v[96:99]
	v_mfma_f32_16x16x32_bf16 v[124:127], v[172:175], v[188:191], v[124:127]
	v_mfma_f32_16x16x32_bf16 v[120:123], v[180:183], v[188:191], v[120:123]
	v_mfma_f32_16x16x32_bf16 v[116:119], v[172:175], v[196:199], v[116:119]
	v_mfma_f32_16x16x32_bf16 v[112:115], v[180:183], v[196:199], v[112:115]
	v_mfma_f32_16x16x32_bf16 v[108:111], v[172:175], v[204:207], v[108:111]
	v_mfma_f32_16x16x32_bf16 v[104:107], v[180:183], v[204:207], v[104:107]
	v_mfma_f32_16x16x32_bf16 v[100:103], v[172:175], v[212:215], v[100:103]
	s_setprio 3
	s_barrier
; #define PG8_STAGE(bufoff, gbase, voff) do { _Pragma("unroll") for (int _i = 0; _i < 2; ++_i) \
;         __builtin_amdgcn_global_load_lds((const unsigned*)((const char*)(gbase) + (voff)[_i]), (PG8_LAS unsigned*)(lds + (bufoff) + ldsw + _i * 8192), 16, 0, 0); } while (0)
; #define PG8_LDA(dst, b, h) do { _Pragma("unroll") for (int m = 0; m < 4; ++m) _Pragma("unroll") for (int k = 0; k < 2; ++k) dst[m][k] = *(const PG8_LAS bf16x8*)(lds + PG8_SA(b, h) + aoff + m * 2048 + k * 1024); } while (0)
; #define PG8_MMA(ai, bj, At, Bt) do { __builtin_amdgcn_s_setprio(1); _Pragma("unroll") for (int m = 0; m < 4; ++m) _Pragma("unroll") for (int n = 0; n < 2; ++n) _Pragma("unroll") for (int k = 0; k < 2; ++k) \
;         acc[ai][bj][m][n] = __builtin_amdgcn_mfma_f32_16x16x32_bf16(Bt[n][k], At[m][k], acc[ai][bj][m][n], 0, 0, 0); __builtin_amdgcn_s_setprio(0); } while (0)
; #define PG8_WAIT_V(n) asm volatile("s_waitcnt vmcnt(" #n ")" ::: "memory")
; #define PG8_WAIT_L(n) asm volatile("s_waitcnt lgkmcnt(" #n ")" ::: "memory")
; #define PG8_BAR __builtin_amdgcn_s_barrier()
; #define PG8_SCHED __builtin_amdgcn_sched_barrier(0)
; template <class Epi, class Sched, bool ALIGN_EPI = false, bool SP2 = false>
; __device__ __forceinline__ void gemm_phase(PG8_LAS unsigned char* lds, const Gemm g, const Sched& S, const Epi& E, const int wv  ) {
;     ...
;         for (int t = 0; t < nt; t += 2) {
;             const bool last = (t == nt - 2);
;     ...
;             PG8_WAIT_V(8); PG8_WAIT_L(0); PG8_BAR; PG8_MMA(0, 0, At, B0); PG8_MMA(0, 1, At, B1); PG8_BAR; PG8_SCHED;
;             PG8_LDA(At, 1, 1); PG8_STAGE(PG8_SB(1, 0), b3, voffB); PG8_STAGE(PG8_SB(1, 1), b3 + hstepB, voffB); PG8_STAGE(PG8_SA(1, 0), a3, voffA);
;             PG8_WAIT_V(8); PG8_WAIT_L(0); PG8_BAR; PG8_MMA(1, 0, At, B0); PG8_MMA(1, 1, At, B1); PG8_BAR; PG8_SCHED;
	v_mfma_f32_16x16x32_bf16 v[96:99], v[180:183], v[212:215], v[96:99]
	s_setprio 0
	s_add_i32 s62, s90, s67
	v_lshl_add_u64 v[216:217], v[216:217], 0, s[12:13]
	s_mov_b32 m0, s62
	ds_read_b128 v[184:187], v154 offset:49152
	ds_read_b128 v[188:191], v154 offset:50176
	ds_read_b128 v[192:195], v154 offset:51200
	ds_read_b128 v[196:199], v154 offset:52224
	ds_read_b128 v[200:203], v154 offset:53248
	ds_read_b128 v[204:207], v154 offset:54272
	ds_read_b128 v[208:211], v154 offset:55296
	ds_read_b128 v[212:215], v154 offset:56320
	global_load_lds_dwordx4 v[216:217], off
	s_add_i32 m0, s62, 0x2000
	s_add_u32 s60, s60, 0x100080
	v_lshl_add_u64 v[216:217], v[218:219], 0, s[12:13]
	s_addc_u32 s61, s61, 0
	s_add_i32 s62, s91, s67
	global_load_lds_dwordx4 v[216:217], off
	v_lshl_add_u64 v[216:217], s[60:61], 0, v[130:131]
	s_mov_b32 m0, s62
	s_nop 0
	global_load_lds_dwordx4 v[216:217], off
	v_lshl_add_u64 v[216:217], s[60:61], 0, v[134:135]
	s_add_i32 m0, s62, 0x2000
	s_nop 0
	global_load_lds_dwordx4 v[216:217], off
	v_lshl_add_u64 v[216:217], v[220:221], 0, s[12:13]
	s_mov_b32 m0, s74
	s_nop 0
	global_load_lds_dwordx4 v[216:217], off
	v_lshl_add_u64 v[216:217], v[222:223], 0, s[12:13]
	s_mov_b32 m0, s75
	s_nop 0
	global_load_lds_dwordx4 v[216:217], off
	s_waitcnt vmcnt(8)
	s_waitcnt lgkmcnt(0)
	s_barrier
	s_setprio 2
	s_waitcnt lgkmcnt(0)
	v_mfma_f32_16x16x32_bf16 v[28:31], v[146:149], v[184:187], v[28:31]
	v_mfma_f32_16x16x32_bf16 v[24:27], v[160:163], v[184:187], v[24:27]
	v_mfma_f32_16x16x32_bf16 v[20:23], v[146:149], v[192:195], v[20:23]
	v_mfma_f32_16x16x32_bf16 v[16:19], v[160:163], v[192:195], v[16:19]
	v_mfma_f32_16x16x32_bf16 v[12:15], v[146:149], v[200:203], v[12:15]
	v_mfma_f32_16x16x32_bf16 v[8:11], v[160:163], v[200:203], v[8:11]
	v_mfma_f32_16x16x32_bf16 v[4:7], v[146:149], v[208:211], v[4:7]
	v_mfma_f32_16x16x32_bf16 v[0:3], v[160:163], v[208:211], v[0:3]
	v_mfma_f32_16x16x32_bf16 v[28:31], v[156:159], v[188:191], v[28:31]
	v_mfma_f32_16x16x32_bf16 v[24:27], v[164:167], v[188:191], v[24:27]
	v_mfma_f32_16x16x32_bf16 v[20:23], v[156:159], v[196:199], v[20:23]
	v_mfma_f32_16x16x32_bf16 v[16:19], v[164:167], v[196:199], v[16:19]
	v_mfma_f32_16x16x32_bf16 v[12:15], v[156:159], v[204:207], v[12:15]
	v_mfma_f32_16x16x32_bf16 v[8:11], v[164:167], v[204:207], v[8:11]
	v_mfma_f32_16x16x32_bf16 v[4:7], v[156:159], v[212:215], v[4:7]
	v_mfma_f32_16x16x32_bf16 v[0:3], v[164:167], v[212:215], v[0:3]
	s_setprio 0
	s_setprio 2
	v_mfma_f32_16x16x32_bf16 v[92:95], v[168:171], v[184:187], v[92:95]
	v_mfma_f32_16x16x32_bf16 v[88:91], v[176:179], v[184:187], v[88:91]
	v_mfma_f32_16x16x32_bf16 v[84:87], v[168:171], v[192:195], v[84:87]
	v_mfma_f32_16x16x32_bf16 v[80:83], v[176:179], v[192:195], v[80:83]
	v_mfma_f32_16x16x32_bf16 v[60:63], v[168:171], v[200:203], v[60:63]
	v_mfma_f32_16x16x32_bf16 v[48:51], v[176:179], v[200:203], v[48:51]
	v_mfma_f32_16x16x32_bf16 v[36:39], v[168:171], v[208:211], v[36:39]
	v_mfma_f32_16x16x32_bf16 v[32:35], v[176:179], v[208:211], v[32:35]
	v_mfma_f32_16x16x32_bf16 v[92:95], v[172:175], v[188:191], v[92:95]
	v_mfma_f32_16x16x32_bf16 v[88:91], v[180:183], v[188:191], v[88:91]
	v_mfma_f32_16x16x32_bf16 v[84:87], v[172:175], v[196:199], v[84:87]
	v_mfma_f32_16x16x32_bf16 v[80:83], v[180:183], v[196:199], v[80:83]
	v_mfma_f32_16x16x32_bf16 v[60:63], v[172:175], v[204:207], v[60:63]
	v_mfma_f32_16x16x32_bf16 v[48:51], v[180:183], v[204:207], v[48:51]
	v_mfma_f32_16x16x32_bf16 v[36:39], v[172:175], v[212:215], v[36:39]
	s_setprio 3
	s_barrier
	v_mfma_f32_16x16x32_bf16 v[32:35], v[180:183], v[212:215], v[32:35]
	s_setprio 0
	s_add_i32 s87, s87, 2
	s_add_u32 s58, s58, 0x100
	s_addc_u32 s59, s59, 0
	s_add_u32 s85, s85, 0x100
	s_addc_u32 s86, s86, 0
	s_cmp_gt_u32 s87, 61
	s_cbranch_scc0 .LBB0_706
	s_and_b64 vcc, exec, s[14:15]
	s_cbranch_vccz .LBB0_709
	s_barrier

; #define PG8_STAGE(bufoff, gbase, voff) do { _Pragma("unroll") for (int _i = 0; _i < 2; ++_i) \
;         __builtin_amdgcn_global_load_lds((const unsigned*)((const char*)(gbase) + (voff)[_i]), (PG8_LAS unsigned*)(lds + (bufoff) + ldsw + _i * 8192), 16, 0, 0); } while (0)
; #define PG8_LDA(dst, b, h) do { _Pragma("unroll") for (int m = 0; m < 4; ++m) _Pragma("unroll") for (int k = 0; k < 2; ++k) dst[m][k] = *(const PG8_LAS bf16x8*)(lds + PG8_SA(b, h) + aoff + m * 2048 + k * 1024); } while (0)
; #define PG8_LDB(dst, b, h) do { _Pragma("unroll") for (int n = 0; n < 2; ++n) _Pragma("unroll") for (int k = 0; k < 2; ++k) dst[n][k] = *(const PG8_LAS bf16x8*)(lds + PG8_SB(b, h) + boff + n * 2048 + k * 1024); } while (0)
; #define PG8_MMA(ai, bj, At, Bt) do { __builtin_amdgcn_s_setprio(1); _Pragma("unroll") for (int m = 0; m < 4; ++m) _Pragma("unroll") for (int n = 0; n < 2; ++n) _Pragma("unroll") for (int k = 0; k < 2; ++k) \
;         acc[ai][bj][m][n] = __builtin_amdgcn_mfma_f32_16x16x32_bf16(Bt[n][k], At[m][k], acc[ai][bj][m][n], 0, 0, 0); __builtin_amdgcn_s_setprio(0); } while (0)
; #define PG8_WAIT_V(n) asm volatile("s_waitcnt vmcnt(" #n ")" ::: "memory")
; #define PG8_WAIT_L(n) asm volatile("s_waitcnt lgkmcnt(" #n ")" ::: "memory")
; template <class Epi, class Sched, bool ALIGN_EPI = false, bool SP2 = false>
; __device__ __forceinline__ void gemm_phase(PG8_LAS unsigned char* lds, const Gemm g, const Sched& S, const Epi& E, const int wv  ) {
;     ...
;             const bool last = (t == nt - 2);
;             const char* a1 = cA + (size_t)(t + 1) * kstep;
;             const char* a2 = last ? nA : cA + (size_t)(t + 2) * kstep; const char* b2 = last ? nB : cB + (size_t)(t + 2) * kstep;
;             const char* a3 = a2 + kstep; const char* b3 = b2 + kstep;
;             if (last && has_next) S.a_ready(nxt);
;             if constexpr (SP2) {
;             PG8_LDB(B0, 0, 0); PG8_LDB(B1, 0, 1); PG8_SCHED; PG8_LDA(At, 0, 0); PG8_STAGE(PG8_SA(1, 1), a1 + hstepA, voffA);
;             PG8_WAIT_V(8); PG8_WAIT_L(0); PG8_BAR; PG8_MMA(0, 0, At, B0); PG8_MMA(0, 1, At, B1); PG8_BAR; PG8_SCHED;
;             PG8_LDA(At, 0, 1); PG8_STAGE(PG8_SB(0, 0), b2, voffB); PG8_STAGE(PG8_SB(0, 1), b2 + hstepB, voffB); PG8_STAGE(PG8_SA(0, 0), a2, voffA);
;             PG8_WAIT_V(8); PG8_WAIT_L(0); PG8_BAR; PG8_MMA(1, 0, At, B0); PG8_MMA(1, 1, At, B1); PG8_BAR; PG8_SCHED;
.LBB0_850:
	ds_read_b128 v[146:149], v152
	ds_read_b128 v[156:159], v152 offset:1024
	ds_read_b128 v[160:163], v152 offset:2048
	ds_read_b128 v[164:167], v152 offset:3072
	ds_read_b128 v[168:171], v153
	ds_read_b128 v[172:175], v153 offset:1024
	ds_read_b128 v[176:179], v153 offset:2048
	ds_read_b128 v[180:183], v153 offset:3072
	s_add_u32 s60, s58, 0xfff00080
	s_addc_u32 s61, s59, -1
	s_cmp_eq_u32 s92, 60
	s_cselect_b32 s63, s51, s61
	s_cselect_b32 s62, s86, s60
	s_cselect_b32 s61, s49, s91
	s_cselect_b32 s60, s87, s90
	v_lshl_add_u64 v[216:217], s[58:59], 0, v[138:139]
	s_add_i32 m0, s71, 0xc000
	ds_read_b128 v[184:187], v154
	ds_read_b128 v[188:191], v154 offset:1024
	ds_read_b128 v[192:195], v154 offset:2048
	ds_read_b128 v[196:199], v154 offset:3072
	ds_read_b128 v[200:203], v154 offset:4096
	ds_read_b128 v[204:207], v154 offset:5120
	ds_read_b128 v[208:211], v154 offset:6144
	ds_read_b128 v[212:215], v154 offset:7168
	global_load_lds_dwordx4 v[216:217], off
	v_lshl_add_u64 v[216:217], s[58:59], 0, v[140:141]
	s_add_i32 m0, s71, 0xe000
	s_nop 0
	global_load_lds_dwordx4 v[216:217], off
	s_waitcnt vmcnt(8)
	s_waitcnt lgkmcnt(0)
	s_barrier
	s_setprio 2
	s_waitcnt lgkmcnt(0)
	v_mfma_f32_16x16x32_bf16 v[76:79], v[146:149], v[184:187], v[76:79]
	v_mfma_f32_16x16x32_bf16 v[72:75], v[160:163], v[184:187], v[72:75]
	v_mfma_f32_16x16x32_bf16 v[68:71], v[146:149], v[192:195], v[68:71]
	v_mfma_f32_16x16x32_bf16 v[64:67], v[160:163], v[192:195], v[64:67]
	v_mfma_f32_16x16x32_bf16 v[56:59], v[146:149], v[200:203], v[56:59]
	v_mfma_f32_16x16x32_bf16 v[52:55], v[160:163], v[200:203], v[52:55]
	v_mfma_f32_16x16x32_bf16 v[44:47], v[146:149], v[208:211], v[44:47]
	v_mfma_f32_16x16x32_bf16 v[40:43], v[160:163], v[208:211], v[40:43]
	v_mfma_f32_16x16x32_bf16 v[76:79], v[156:159], v[188:191], v[76:79]
	v_mfma_f32_16x16x32_bf16 v[72:75], v[164:167], v[188:191], v[72:75]
	v_mfma_f32_16x16x32_bf16 v[68:71], v[156:159], v[196:199], v[68:71]
	v_mfma_f32_16x16x32_bf16 v[64:67], v[164:167], v[196:199], v[64:67]
	v_mfma_f32_16x16x32_bf16 v[56:59], v[156:159], v[204:207], v[56:59]
	v_mfma_f32_16x16x32_bf16 v[52:55], v[164:167], v[204:207], v[52:55]
	v_mfma_f32_16x16x32_bf16 v[44:47], v[156:159], v[212:215], v[44:47]
	v_mfma_f32_16x16x32_bf16 v[40:43], v[164:167], v[212:215], v[40:43]
	s_setprio 0
	s_setprio 2
	v_mfma_f32_16x16x32_bf16 v[124:127], v[168:171], v[184:187], v[124:127]
	v_mfma_f32_16x16x32_bf16 v[120:123], v[176:179], v[184:187], v[120:123]
	v_mfma_f32_16x16x32_bf16 v[116:119], v[168:171], v[192:195], v[116:119]
	v_mfma_f32_16x16x32_bf16 v[112:115], v[176:179], v[192:195], v[112:115]
	v_mfma_f32_16x16x32_bf16 v[108:111], v[168:171], v[200:203], v[108:111]
	v_mfma_f32_16x16x32_bf16 v[104:107], v[176:179], v[200:203], v[104:107]
	v_mfma_f32_16x16x32_bf16 v[100:103], v[168:171], v[208:211], v[100:103]
	v_mfma_f32_16x16x32_bf16 v[96:99], v[176:179], v[208:211], v[96:99]
	v_mfma_f32_16x16x32_bf16 v[124:127], v[172:175], v[188:191], v[124:127]
	v_mfma_f32_16x16x32_bf16 v[120:123], v[180:183], v[188:191], v[120:123]
	v_mfma_f32_16x16x32_bf16 v[116:119], v[172:175], v[196:199], v[116:119]
	v_mfma_f32_16x16x32_bf16 v[112:115], v[180:183], v[196:199], v[112:115]
	v_mfma_f32_16x16x32_bf16 v[108:111], v[172:175], v[204:207], v[108:111]
	v_mfma_f32_16x16x32_bf16 v[104:107], v[180:183], v[204:207], v[104:107]
	v_mfma_f32_16x16x32_bf16 v[100:103], v[172:175], v[212:215], v[100:103]
	s_setprio 3
	s_barrier
	v_mfma_f32_16x16x32_bf16 v[96:99], v[180:183], v[212:215], v[96:99]
	s_setprio 0
	s_add_i32 s93, s80, s70
	v_lshl_add_u64 v[216:217], s[60:61], 0, v[130:131]
	s_mov_b32 m0, s93
	ds_read_b128 v[184:187], v154 offset:16384
	ds_read_b128 v[188:191], v154 offset:17408
	ds_read_b128 v[192:195], v154 offset:18432
	ds_read_b128 v[196:199], v154 offset:19456
	ds_read_b128 v[200:203], v154 offset:20480
	ds_read_b128 v[204:207], v154 offset:21504
	ds_read_b128 v[208:211], v154 offset:22528
	ds_read_b128 v[212:215], v154 offset:23552
	global_load_lds_dwordx4 v[216:217], off
	s_add_i32 m0, s93, 0x2000
	s_add_u32 s94, s60, 0x100000
	v_lshl_add_u64 v[218:219], s[60:61], 0, v[134:135]
	s_addc_u32 s95, s61, 0
	s_add_i32 s93, s81, s70
	global_load_lds_dwordx4 v[218:219], off
	v_lshl_add_u64 v[220:221], s[94:95], 0, v[130:131]
	s_mov_b32 m0, s93
	v_lshl_add_u64 v[222:223], s[62:63], 0, v[132:133]
	global_load_lds_dwordx4 v[220:221], off
	v_lshl_add_u64 v[220:221], s[94:95], 0, v[134:135]
	s_add_i32 m0, s93, 0x2000
	s_nop 0
	global_load_lds_dwordx4 v[220:221], off
	v_lshl_add_u64 v[220:221], s[62:63], 0, v[128:129]
	s_mov_b32 m0, s71
	s_nop 0
	global_load_lds_dwordx4 v[220:221], off
	s_mov_b32 m0, s72
	s_nop 0
	global_load_lds_dwordx4 v[222:223], off
	s_waitcnt vmcnt(8)
	s_waitcnt lgkmcnt(0)
	s_barrier
; #define PG8_STAGE(bufoff, gbase, voff) do { _Pragma("unroll") for (int _i = 0; _i < 2; ++_i) \
;         __builtin_amdgcn_global_load_lds((const unsigned*)((const char*)(gbase) + (voff)[_i]), (PG8_LAS unsigned*)(lds + (bufoff) + ldsw + _i * 8192), 16, 0, 0); } while (0)
; #define PG8_LDA(dst, b, h) do { _Pragma("unroll") for (int m = 0; m < 4; ++m) _Pragma("unroll") for (int k = 0; k < 2; ++k) dst[m][k] = *(const PG8_LAS bf16x8*)(lds + PG8_SA(b, h) + aoff + m * 2048 + k * 1024); } while (0)
; #define PG8_LDB(dst, b, h) do { _Pragma("unroll") for (int n = 0; n < 2; ++n) _Pragma("unroll") for (int k = 0; k < 2; ++k) dst[n][k] = *(const PG8_LAS bf16x8*)(lds + PG8_SB(b, h) + boff + n * 2048 + k * 1024); } while (0)
; #define PG8_MMA(ai, bj, At, Bt) do { __builtin_amdgcn_s_setprio(1); _Pragma("unroll") for (int m = 0; m < 4; ++m) _Pragma("unroll") for (int n = 0; n < 2; ++n) _Pragma("unroll") for (int k = 0; k < 2; ++k) \
;         acc[ai][bj][m][n] = __builtin_amdgcn_mfma_f32_16x16x32_bf16(Bt[n][k], At[m][k], acc[ai][bj][m][n], 0, 0, 0); __builtin_amdgcn_s_setprio(0); } while (0)
; #define PG8_WAIT_V(n) asm volatile("s_waitcnt vmcnt(" #n ")" ::: "memory")
; #define PG8_WAIT_L(n) asm volatile("s_waitcnt lgkmcnt(" #n ")" ::: "memory")
; #define PG8_BAR __builtin_amdgcn_s_barrier()
; #define PG8_SCHED __builtin_amdgcn_sched_barrier(0)
; template <class Epi, class Sched, bool ALIGN_EPI = false, bool SP2 = false>
; __device__ __forceinline__ void gemm_phase(PG8_LAS unsigned char* lds, const Gemm g, const Sched& S, const Epi& E, const int wv  ) {
;     ...
;             PG8_WAIT_V(8); PG8_WAIT_L(0); PG8_BAR; PG8_MMA(1, 0, At, B0); PG8_MMA(1, 1, At, B1); PG8_BAR; PG8_SCHED;
;             PG8_LDB(B0, 1, 0); PG8_LDB(B1, 1, 1); PG8_SCHED; PG8_LDA(At, 1, 0); PG8_STAGE(PG8_SA(0, 1), a2 + hstepA, voffA);
;             PG8_WAIT_V(8); PG8_WAIT_L(0); PG8_BAR; PG8_MMA(0, 0, At, B0); PG8_MMA(0, 1, At, B1); PG8_BAR; PG8_SCHED;
	s_setprio 2
	s_waitcnt lgkmcnt(0)
	v_mfma_f32_16x16x32_bf16 v[28:31], v[146:149], v[184:187], v[28:31]
	v_mfma_f32_16x16x32_bf16 v[24:27], v[160:163], v[184:187], v[24:27]
	v_mfma_f32_16x16x32_bf16 v[20:23], v[146:149], v[192:195], v[20:23]
	v_mfma_f32_16x16x32_bf16 v[16:19], v[160:163], v[192:195], v[16:19]
	v_mfma_f32_16x16x32_bf16 v[12:15], v[146:149], v[200:203], v[12:15]
	v_mfma_f32_16x16x32_bf16 v[8:11], v[160:163], v[200:203], v[8:11]
	v_mfma_f32_16x16x32_bf16 v[4:7], v[146:149], v[208:211], v[4:7]
	v_mfma_f32_16x16x32_bf16 v[0:3], v[160:163], v[208:211], v[0:3]
	v_mfma_f32_16x16x32_bf16 v[28:31], v[156:159], v[188:191], v[28:31]
	v_mfma_f32_16x16x32_bf16 v[24:27], v[164:167], v[188:191], v[24:27]
	v_mfma_f32_16x16x32_bf16 v[20:23], v[156:159], v[196:199], v[20:23]
	v_mfma_f32_16x16x32_bf16 v[16:19], v[164:167], v[196:199], v[16:19]
	v_mfma_f32_16x16x32_bf16 v[12:15], v[156:159], v[204:207], v[12:15]
	v_mfma_f32_16x16x32_bf16 v[8:11], v[164:167], v[204:207], v[8:11]
	v_mfma_f32_16x16x32_bf16 v[4:7], v[156:159], v[212:215], v[4:7]
	v_mfma_f32_16x16x32_bf16 v[0:3], v[164:167], v[212:215], v[0:3]
	s_setprio 0
	s_setprio 2
	v_mfma_f32_16x16x32_bf16 v[92:95], v[168:171], v[184:187], v[92:95]
	v_mfma_f32_16x16x32_bf16 v[88:91], v[176:179], v[184:187], v[88:91]
	v_mfma_f32_16x16x32_bf16 v[84:87], v[168:171], v[192:195], v[84:87]
	v_mfma_f32_16x16x32_bf16 v[80:83], v[176:179], v[192:195], v[80:83]
	v_mfma_f32_16x16x32_bf16 v[60:63], v[168:171], v[200:203], v[60:63]
	v_mfma_f32_16x16x32_bf16 v[48:51], v[176:179], v[200:203], v[48:51]
	v_mfma_f32_16x16x32_bf16 v[36:39], v[168:171], v[208:211], v[36:39]
	v_mfma_f32_16x16x32_bf16 v[32:35], v[176:179], v[208:211], v[32:35]
	v_mfma_f32_16x16x32_bf16 v[92:95], v[172:175], v[188:191], v[92:95]
	v_mfma_f32_16x16x32_bf16 v[88:91], v[180:183], v[188:191], v[88:91]
	v_mfma_f32_16x16x32_bf16 v[84:87], v[172:175], v[196:199], v[84:87]
	v_mfma_f32_16x16x32_bf16 v[80:83], v[180:183], v[196:199], v[80:83]
	v_mfma_f32_16x16x32_bf16 v[60:63], v[172:175], v[204:207], v[60:63]
	v_mfma_f32_16x16x32_bf16 v[48:51], v[180:183], v[204:207], v[48:51]
	v_mfma_f32_16x16x32_bf16 v[36:39], v[172:175], v[212:215], v[36:39]
	s_setprio 3
	s_barrier
	v_mfma_f32_16x16x32_bf16 v[32:35], v[180:183], v[212:215], v[32:35]
	s_setprio 0
	s_add_i32 s93, 0, 0x18000
	v_add_u32_e32 v155, s93, v150
	s_add_i32 s94, 0, 0x1c000
	ds_read_b128 v[146:149], v155
	ds_read_b128 v[156:159], v155 offset:1024
	ds_read_b128 v[160:163], v155 offset:2048
	ds_read_b128 v[164:167], v155 offset:3072
	v_add_u32_e32 v155, s94, v150
	ds_read_b128 v[168:171], v155
	ds_read_b128 v[172:175], v155 offset:1024
	ds_read_b128 v[176:179], v155 offset:2048
	ds_read_b128 v[180:183], v155 offset:3072
	s_add_u32 s62, s62, 0x100000
	s_addc_u32 s63, s63, 0
	s_mov_b32 m0, s73
	v_lshl_add_u64 v[224:225], s[62:63], 0, v[128:129]
	ds_read_b128 v[184:187], v154 offset:32768
	ds_read_b128 v[188:191], v154 offset:33792
	ds_read_b128 v[192:195], v154 offset:34816
	ds_read_b128 v[196:199], v154 offset:35840
	ds_read_b128 v[200:203], v154 offset:36864
	ds_read_b128 v[204:207], v154 offset:37888
	ds_read_b128 v[208:211], v154 offset:38912
	ds_read_b128 v[212:215], v154 offset:39936
	global_load_lds_dwordx4 v[224:225], off
	v_lshl_add_u64 v[224:225], s[62:63], 0, v[132:133]
	s_mov_b32 m0, s74
	s_nop 0
	global_load_lds_dwordx4 v[224:225], off
	s_waitcnt vmcnt(8)
	s_waitcnt lgkmcnt(0)
	s_barrier
	s_setprio 2
	s_waitcnt lgkmcnt(0)
	v_mfma_f32_16x16x32_bf16 v[76:79], v[146:149], v[184:187], v[76:79]
	v_mfma_f32_16x16x32_bf16 v[72:75], v[160:163], v[184:187], v[72:75]
	v_mfma_f32_16x16x32_bf16 v[68:71], v[146:149], v[192:195], v[68:71]
	v_mfma_f32_16x16x32_bf16 v[64:67], v[160:163], v[192:195], v[64:67]
	v_mfma_f32_16x16x32_bf16 v[56:59], v[146:149], v[200:203], v[56:59]
	v_mfma_f32_16x16x32_bf16 v[52:55], v[160:163], v[200:203], v[52:55]
	v_mfma_f32_16x16x32_bf16 v[44:47], v[146:149], v[208:211], v[44:47]
	v_mfma_f32_16x16x32_bf16 v[40:43], v[160:163], v[208:211], v[40:43]
	v_mfma_f32_16x16x32_bf16 v[76:79], v[156:159], v[188:191], v[76:79]
	v_mfma_f32_16x16x32_bf16 v[72:75], v[164:167], v[188:191], v[72:75]
	v_mfma_f32_16x16x32_bf16 v[68:71], v[156:159], v[196:199], v[68:71]
	v_mfma_f32_16x16x32_bf16 v[64:67], v[164:167], v[196:199], v[64:67]
	v_mfma_f32_16x16x32_bf16 v[56:59], v[156:159], v[204:207], v[56:59]
	v_mfma_f32_16x16x32_bf16 v[52:55], v[164:167], v[204:207], v[52:55]
	v_mfma_f32_16x16x32_bf16 v[44:47], v[156:159], v[212:215], v[44:47]
	v_mfma_f32_16x16x32_bf16 v[40:43], v[164:167], v[212:215], v[40:43]
	s_setprio 0
	s_setprio 2
	v_mfma_f32_16x16x32_bf16 v[124:127], v[168:171], v[184:187], v[124:127]
	v_mfma_f32_16x16x32_bf16 v[120:123], v[176:179], v[184:187], v[120:123]
	v_mfma_f32_16x16x32_bf16 v[116:119], v[168:171], v[192:195], v[116:119]
	v_mfma_f32_16x16x32_bf16 v[112:115], v[176:179], v[192:195], v[112:115]
	v_mfma_f32_16x16x32_bf16 v[108:111], v[168:171], v[200:203], v[108:111]
	v_mfma_f32_16x16x32_bf16 v[104:107], v[176:179], v[200:203], v[104:107]
	v_mfma_f32_16x16x32_bf16 v[100:103], v[168:171], v[208:211], v[100:103]
	v_mfma_f32_16x16x32_bf16 v[96:99], v[176:179], v[208:211], v[96:99]
	v_mfma_f32_16x16x32_bf16 v[124:127], v[172:175], v[188:191], v[124:127]
	v_mfma_f32_16x16x32_bf16 v[120:123], v[180:183], v[188:191], v[120:123]
	v_mfma_f32_16x16x32_bf16 v[116:119], v[172:175], v[196:199], v[116:119]
	v_mfma_f32_16x16x32_bf16 v[112:115], v[180:183], v[196:199], v[112:115]
	v_mfma_f32_16x16x32_bf16 v[108:111], v[172:175], v[204:207], v[108:111]
	v_mfma_f32_16x16x32_bf16 v[104:107], v[180:183], v[204:207], v[104:107]
	v_mfma_f32_16x16x32_bf16 v[100:103], v[172:175], v[212:215], v[100:103]
	s_setprio 3
	s_barrier
; #define PG8_STAGE(bufoff, gbase, voff) do { _Pragma("unroll") for (int _i = 0; _i < 2; ++_i) \
;         __builtin_amdgcn_global_load_lds((const unsigned*)((const char*)(gbase) + (voff)[_i]), (PG8_LAS unsigned*)(lds + (bufoff) + ldsw + _i * 8192), 16, 0, 0); } while (0)
; #define PG8_LDA(dst, b, h) do { _Pragma("unroll") for (int m = 0; m < 4; ++m) _Pragma("unroll") for (int k = 0; k < 2; ++k) dst[m][k] = *(const PG8_LAS bf16x8*)(lds + PG8_SA(b, h) + aoff + m * 2048 + k * 1024); } while (0)
; #define PG8_MMA(ai, bj, At, Bt) do { __builtin_amdgcn_s_setprio(1); _Pragma("unroll") for (int m = 0; m < 4; ++m) _Pragma("unroll") for (int n = 0; n < 2; ++n) _Pragma("unroll") for (int k = 0; k < 2; ++k) \
;         acc[ai][bj][m][n] = __builtin_amdgcn_mfma_f32_16x16x32_bf16(Bt[n][k], At[m][k], acc[ai][bj][m][n], 0, 0, 0); __builtin_amdgcn_s_setprio(0); } while (0)
; #define PG8_WAIT_V(n) asm volatile("s_waitcnt vmcnt(" #n ")" ::: "memory")
; #define PG8_WAIT_L(n) asm volatile("s_waitcnt lgkmcnt(" #n ")" ::: "memory")
; #define PG8_BAR __builtin_amdgcn_s_barrier()
; #define PG8_SCHED __builtin_amdgcn_sched_barrier(0)
; template <class Epi, class Sched, bool ALIGN_EPI = false, bool SP2 = false>
; __device__ __forceinline__ void gemm_phase(PG8_LAS unsigned char* lds, const Gemm g, const Sched& S, const Epi& E, const int wv  ) {
;     ...
;         for (int t = 0; t < nt; t += 2) {
;             const bool last = (t == nt - 2);
;     ...
;             PG8_WAIT_V(8); PG8_WAIT_L(0); PG8_BAR; PG8_MMA(0, 0, At, B0); PG8_MMA(0, 1, At, B1); PG8_BAR; PG8_SCHED;
;             PG8_LDA(At, 1, 1); PG8_STAGE(PG8_SB(1, 0), b3, voffB); PG8_STAGE(PG8_SB(1, 1), b3 + hstepB, voffB); PG8_STAGE(PG8_SA(1, 0), a3, voffA);
;             PG8_WAIT_V(8); PG8_WAIT_L(0); PG8_BAR; PG8_MMA(1, 0, At, B0); PG8_MMA(1, 1, At, B1); PG8_BAR; PG8_SCHED;
	v_mfma_f32_16x16x32_bf16 v[96:99], v[180:183], v[212:215], v[96:99]
	s_setprio 0
	s_add_i32 s62, s93, s70
	v_lshl_add_u64 v[216:217], v[216:217], 0, s[10:11]
	s_mov_b32 m0, s62
	ds_read_b128 v[184:187], v154 offset:49152
	ds_read_b128 v[188:191], v154 offset:50176
	ds_read_b128 v[192:195], v154 offset:51200
	ds_read_b128 v[196:199], v154 offset:52224
	ds_read_b128 v[200:203], v154 offset:53248
	ds_read_b128 v[204:207], v154 offset:54272
	ds_read_b128 v[208:211], v154 offset:55296
	ds_read_b128 v[212:215], v154 offset:56320
	global_load_lds_dwordx4 v[216:217], off
	s_add_i32 m0, s62, 0x2000
	s_add_u32 s60, s60, 0x100080
	v_lshl_add_u64 v[216:217], v[218:219], 0, s[10:11]
	s_addc_u32 s61, s61, 0
	s_add_i32 s62, s94, s70
	global_load_lds_dwordx4 v[216:217], off
	v_lshl_add_u64 v[216:217], s[60:61], 0, v[130:131]
	s_mov_b32 m0, s62
	s_nop 0
	global_load_lds_dwordx4 v[216:217], off
	v_lshl_add_u64 v[216:217], s[60:61], 0, v[134:135]
	s_add_i32 m0, s62, 0x2000
	s_nop 0
	global_load_lds_dwordx4 v[216:217], off
	v_lshl_add_u64 v[216:217], v[220:221], 0, s[10:11]
	s_mov_b32 m0, s77
	s_nop 0
	global_load_lds_dwordx4 v[216:217], off
	v_lshl_add_u64 v[216:217], v[222:223], 0, s[10:11]
	s_mov_b32 m0, s78
	s_nop 0
	global_load_lds_dwordx4 v[216:217], off
	s_waitcnt vmcnt(8)
	s_waitcnt lgkmcnt(0)
	s_barrier
	s_setprio 2
	s_waitcnt lgkmcnt(0)
	v_mfma_f32_16x16x32_bf16 v[28:31], v[146:149], v[184:187], v[28:31]
	v_mfma_f32_16x16x32_bf16 v[24:27], v[160:163], v[184:187], v[24:27]
	v_mfma_f32_16x16x32_bf16 v[20:23], v[146:149], v[192:195], v[20:23]
	v_mfma_f32_16x16x32_bf16 v[16:19], v[160:163], v[192:195], v[16:19]
	v_mfma_f32_16x16x32_bf16 v[12:15], v[146:149], v[200:203], v[12:15]
	v_mfma_f32_16x16x32_bf16 v[8:11], v[160:163], v[200:203], v[8:11]
	v_mfma_f32_16x16x32_bf16 v[4:7], v[146:149], v[208:211], v[4:7]
	v_mfma_f32_16x16x32_bf16 v[0:3], v[160:163], v[208:211], v[0:3]
	v_mfma_f32_16x16x32_bf16 v[28:31], v[156:159], v[188:191], v[28:31]
	v_mfma_f32_16x16x32_bf16 v[24:27], v[164:167], v[188:191], v[24:27]
	v_mfma_f32_16x16x32_bf16 v[20:23], v[156:159], v[196:199], v[20:23]
	v_mfma_f32_16x16x32_bf16 v[16:19], v[164:167], v[196:199], v[16:19]
	v_mfma_f32_16x16x32_bf16 v[12:15], v[156:159], v[204:207], v[12:15]
	v_mfma_f32_16x16x32_bf16 v[8:11], v[164:167], v[204:207], v[8:11]
	v_mfma_f32_16x16x32_bf16 v[4:7], v[156:159], v[212:215], v[4:7]
	v_mfma_f32_16x16x32_bf16 v[0:3], v[164:167], v[212:215], v[0:3]
	s_setprio 0
	s_setprio 2
	v_mfma_f32_16x16x32_bf16 v[92:95], v[168:171], v[184:187], v[92:95]
	v_mfma_f32_16x16x32_bf16 v[88:91], v[176:179], v[184:187], v[88:91]
	v_mfma_f32_16x16x32_bf16 v[84:87], v[168:171], v[192:195], v[84:87]
	v_mfma_f32_16x16x32_bf16 v[80:83], v[176:179], v[192:195], v[80:83]
	v_mfma_f32_16x16x32_bf16 v[60:63], v[168:171], v[200:203], v[60:63]
	v_mfma_f32_16x16x32_bf16 v[48:51], v[176:179], v[200:203], v[48:51]
	v_mfma_f32_16x16x32_bf16 v[36:39], v[168:171], v[208:211], v[36:39]
	v_mfma_f32_16x16x32_bf16 v[32:35], v[176:179], v[208:211], v[32:35]
	v_mfma_f32_16x16x32_bf16 v[92:95], v[172:175], v[188:191], v[92:95]
	v_mfma_f32_16x16x32_bf16 v[88:91], v[180:183], v[188:191], v[88:91]
	v_mfma_f32_16x16x32_bf16 v[84:87], v[172:175], v[196:199], v[84:87]
	v_mfma_f32_16x16x32_bf16 v[80:83], v[180:183], v[196:199], v[80:83]
	v_mfma_f32_16x16x32_bf16 v[60:63], v[172:175], v[204:207], v[60:63]
	v_mfma_f32_16x16x32_bf16 v[48:51], v[180:183], v[204:207], v[48:51]
	v_mfma_f32_16x16x32_bf16 v[36:39], v[172:175], v[212:215], v[36:39]
	s_setprio 3
	s_barrier
	v_mfma_f32_16x16x32_bf16 v[32:35], v[180:183], v[212:215], v[32:35]
	s_setprio 0
	s_add_i32 s92, s92, 2
	s_add_u32 s58, s58, 0x100
	s_addc_u32 s59, s59, 0
	s_add_u32 s90, s90, 0x100
	s_addc_u32 s91, s91, 0
	s_cmp_gt_u32 s92, 61
	s_cbranch_scc0 .LBB0_850
	s_and_b64 vcc, exec, s[12:13]
	s_cbranch_vccz .LBB0_853
	s_barrier

; #define PG8_STAGE(bufoff, gbase, voff) do { _Pragma("unroll") for (int _i = 0; _i < 2; ++_i) \
;         __builtin_amdgcn_global_load_lds((const unsigned*)((const char*)(gbase) + (voff)[_i]), (PG8_LAS unsigned*)(lds + (bufoff) + ldsw + _i * 8192), 16, 0, 0); } while (0)
; #define PG8_LDA(dst, b, h) do { _Pragma("unroll") for (int m = 0; m < 4; ++m) _Pragma("unroll") for (int k = 0; k < 2; ++k) dst[m][k] = *(const PG8_LAS bf16x8*)(lds + PG8_SA(b, h) + aoff + m * 2048 + k * 1024); } while (0)
; #define PG8_LDB(dst, b, h) do { _Pragma("unroll") for (int n = 0; n < 2; ++n) _Pragma("unroll") for (int k = 0; k < 2; ++k) dst[n][k] = *(const PG8_LAS bf16x8*)(lds + PG8_SB(b, h) + boff + n * 2048 + k * 1024); } while (0)
; #define PG8_MMA(ai, bj, At, Bt) do { __builtin_amdgcn_s_setprio(1); _Pragma("unroll") for (int m = 0; m < 4; ++m) _Pragma("unroll") for (int n = 0; n < 2; ++n) _Pragma("unroll") for (int k = 0; k < 2; ++k) \
;         acc[ai][bj][m][n] = __builtin_amdgcn_mfma_f32_16x16x32_bf16(Bt[n][k], At[m][k], acc[ai][bj][m][n], 0, 0, 0); __builtin_amdgcn_s_setprio(0); } while (0)
; #define PG8_WAIT_V(n) asm volatile("s_waitcnt vmcnt(" #n ")" ::: "memory")
; #define PG8_WAIT_L(n) asm volatile("s_waitcnt lgkmcnt(" #n ")" ::: "memory")
; #define PG8_BAR __builtin_amdgcn_s_barrier()
; #define PG8_SCHED __builtin_amdgcn_sched_barrier(0)
; template <class Epi, class Sched, bool ALIGN_EPI = false, bool SP2 = false>
; __device__ __forceinline__ void gemm_phase(PG8_LAS unsigned char* lds, const Gemm g, const Sched& S, const Epi& E, const int wv  ) {
;     ...
;             const bool last = (t == nt - 2);
;             const char* a1 = cA + (size_t)(t + 1) * kstep;
;             const char* a2 = last ? nA : cA + (size_t)(t + 2) * kstep; const char* b2 = last ? nB : cB + (size_t)(t + 2) * kstep;
;             const char* a3 = a2 + kstep; const char* b3 = b2 + kstep;
;             if (last && has_next) S.a_ready(nxt);
;             if constexpr (SP2) {
;             PG8_LDB(B0, 0, 0); PG8_LDB(B1, 0, 1); PG8_SCHED; PG8_LDA(At, 0, 0); PG8_STAGE(PG8_SA(1, 1), a1 + hstepA, voffA);
;             PG8_WAIT_V(8); PG8_WAIT_L(0); PG8_BAR; PG8_MMA(0, 0, At, B0); PG8_MMA(0, 1, At, B1); PG8_BAR; PG8_SCHED;
;             PG8_LDA(At, 0, 1); PG8_STAGE(PG8_SB(0, 0), b2, voffB); PG8_STAGE(PG8_SB(0, 1), b2 + hstepB, voffB); PG8_STAGE(PG8_SA(0, 0), a2, voffA);
.LBB0_871:
	ds_read_b128 v[142:145], v148
	ds_read_b128 v[152:155], v148 offset:1024
	ds_read_b128 v[156:159], v148 offset:2048
	ds_read_b128 v[160:163], v148 offset:3072
	ds_read_b128 v[164:167], v149
	ds_read_b128 v[168:171], v149 offset:1024
	ds_read_b128 v[172:175], v149 offset:2048
	ds_read_b128 v[176:179], v149 offset:3072
	s_add_u32 s60, s58, 0xfff00080
	s_addc_u32 s61, s59, -1
	s_cmp_eq_u32 s96, 60
	s_cselect_b32 s63, s49, s61
	s_cselect_b32 s62, s92, s60
	s_cselect_b32 s61, s47, s95
	s_cselect_b32 s60, s93, s94
	v_lshl_add_u64 v[212:213], s[58:59], 0, v[138:139]
	s_add_i32 m0, s75, 0xc000
	ds_read_b128 v[180:183], v150
	ds_read_b128 v[184:187], v150 offset:1024
	ds_read_b128 v[188:191], v150 offset:2048
	ds_read_b128 v[192:195], v150 offset:3072
	ds_read_b128 v[196:199], v150 offset:4096
	ds_read_b128 v[200:203], v150 offset:5120
	ds_read_b128 v[204:207], v150 offset:6144
	ds_read_b128 v[208:211], v150 offset:7168
	global_load_lds_dwordx4 v[212:213], off
	v_lshl_add_u64 v[212:213], s[58:59], 0, v[140:141]
	s_add_i32 m0, s75, 0xe000
	s_nop 0
	global_load_lds_dwordx4 v[212:213], off
	s_waitcnt vmcnt(8)
	s_waitcnt lgkmcnt(0)
	s_barrier
	s_setprio 2
	s_waitcnt lgkmcnt(0)
	v_mfma_f32_16x16x32_bf16 v[76:79], v[142:145], v[180:183], v[76:79]
	v_mfma_f32_16x16x32_bf16 v[72:75], v[156:159], v[180:183], v[72:75]
	v_mfma_f32_16x16x32_bf16 v[68:71], v[142:145], v[188:191], v[68:71]
	v_mfma_f32_16x16x32_bf16 v[64:67], v[156:159], v[188:191], v[64:67]
	v_mfma_f32_16x16x32_bf16 v[56:59], v[142:145], v[196:199], v[56:59]
	v_mfma_f32_16x16x32_bf16 v[52:55], v[156:159], v[196:199], v[52:55]
	v_mfma_f32_16x16x32_bf16 v[44:47], v[142:145], v[204:207], v[44:47]
	v_mfma_f32_16x16x32_bf16 v[40:43], v[156:159], v[204:207], v[40:43]
	v_mfma_f32_16x16x32_bf16 v[76:79], v[152:155], v[184:187], v[76:79]
	v_mfma_f32_16x16x32_bf16 v[72:75], v[160:163], v[184:187], v[72:75]
	v_mfma_f32_16x16x32_bf16 v[68:71], v[152:155], v[192:195], v[68:71]
	v_mfma_f32_16x16x32_bf16 v[64:67], v[160:163], v[192:195], v[64:67]
	v_mfma_f32_16x16x32_bf16 v[56:59], v[152:155], v[200:203], v[56:59]
	v_mfma_f32_16x16x32_bf16 v[52:55], v[160:163], v[200:203], v[52:55]
	v_mfma_f32_16x16x32_bf16 v[44:47], v[152:155], v[208:211], v[44:47]
	v_mfma_f32_16x16x32_bf16 v[40:43], v[160:163], v[208:211], v[40:43]
	s_setprio 0
	s_setprio 2
	v_mfma_f32_16x16x32_bf16 v[124:127], v[164:167], v[180:183], v[124:127]
	v_mfma_f32_16x16x32_bf16 v[120:123], v[172:175], v[180:183], v[120:123]
	v_mfma_f32_16x16x32_bf16 v[116:119], v[164:167], v[188:191], v[116:119]
	v_mfma_f32_16x16x32_bf16 v[112:115], v[172:175], v[188:191], v[112:115]
	v_mfma_f32_16x16x32_bf16 v[108:111], v[164:167], v[196:199], v[108:111]
	v_mfma_f32_16x16x32_bf16 v[104:107], v[172:175], v[196:199], v[104:107]
	v_mfma_f32_16x16x32_bf16 v[100:103], v[164:167], v[204:207], v[100:103]
	v_mfma_f32_16x16x32_bf16 v[96:99], v[172:175], v[204:207], v[96:99]
	v_mfma_f32_16x16x32_bf16 v[124:127], v[168:171], v[184:187], v[124:127]
	v_mfma_f32_16x16x32_bf16 v[120:123], v[176:179], v[184:187], v[120:123]
	v_mfma_f32_16x16x32_bf16 v[116:119], v[168:171], v[192:195], v[116:119]
	v_mfma_f32_16x16x32_bf16 v[112:115], v[176:179], v[192:195], v[112:115]
	v_mfma_f32_16x16x32_bf16 v[108:111], v[168:171], v[200:203], v[108:111]
	v_mfma_f32_16x16x32_bf16 v[104:107], v[176:179], v[200:203], v[104:107]
	v_mfma_f32_16x16x32_bf16 v[100:103], v[168:171], v[208:211], v[100:103]
	s_setprio 3
	s_barrier
	v_mfma_f32_16x16x32_bf16 v[96:99], v[176:179], v[208:211], v[96:99]
	s_setprio 0
	s_add_i32 s97, s84, s73
	v_lshl_add_u64 v[212:213], s[60:61], 0, v[132:133]
	s_mov_b32 m0, s97
	ds_read_b128 v[180:183], v150 offset:16384
	ds_read_b128 v[184:187], v150 offset:17408
	ds_read_b128 v[188:191], v150 offset:18432
	ds_read_b128 v[192:195], v150 offset:19456
	ds_read_b128 v[196:199], v150 offset:20480
	ds_read_b128 v[200:203], v150 offset:21504
	ds_read_b128 v[204:207], v150 offset:22528
	ds_read_b128 v[208:211], v150 offset:23552
	global_load_lds_dwordx4 v[212:213], off
	s_add_i32 m0, s97, 0x2000
	s_add_u32 vcc_lo, s60, 0x100000
	v_lshl_add_u64 v[214:215], s[60:61], 0, v[128:129]
	s_addc_u32 vcc_hi, s61, 0
	s_add_i32 s97, s85, s73
	global_load_lds_dwordx4 v[214:215], off
	v_lshl_add_u64 v[216:217], vcc, 0, v[132:133]
	s_mov_b32 m0, s97
	v_lshl_add_u64 v[218:219], s[62:63], 0, v[130:131]
	global_load_lds_dwordx4 v[216:217], off
	v_lshl_add_u64 v[216:217], vcc, 0, v[128:129]
	s_add_i32 m0, s97, 0x2000
	s_nop 0
	global_load_lds_dwordx4 v[216:217], off
	v_lshl_add_u64 v[216:217], s[62:63], 0, v[134:135]
	s_mov_b32 m0, s75
	s_nop 0
	global_load_lds_dwordx4 v[216:217], off
	s_mov_b32 m0, s76
	s_nop 0
	global_load_lds_dwordx4 v[218:219], off
	s_waitcnt vmcnt(8)
	s_waitcnt lgkmcnt(0)
	s_barrier
; #define PG8_STAGE(bufoff, gbase, voff) do { _Pragma("unroll") for (int _i = 0; _i < 2; ++_i) \
;         __builtin_amdgcn_global_load_lds((const unsigned*)((const char*)(gbase) + (voff)[_i]), (PG8_LAS unsigned*)(lds + (bufoff) + ldsw + _i * 8192), 16, 0, 0); } while (0)
; #define PG8_LDA(dst, b, h) do { _Pragma("unroll") for (int m = 0; m < 4; ++m) _Pragma("unroll") for (int k = 0; k < 2; ++k) dst[m][k] = *(const PG8_LAS bf16x8*)(lds + PG8_SA(b, h) + aoff + m * 2048 + k * 1024); } while (0)
; #define PG8_LDB(dst, b, h) do { _Pragma("unroll") for (int n = 0; n < 2; ++n) _Pragma("unroll") for (int k = 0; k < 2; ++k) dst[n][k] = *(const PG8_LAS bf16x8*)(lds + PG8_SB(b, h) + boff + n * 2048 + k * 1024); } while (0)
; #define PG8_MMA(ai, bj, At, Bt) do { __builtin_amdgcn_s_setprio(1); _Pragma("unroll") for (int m = 0; m < 4; ++m) _Pragma("unroll") for (int n = 0; n < 2; ++n) _Pragma("unroll") for (int k = 0; k < 2; ++k) \
;         acc[ai][bj][m][n] = __builtin_amdgcn_mfma_f32_16x16x32_bf16(Bt[n][k], At[m][k], acc[ai][bj][m][n], 0, 0, 0); __builtin_amdgcn_s_setprio(0); } while (0)
; #define PG8_WAIT_V(n) asm volatile("s_waitcnt vmcnt(" #n ")" ::: "memory")
; #define PG8_WAIT_L(n) asm volatile("s_waitcnt lgkmcnt(" #n ")" ::: "memory")
; #define PG8_BAR __builtin_amdgcn_s_barrier()
; #define PG8_SCHED __builtin_amdgcn_sched_barrier(0)
; template <class Epi, class Sched, bool ALIGN_EPI = false, bool SP2 = false>
; __device__ __forceinline__ void gemm_phase(PG8_LAS unsigned char* lds, const Gemm g, const Sched& S, const Epi& E, const int wv  ) {
;     ...
;             PG8_WAIT_V(8); PG8_WAIT_L(0); PG8_BAR; PG8_MMA(1, 0, At, B0); PG8_MMA(1, 1, At, B1); PG8_BAR; PG8_SCHED;
;             PG8_LDB(B0, 1, 0); PG8_LDB(B1, 1, 1); PG8_SCHED; PG8_LDA(At, 1, 0); PG8_STAGE(PG8_SA(0, 1), a2 + hstepA, voffA);
;             PG8_WAIT_V(8); PG8_WAIT_L(0); PG8_BAR; PG8_MMA(0, 0, At, B0); PG8_MMA(0, 1, At, B1); PG8_BAR; PG8_SCHED;
	s_setprio 2
	s_waitcnt lgkmcnt(0)
	v_mfma_f32_16x16x32_bf16 v[28:31], v[142:145], v[180:183], v[28:31]
	v_mfma_f32_16x16x32_bf16 v[24:27], v[156:159], v[180:183], v[24:27]
	v_mfma_f32_16x16x32_bf16 v[20:23], v[142:145], v[188:191], v[20:23]
	v_mfma_f32_16x16x32_bf16 v[16:19], v[156:159], v[188:191], v[16:19]
	v_mfma_f32_16x16x32_bf16 v[12:15], v[142:145], v[196:199], v[12:15]
	v_mfma_f32_16x16x32_bf16 v[8:11], v[156:159], v[196:199], v[8:11]
	v_mfma_f32_16x16x32_bf16 v[4:7], v[142:145], v[204:207], v[4:7]
	v_mfma_f32_16x16x32_bf16 v[0:3], v[156:159], v[204:207], v[0:3]
	v_mfma_f32_16x16x32_bf16 v[28:31], v[152:155], v[184:187], v[28:31]
	v_mfma_f32_16x16x32_bf16 v[24:27], v[160:163], v[184:187], v[24:27]
	v_mfma_f32_16x16x32_bf16 v[20:23], v[152:155], v[192:195], v[20:23]
	v_mfma_f32_16x16x32_bf16 v[16:19], v[160:163], v[192:195], v[16:19]
	v_mfma_f32_16x16x32_bf16 v[12:15], v[152:155], v[200:203], v[12:15]
	v_mfma_f32_16x16x32_bf16 v[8:11], v[160:163], v[200:203], v[8:11]
	v_mfma_f32_16x16x32_bf16 v[4:7], v[152:155], v[208:211], v[4:7]
	v_mfma_f32_16x16x32_bf16 v[0:3], v[160:163], v[208:211], v[0:3]
	s_setprio 0
	s_setprio 2
	v_mfma_f32_16x16x32_bf16 v[92:95], v[164:167], v[180:183], v[92:95]
	v_mfma_f32_16x16x32_bf16 v[88:91], v[172:175], v[180:183], v[88:91]
	v_mfma_f32_16x16x32_bf16 v[84:87], v[164:167], v[188:191], v[84:87]
	v_mfma_f32_16x16x32_bf16 v[80:83], v[172:175], v[188:191], v[80:83]
	v_mfma_f32_16x16x32_bf16 v[60:63], v[164:167], v[196:199], v[60:63]
	v_mfma_f32_16x16x32_bf16 v[48:51], v[172:175], v[196:199], v[48:51]
	v_mfma_f32_16x16x32_bf16 v[36:39], v[164:167], v[204:207], v[36:39]
	v_mfma_f32_16x16x32_bf16 v[32:35], v[172:175], v[204:207], v[32:35]
	v_mfma_f32_16x16x32_bf16 v[92:95], v[168:171], v[184:187], v[92:95]
	v_mfma_f32_16x16x32_bf16 v[88:91], v[176:179], v[184:187], v[88:91]
	v_mfma_f32_16x16x32_bf16 v[84:87], v[168:171], v[192:195], v[84:87]
	v_mfma_f32_16x16x32_bf16 v[80:83], v[176:179], v[192:195], v[80:83]
	v_mfma_f32_16x16x32_bf16 v[60:63], v[168:171], v[200:203], v[60:63]
	v_mfma_f32_16x16x32_bf16 v[48:51], v[176:179], v[200:203], v[48:51]
	v_mfma_f32_16x16x32_bf16 v[36:39], v[168:171], v[208:211], v[36:39]
	s_setprio 3
	s_barrier
	v_mfma_f32_16x16x32_bf16 v[32:35], v[176:179], v[208:211], v[32:35]
	s_setprio 0
	s_add_i32 s97, 0, 0x18000
	v_add_u32_e32 v151, s97, v146
	s_add_i32 vcc_lo, 0, 0x1c000
	ds_read_b128 v[142:145], v151
	ds_read_b128 v[152:155], v151 offset:1024
	ds_read_b128 v[156:159], v151 offset:2048
	ds_read_b128 v[160:163], v151 offset:3072
	v_add_u32_e32 v151, vcc_lo, v146
	ds_read_b128 v[164:167], v151
	ds_read_b128 v[168:171], v151 offset:1024
	ds_read_b128 v[172:175], v151 offset:2048
	ds_read_b128 v[176:179], v151 offset:3072
	s_add_u32 s62, s62, 0x100000
	s_addc_u32 s63, s63, 0
	s_mov_b32 m0, s77
	v_lshl_add_u64 v[220:221], s[62:63], 0, v[134:135]
	ds_read_b128 v[180:183], v150 offset:32768
	ds_read_b128 v[184:187], v150 offset:33792
	ds_read_b128 v[188:191], v150 offset:34816
	ds_read_b128 v[192:195], v150 offset:35840
	ds_read_b128 v[196:199], v150 offset:36864
	ds_read_b128 v[200:203], v150 offset:37888
	ds_read_b128 v[204:207], v150 offset:38912
	ds_read_b128 v[208:211], v150 offset:39936
	global_load_lds_dwordx4 v[220:221], off
	v_lshl_add_u64 v[220:221], s[62:63], 0, v[130:131]
	s_mov_b32 m0, s78
	s_nop 0
	global_load_lds_dwordx4 v[220:221], off
	s_waitcnt vmcnt(8)
	s_waitcnt lgkmcnt(0)
	s_barrier
	s_setprio 2
	s_waitcnt lgkmcnt(0)
	v_mfma_f32_16x16x32_bf16 v[76:79], v[142:145], v[180:183], v[76:79]
	v_mfma_f32_16x16x32_bf16 v[72:75], v[156:159], v[180:183], v[72:75]
	v_mfma_f32_16x16x32_bf16 v[68:71], v[142:145], v[188:191], v[68:71]
	v_mfma_f32_16x16x32_bf16 v[64:67], v[156:159], v[188:191], v[64:67]
	v_mfma_f32_16x16x32_bf16 v[56:59], v[142:145], v[196:199], v[56:59]
	v_mfma_f32_16x16x32_bf16 v[52:55], v[156:159], v[196:199], v[52:55]
	v_mfma_f32_16x16x32_bf16 v[44:47], v[142:145], v[204:207], v[44:47]
	v_mfma_f32_16x16x32_bf16 v[40:43], v[156:159], v[204:207], v[40:43]
	v_mfma_f32_16x16x32_bf16 v[76:79], v[152:155], v[184:187], v[76:79]
	v_mfma_f32_16x16x32_bf16 v[72:75], v[160:163], v[184:187], v[72:75]
	v_mfma_f32_16x16x32_bf16 v[68:71], v[152:155], v[192:195], v[68:71]
	v_mfma_f32_16x16x32_bf16 v[64:67], v[160:163], v[192:195], v[64:67]
	v_mfma_f32_16x16x32_bf16 v[56:59], v[152:155], v[200:203], v[56:59]
	v_mfma_f32_16x16x32_bf16 v[52:55], v[160:163], v[200:203], v[52:55]
	v_mfma_f32_16x16x32_bf16 v[44:47], v[152:155], v[208:211], v[44:47]
	v_mfma_f32_16x16x32_bf16 v[40:43], v[160:163], v[208:211], v[40:43]
	s_setprio 0
	s_setprio 2
	v_mfma_f32_16x16x32_bf16 v[124:127], v[164:167], v[180:183], v[124:127]
	v_mfma_f32_16x16x32_bf16 v[120:123], v[172:175], v[180:183], v[120:123]
	v_mfma_f32_16x16x32_bf16 v[116:119], v[164:167], v[188:191], v[116:119]
	v_mfma_f32_16x16x32_bf16 v[112:115], v[172:175], v[188:191], v[112:115]
	v_mfma_f32_16x16x32_bf16 v[108:111], v[164:167], v[196:199], v[108:111]
	v_mfma_f32_16x16x32_bf16 v[104:107], v[172:175], v[196:199], v[104:107]
	v_mfma_f32_16x16x32_bf16 v[100:103], v[164:167], v[204:207], v[100:103]
	v_mfma_f32_16x16x32_bf16 v[96:99], v[172:175], v[204:207], v[96:99]
	v_mfma_f32_16x16x32_bf16 v[124:127], v[168:171], v[184:187], v[124:127]
	v_mfma_f32_16x16x32_bf16 v[120:123], v[176:179], v[184:187], v[120:123]
	v_mfma_f32_16x16x32_bf16 v[116:119], v[168:171], v[192:195], v[116:119]
	v_mfma_f32_16x16x32_bf16 v[112:115], v[176:179], v[192:195], v[112:115]
	v_mfma_f32_16x16x32_bf16 v[108:111], v[168:171], v[200:203], v[108:111]
	v_mfma_f32_16x16x32_bf16 v[104:107], v[176:179], v[200:203], v[104:107]
	v_mfma_f32_16x16x32_bf16 v[100:103], v[168:171], v[208:211], v[100:103]
	s_setprio 3
	s_barrier
; #define PG8_STAGE(bufoff, gbase, voff) do { _Pragma("unroll") for (int _i = 0; _i < 2; ++_i) \
;         __builtin_amdgcn_global_load_lds((const unsigned*)((const char*)(gbase) + (voff)[_i]), (PG8_LAS unsigned*)(lds + (bufoff) + ldsw + _i * 8192), 16, 0, 0); } while (0)
; #define PG8_LDA(dst, b, h) do { _Pragma("unroll") for (int m = 0; m < 4; ++m) _Pragma("unroll") for (int k = 0; k < 2; ++k) dst[m][k] = *(const PG8_LAS bf16x8*)(lds + PG8_SA(b, h) + aoff + m * 2048 + k * 1024); } while (0)
; #define PG8_MMA(ai, bj, At, Bt) do { __builtin_amdgcn_s_setprio(1); _Pragma("unroll") for (int m = 0; m < 4; ++m) _Pragma("unroll") for (int n = 0; n < 2; ++n) _Pragma("unroll") for (int k = 0; k < 2; ++k) \
;         acc[ai][bj][m][n] = __builtin_amdgcn_mfma_f32_16x16x32_bf16(Bt[n][k], At[m][k], acc[ai][bj][m][n], 0, 0, 0); __builtin_amdgcn_s_setprio(0); } while (0)
; #define PG8_WAIT_V(n) asm volatile("s_waitcnt vmcnt(" #n ")" ::: "memory")
; #define PG8_WAIT_L(n) asm volatile("s_waitcnt lgkmcnt(" #n ")" ::: "memory")
; #define PG8_BAR __builtin_amdgcn_s_barrier()
; #define PG8_SCHED __builtin_amdgcn_sched_barrier(0)
; template <class Epi, class Sched, bool ALIGN_EPI = false, bool SP2 = false>
; __device__ __forceinline__ void gemm_phase(PG8_LAS unsigned char* lds, const Gemm g, const Sched& S, const Epi& E, const int wv  ) {
;     ...
;             PG8_LDA(At, 1, 1); PG8_STAGE(PG8_SB(1, 0), b3, voffB); PG8_STAGE(PG8_SB(1, 1), b3 + hstepB, voffB); PG8_STAGE(PG8_SA(1, 0), a3, voffA);
;             PG8_WAIT_V(8); PG8_WAIT_L(0); PG8_BAR; PG8_MMA(1, 0, At, B0); PG8_MMA(1, 1, At, B1); PG8_BAR; PG8_SCHED;
;     ...
;         if constexpr (ALIGN_EPI) { if (wr == 0) PG8_BAR; }
	v_mfma_f32_16x16x32_bf16 v[96:99], v[176:179], v[208:211], v[96:99]
	s_setprio 0
	s_add_i32 s62, s97, s73
	v_lshl_add_u64 v[212:213], v[212:213], 0, s[8:9]
	s_mov_b32 m0, s62
	ds_read_b128 v[180:183], v150 offset:49152
	ds_read_b128 v[184:187], v150 offset:50176
	ds_read_b128 v[188:191], v150 offset:51200
	ds_read_b128 v[192:195], v150 offset:52224
	ds_read_b128 v[196:199], v150 offset:53248
	ds_read_b128 v[200:203], v150 offset:54272
	ds_read_b128 v[204:207], v150 offset:55296
	ds_read_b128 v[208:211], v150 offset:56320
	global_load_lds_dwordx4 v[212:213], off
	s_add_i32 m0, s62, 0x2000
	s_add_u32 s60, s60, 0x100080
	v_lshl_add_u64 v[212:213], v[214:215], 0, s[8:9]
	s_addc_u32 s61, s61, 0
	s_add_i32 s62, vcc_lo, s73
	global_load_lds_dwordx4 v[212:213], off
	v_lshl_add_u64 v[212:213], s[60:61], 0, v[132:133]
	s_mov_b32 m0, s62
	s_nop 0
	global_load_lds_dwordx4 v[212:213], off
	v_lshl_add_u64 v[212:213], s[60:61], 0, v[128:129]
	s_add_i32 m0, s62, 0x2000
	s_nop 0
	global_load_lds_dwordx4 v[212:213], off
	v_lshl_add_u64 v[212:213], v[216:217], 0, s[8:9]
	s_mov_b32 m0, s80
	s_nop 0
	global_load_lds_dwordx4 v[212:213], off
	v_lshl_add_u64 v[212:213], v[218:219], 0, s[8:9]
	s_mov_b32 m0, s81
	s_nop 0
	global_load_lds_dwordx4 v[212:213], off
	s_waitcnt vmcnt(8)
	s_waitcnt lgkmcnt(0)
	s_barrier
	s_setprio 2
	s_waitcnt lgkmcnt(0)
	v_mfma_f32_16x16x32_bf16 v[28:31], v[142:145], v[180:183], v[28:31]
	v_mfma_f32_16x16x32_bf16 v[24:27], v[156:159], v[180:183], v[24:27]
	v_mfma_f32_16x16x32_bf16 v[20:23], v[142:145], v[188:191], v[20:23]
	v_mfma_f32_16x16x32_bf16 v[16:19], v[156:159], v[188:191], v[16:19]
	v_mfma_f32_16x16x32_bf16 v[12:15], v[142:145], v[196:199], v[12:15]
	v_mfma_f32_16x16x32_bf16 v[8:11], v[156:159], v[196:199], v[8:11]
	v_mfma_f32_16x16x32_bf16 v[4:7], v[142:145], v[204:207], v[4:7]
	v_mfma_f32_16x16x32_bf16 v[0:3], v[156:159], v[204:207], v[0:3]
	v_mfma_f32_16x16x32_bf16 v[28:31], v[152:155], v[184:187], v[28:31]
	v_mfma_f32_16x16x32_bf16 v[24:27], v[160:163], v[184:187], v[24:27]
	v_mfma_f32_16x16x32_bf16 v[20:23], v[152:155], v[192:195], v[20:23]
	v_mfma_f32_16x16x32_bf16 v[16:19], v[160:163], v[192:195], v[16:19]
	v_mfma_f32_16x16x32_bf16 v[12:15], v[152:155], v[200:203], v[12:15]
	v_mfma_f32_16x16x32_bf16 v[8:11], v[160:163], v[200:203], v[8:11]
	v_mfma_f32_16x16x32_bf16 v[4:7], v[152:155], v[208:211], v[4:7]
	v_mfma_f32_16x16x32_bf16 v[0:3], v[160:163], v[208:211], v[0:3]
	s_setprio 0
	s_setprio 2
	v_mfma_f32_16x16x32_bf16 v[92:95], v[164:167], v[180:183], v[92:95]
	v_mfma_f32_16x16x32_bf16 v[88:91], v[172:175], v[180:183], v[88:91]
	v_mfma_f32_16x16x32_bf16 v[84:87], v[164:167], v[188:191], v[84:87]
	v_mfma_f32_16x16x32_bf16 v[80:83], v[172:175], v[188:191], v[80:83]
	v_mfma_f32_16x16x32_bf16 v[60:63], v[164:167], v[196:199], v[60:63]
	v_mfma_f32_16x16x32_bf16 v[48:51], v[172:175], v[196:199], v[48:51]
	v_mfma_f32_16x16x32_bf16 v[36:39], v[164:167], v[204:207], v[36:39]
	v_mfma_f32_16x16x32_bf16 v[32:35], v[172:175], v[204:207], v[32:35]
	v_mfma_f32_16x16x32_bf16 v[92:95], v[168:171], v[184:187], v[92:95]
	v_mfma_f32_16x16x32_bf16 v[88:91], v[176:179], v[184:187], v[88:91]
	v_mfma_f32_16x16x32_bf16 v[84:87], v[168:171], v[192:195], v[84:87]
	v_mfma_f32_16x16x32_bf16 v[80:83], v[176:179], v[192:195], v[80:83]
	v_mfma_f32_16x16x32_bf16 v[60:63], v[168:171], v[200:203], v[60:63]
	v_mfma_f32_16x16x32_bf16 v[48:51], v[176:179], v[200:203], v[48:51]
	v_mfma_f32_16x16x32_bf16 v[36:39], v[168:171], v[208:211], v[36:39]
	s_setprio 3
	s_barrier
	v_mfma_f32_16x16x32_bf16 v[32:35], v[176:179], v[208:211], v[32:35]
	s_setprio 0
	s_add_i32 s96, s96, 2
	s_add_u32 s58, s58, 0x100
	s_addc_u32 s59, s59, 0
	s_add_u32 s94, s94, 0x100
	s_addc_u32 s95, s95, 0
	s_cmp_gt_u32 s96, 61
	s_cbranch_scc0 .LBB0_871
	s_and_b64 vcc, exec, s[10:11]
	s_cbranch_vccz .LBB0_874
	s_barrier

; #define PG8_STAGE(bufoff, gbase, voff) do { _Pragma("unroll") for (int _i = 0; _i < 2; ++_i) \
;         __builtin_amdgcn_global_load_lds((const unsigned*)((const char*)(gbase) + (voff)[_i]), (PG8_LAS unsigned*)(lds + (bufoff) + ldsw + _i * 8192), 16, 0, 0); } while (0)
; #define PG8_LDA(dst, b, h) do { _Pragma("unroll") for (int m = 0; m < 4; ++m) _Pragma("unroll") for (int k = 0; k < 2; ++k) dst[m][k] = *(const PG8_LAS bf16x8*)(lds + PG8_SA(b, h) + aoff + m * 2048 + k * 1024); } while (0)
; #define PG8_LDB(dst, b, h) do { _Pragma("unroll") for (int n = 0; n < 2; ++n) _Pragma("unroll") for (int k = 0; k < 2; ++k) dst[n][k] = *(const PG8_LAS bf16x8*)(lds + PG8_SB(b, h) + boff + n * 2048 + k * 1024); } while (0)
; #define PG8_MMA(ai, bj, At, Bt) do { __builtin_amdgcn_s_setprio(1); _Pragma("unroll") for (int m = 0; m < 4; ++m) _Pragma("unroll") for (int n = 0; n < 2; ++n) _Pragma("unroll") for (int k = 0; k < 2; ++k) \
;         acc[ai][bj][m][n] = __builtin_amdgcn_mfma_f32_16x16x32_bf16(Bt[n][k], At[m][k], acc[ai][bj][m][n], 0, 0, 0); __builtin_amdgcn_s_setprio(0); } while (0)
; #define PG8_WAIT_V(n) asm volatile("s_waitcnt vmcnt(" #n ")" ::: "memory")
; #define PG8_WAIT_L(n) asm volatile("s_waitcnt lgkmcnt(" #n ")" ::: "memory")
; #define PG8_BAR __builtin_amdgcn_s_barrier()
; #define PG8_SCHED __builtin_amdgcn_sched_barrier(0)
; template <class Epi, class Sched, bool ALIGN_EPI = false, bool SP2 = false>
; __device__ __forceinline__ void gemm_phase(PG8_LAS unsigned char* lds, const Gemm g, const Sched& S, const Epi& E, const int wv  ) {
;     ...
;             const bool last = (t == nt - 2);
;             const char* a1 = cA + (size_t)(t + 1) * kstep;
;             const char* a2 = last ? nA : cA + (size_t)(t + 2) * kstep; const char* b2 = last ? nB : cB + (size_t)(t + 2) * kstep;
;             const char* a3 = a2 + kstep; const char* b3 = b2 + kstep;
;             if (last && has_next) S.a_ready(nxt);
;             if constexpr (SP2) {
;             PG8_LDB(B0, 0, 0); PG8_LDB(B1, 0, 1); PG8_SCHED; PG8_LDA(At, 0, 0); PG8_STAGE(PG8_SA(1, 1), a1 + hstepA, voffA);
;             PG8_WAIT_V(8); PG8_WAIT_L(0); PG8_BAR; PG8_MMA(0, 0, At, B0); PG8_MMA(0, 1, At, B1); PG8_BAR; PG8_SCHED;
;             PG8_LDA(At, 0, 1); PG8_STAGE(PG8_SB(0, 0), b2, voffB); PG8_STAGE(PG8_SB(0, 1), b2 + hstepB, voffB); PG8_STAGE(PG8_SA(0, 0), a2, voffA);
.LBB0_892:
	ds_read_b128 v[142:145], v148
	ds_read_b128 v[152:155], v148 offset:1024
	ds_read_b128 v[156:159], v148 offset:2048
	ds_read_b128 v[160:163], v148 offset:3072
	ds_read_b128 v[164:167], v149
	ds_read_b128 v[168:171], v149 offset:1024
	ds_read_b128 v[172:175], v149 offset:2048
	ds_read_b128 v[176:179], v149 offset:3072
	s_add_u32 s60, s58, 0xfff00080
	s_addc_u32 s61, s59, -1
	s_cmp_eq_u32 s92, 60
	s_cselect_b32 s63, s49, s61
	s_cselect_b32 s62, s86, s60
	s_cselect_b32 s61, s47, s91
	s_cselect_b32 s60, s87, s90
	v_lshl_add_u64 v[212:213], s[58:59], 0, v[138:139]
	s_add_i32 m0, s71, 0xc000
	ds_read_b128 v[180:183], v150
	ds_read_b128 v[184:187], v150 offset:1024
	ds_read_b128 v[188:191], v150 offset:2048
	ds_read_b128 v[192:195], v150 offset:3072
	ds_read_b128 v[196:199], v150 offset:4096
	ds_read_b128 v[200:203], v150 offset:5120
	ds_read_b128 v[204:207], v150 offset:6144
	ds_read_b128 v[208:211], v150 offset:7168
	global_load_lds_dwordx4 v[212:213], off
	v_lshl_add_u64 v[212:213], s[58:59], 0, v[140:141]
	s_add_i32 m0, s71, 0xe000
	s_nop 0
	global_load_lds_dwordx4 v[212:213], off
	s_waitcnt vmcnt(8)
	s_waitcnt lgkmcnt(0)
	s_barrier
	s_setprio 2
	s_waitcnt lgkmcnt(0)
	v_mfma_f32_16x16x32_bf16 v[76:79], v[142:145], v[180:183], v[76:79]
	v_mfma_f32_16x16x32_bf16 v[72:75], v[156:159], v[180:183], v[72:75]
	v_mfma_f32_16x16x32_bf16 v[68:71], v[142:145], v[188:191], v[68:71]
	v_mfma_f32_16x16x32_bf16 v[64:67], v[156:159], v[188:191], v[64:67]
	v_mfma_f32_16x16x32_bf16 v[56:59], v[142:145], v[196:199], v[56:59]
	v_mfma_f32_16x16x32_bf16 v[52:55], v[156:159], v[196:199], v[52:55]
	v_mfma_f32_16x16x32_bf16 v[44:47], v[142:145], v[204:207], v[44:47]
	v_mfma_f32_16x16x32_bf16 v[40:43], v[156:159], v[204:207], v[40:43]
	v_mfma_f32_16x16x32_bf16 v[76:79], v[152:155], v[184:187], v[76:79]
	v_mfma_f32_16x16x32_bf16 v[72:75], v[160:163], v[184:187], v[72:75]
	v_mfma_f32_16x16x32_bf16 v[68:71], v[152:155], v[192:195], v[68:71]
	v_mfma_f32_16x16x32_bf16 v[64:67], v[160:163], v[192:195], v[64:67]
	v_mfma_f32_16x16x32_bf16 v[56:59], v[152:155], v[200:203], v[56:59]
	v_mfma_f32_16x16x32_bf16 v[52:55], v[160:163], v[200:203], v[52:55]
	v_mfma_f32_16x16x32_bf16 v[44:47], v[152:155], v[208:211], v[44:47]
	v_mfma_f32_16x16x32_bf16 v[40:43], v[160:163], v[208:211], v[40:43]
	s_setprio 0
	s_setprio 2
	v_mfma_f32_16x16x32_bf16 v[124:127], v[164:167], v[180:183], v[124:127]
	v_mfma_f32_16x16x32_bf16 v[120:123], v[172:175], v[180:183], v[120:123]
	v_mfma_f32_16x16x32_bf16 v[116:119], v[164:167], v[188:191], v[116:119]
	v_mfma_f32_16x16x32_bf16 v[112:115], v[172:175], v[188:191], v[112:115]
	v_mfma_f32_16x16x32_bf16 v[108:111], v[164:167], v[196:199], v[108:111]
	v_mfma_f32_16x16x32_bf16 v[104:107], v[172:175], v[196:199], v[104:107]
	v_mfma_f32_16x16x32_bf16 v[100:103], v[164:167], v[204:207], v[100:103]
	v_mfma_f32_16x16x32_bf16 v[96:99], v[172:175], v[204:207], v[96:99]
	v_mfma_f32_16x16x32_bf16 v[124:127], v[168:171], v[184:187], v[124:127]
	v_mfma_f32_16x16x32_bf16 v[120:123], v[176:179], v[184:187], v[120:123]
	v_mfma_f32_16x16x32_bf16 v[116:119], v[168:171], v[192:195], v[116:119]
	v_mfma_f32_16x16x32_bf16 v[112:115], v[176:179], v[192:195], v[112:115]
	v_mfma_f32_16x16x32_bf16 v[108:111], v[168:171], v[200:203], v[108:111]
	v_mfma_f32_16x16x32_bf16 v[104:107], v[176:179], v[200:203], v[104:107]
	v_mfma_f32_16x16x32_bf16 v[100:103], v[168:171], v[208:211], v[100:103]
	s_setprio 3
	s_barrier
	v_mfma_f32_16x16x32_bf16 v[96:99], v[176:179], v[208:211], v[96:99]
	s_setprio 0
	s_add_i32 s93, s84, s69
	v_lshl_add_u64 v[212:213], s[60:61], 0, v[132:133]
	s_mov_b32 m0, s93
	ds_read_b128 v[180:183], v150 offset:16384
	ds_read_b128 v[184:187], v150 offset:17408
	ds_read_b128 v[188:191], v150 offset:18432
	ds_read_b128 v[192:195], v150 offset:19456
	ds_read_b128 v[196:199], v150 offset:20480
	ds_read_b128 v[200:203], v150 offset:21504
	ds_read_b128 v[204:207], v150 offset:22528
	ds_read_b128 v[208:211], v150 offset:23552
	global_load_lds_dwordx4 v[212:213], off
	s_add_i32 m0, s93, 0x2000
	s_add_u32 s94, s60, 0x100000
	v_lshl_add_u64 v[214:215], s[60:61], 0, v[128:129]
	s_addc_u32 s95, s61, 0
	s_add_i32 s93, s85, s69
	global_load_lds_dwordx4 v[214:215], off
	v_lshl_add_u64 v[216:217], s[94:95], 0, v[132:133]
	s_mov_b32 m0, s93
	v_lshl_add_u64 v[218:219], s[62:63], 0, v[130:131]
	global_load_lds_dwordx4 v[216:217], off
	v_lshl_add_u64 v[216:217], s[94:95], 0, v[128:129]
	s_add_i32 m0, s93, 0x2000
	s_nop 0
	global_load_lds_dwordx4 v[216:217], off
	v_lshl_add_u64 v[216:217], s[62:63], 0, v[134:135]
	s_mov_b32 m0, s71
	s_nop 0
	global_load_lds_dwordx4 v[216:217], off
	s_mov_b32 m0, s72
	s_nop 0
	global_load_lds_dwordx4 v[218:219], off
	s_waitcnt vmcnt(8)
	s_waitcnt lgkmcnt(0)
	s_barrier
; #define PG8_STAGE(bufoff, gbase, voff) do { _Pragma("unroll") for (int _i = 0; _i < 2; ++_i) \
;         __builtin_amdgcn_global_load_lds((const unsigned*)((const char*)(gbase) + (voff)[_i]), (PG8_LAS unsigned*)(lds + (bufoff) + ldsw + _i * 8192), 16, 0, 0); } while (0)
; #define PG8_LDA(dst, b, h) do { _Pragma("unroll") for (int m = 0; m < 4; ++m) _Pragma("unroll") for (int k = 0; k < 2; ++k) dst[m][k] = *(const PG8_LAS bf16x8*)(lds + PG8_SA(b, h) + aoff + m * 2048 + k * 1024); } while (0)
; #define PG8_LDB(dst, b, h) do { _Pragma("unroll") for (int n = 0; n < 2; ++n) _Pragma("unroll") for (int k = 0; k < 2; ++k) dst[n][k] = *(const PG8_LAS bf16x8*)(lds + PG8_SB(b, h) + boff + n * 2048 + k * 1024); } while (0)
; #define PG8_MMA(ai, bj, At, Bt) do { __builtin_amdgcn_s_setprio(1); _Pragma("unroll") for (int m = 0; m < 4; ++m) _Pragma("unroll") for (int n = 0; n < 2; ++n) _Pragma("unroll") for (int k = 0; k < 2; ++k) \
;         acc[ai][bj][m][n] = __builtin_amdgcn_mfma_f32_16x16x32_bf16(Bt[n][k], At[m][k], acc[ai][bj][m][n], 0, 0, 0); __builtin_amdgcn_s_setprio(0); } while (0)
; #define PG8_WAIT_V(n) asm volatile("s_waitcnt vmcnt(" #n ")" ::: "memory")
; #define PG8_WAIT_L(n) asm volatile("s_waitcnt lgkmcnt(" #n ")" ::: "memory")
; #define PG8_BAR __builtin_amdgcn_s_barrier()
; #define PG8_SCHED __builtin_amdgcn_sched_barrier(0)
; template <class Epi, class Sched, bool ALIGN_EPI = false, bool SP2 = false>
; __device__ __forceinline__ void gemm_phase(PG8_LAS unsigned char* lds, const Gemm g, const Sched& S, const Epi& E, const int wv  ) {
;     ...
;             PG8_WAIT_V(8); PG8_WAIT_L(0); PG8_BAR; PG8_MMA(1, 0, At, B0); PG8_MMA(1, 1, At, B1); PG8_BAR; PG8_SCHED;
;             PG8_LDB(B0, 1, 0); PG8_LDB(B1, 1, 1); PG8_SCHED; PG8_LDA(At, 1, 0); PG8_STAGE(PG8_SA(0, 1), a2 + hstepA, voffA);
;             PG8_WAIT_V(8); PG8_WAIT_L(0); PG8_BAR; PG8_MMA(0, 0, At, B0); PG8_MMA(0, 1, At, B1); PG8_BAR; PG8_SCHED;
	s_setprio 2
	s_waitcnt lgkmcnt(0)
	v_mfma_f32_16x16x32_bf16 v[28:31], v[142:145], v[180:183], v[28:31]
	v_mfma_f32_16x16x32_bf16 v[24:27], v[156:159], v[180:183], v[24:27]
	v_mfma_f32_16x16x32_bf16 v[20:23], v[142:145], v[188:191], v[20:23]
	v_mfma_f32_16x16x32_bf16 v[16:19], v[156:159], v[188:191], v[16:19]
	v_mfma_f32_16x16x32_bf16 v[12:15], v[142:145], v[196:199], v[12:15]
	v_mfma_f32_16x16x32_bf16 v[8:11], v[156:159], v[196:199], v[8:11]
	v_mfma_f32_16x16x32_bf16 v[4:7], v[142:145], v[204:207], v[4:7]
	v_mfma_f32_16x16x32_bf16 v[0:3], v[156:159], v[204:207], v[0:3]
	v_mfma_f32_16x16x32_bf16 v[28:31], v[152:155], v[184:187], v[28:31]
	v_mfma_f32_16x16x32_bf16 v[24:27], v[160:163], v[184:187], v[24:27]
	v_mfma_f32_16x16x32_bf16 v[20:23], v[152:155], v[192:195], v[20:23]
	v_mfma_f32_16x16x32_bf16 v[16:19], v[160:163], v[192:195], v[16:19]
	v_mfma_f32_16x16x32_bf16 v[12:15], v[152:155], v[200:203], v[12:15]
	v_mfma_f32_16x16x32_bf16 v[8:11], v[160:163], v[200:203], v[8:11]
	v_mfma_f32_16x16x32_bf16 v[4:7], v[152:155], v[208:211], v[4:7]
	v_mfma_f32_16x16x32_bf16 v[0:3], v[160:163], v[208:211], v[0:3]
	s_setprio 0
	s_setprio 2
	v_mfma_f32_16x16x32_bf16 v[92:95], v[164:167], v[180:183], v[92:95]
	v_mfma_f32_16x16x32_bf16 v[88:91], v[172:175], v[180:183], v[88:91]
	v_mfma_f32_16x16x32_bf16 v[84:87], v[164:167], v[188:191], v[84:87]
	v_mfma_f32_16x16x32_bf16 v[80:83], v[172:175], v[188:191], v[80:83]
	v_mfma_f32_16x16x32_bf16 v[60:63], v[164:167], v[196:199], v[60:63]
	v_mfma_f32_16x16x32_bf16 v[48:51], v[172:175], v[196:199], v[48:51]
	v_mfma_f32_16x16x32_bf16 v[36:39], v[164:167], v[204:207], v[36:39]
	v_mfma_f32_16x16x32_bf16 v[32:35], v[172:175], v[204:207], v[32:35]
	v_mfma_f32_16x16x32_bf16 v[92:95], v[168:171], v[184:187], v[92:95]
	v_mfma_f32_16x16x32_bf16 v[88:91], v[176:179], v[184:187], v[88:91]
	v_mfma_f32_16x16x32_bf16 v[84:87], v[168:171], v[192:195], v[84:87]
	v_mfma_f32_16x16x32_bf16 v[80:83], v[176:179], v[192:195], v[80:83]
	v_mfma_f32_16x16x32_bf16 v[60:63], v[168:171], v[200:203], v[60:63]
	v_mfma_f32_16x16x32_bf16 v[48:51], v[176:179], v[200:203], v[48:51]
	v_mfma_f32_16x16x32_bf16 v[36:39], v[168:171], v[208:211], v[36:39]
	s_setprio 3
	s_barrier
	v_mfma_f32_16x16x32_bf16 v[32:35], v[176:179], v[208:211], v[32:35]
	s_setprio 0
	s_add_i32 s93, 0, 0x18000
	v_add_u32_e32 v151, s93, v146
	s_add_i32 s94, 0, 0x1c000
	ds_read_b128 v[142:145], v151
	ds_read_b128 v[152:155], v151 offset:1024
	ds_read_b128 v[156:159], v151 offset:2048
	ds_read_b128 v[160:163], v151 offset:3072
	v_add_u32_e32 v151, s94, v146
	ds_read_b128 v[164:167], v151
	ds_read_b128 v[168:171], v151 offset:1024
	ds_read_b128 v[172:175], v151 offset:2048
	ds_read_b128 v[176:179], v151 offset:3072
	s_add_u32 s62, s62, 0x100000
	s_addc_u32 s63, s63, 0
	s_mov_b32 m0, s73
	v_lshl_add_u64 v[220:221], s[62:63], 0, v[134:135]
	ds_read_b128 v[180:183], v150 offset:32768
	ds_read_b128 v[184:187], v150 offset:33792
	ds_read_b128 v[188:191], v150 offset:34816
	ds_read_b128 v[192:195], v150 offset:35840
	ds_read_b128 v[196:199], v150 offset:36864
	ds_read_b128 v[200:203], v150 offset:37888
	ds_read_b128 v[204:207], v150 offset:38912
	ds_read_b128 v[208:211], v150 offset:39936
	global_load_lds_dwordx4 v[220:221], off
	v_lshl_add_u64 v[220:221], s[62:63], 0, v[130:131]
	s_mov_b32 m0, s74
	s_nop 0
	global_load_lds_dwordx4 v[220:221], off
	s_waitcnt vmcnt(8)
	s_waitcnt lgkmcnt(0)
	s_barrier
	s_setprio 2
	s_waitcnt lgkmcnt(0)
	v_mfma_f32_16x16x32_bf16 v[76:79], v[142:145], v[180:183], v[76:79]
	v_mfma_f32_16x16x32_bf16 v[72:75], v[156:159], v[180:183], v[72:75]
	v_mfma_f32_16x16x32_bf16 v[68:71], v[142:145], v[188:191], v[68:71]
	v_mfma_f32_16x16x32_bf16 v[64:67], v[156:159], v[188:191], v[64:67]
	v_mfma_f32_16x16x32_bf16 v[56:59], v[142:145], v[196:199], v[56:59]
	v_mfma_f32_16x16x32_bf16 v[52:55], v[156:159], v[196:199], v[52:55]
	v_mfma_f32_16x16x32_bf16 v[44:47], v[142:145], v[204:207], v[44:47]
	v_mfma_f32_16x16x32_bf16 v[40:43], v[156:159], v[204:207], v[40:43]
	v_mfma_f32_16x16x32_bf16 v[76:79], v[152:155], v[184:187], v[76:79]
	v_mfma_f32_16x16x32_bf16 v[72:75], v[160:163], v[184:187], v[72:75]
	v_mfma_f32_16x16x32_bf16 v[68:71], v[152:155], v[192:195], v[68:71]
	v_mfma_f32_16x16x32_bf16 v[64:67], v[160:163], v[192:195], v[64:67]
	v_mfma_f32_16x16x32_bf16 v[56:59], v[152:155], v[200:203], v[56:59]
	v_mfma_f32_16x16x32_bf16 v[52:55], v[160:163], v[200:203], v[52:55]
	v_mfma_f32_16x16x32_bf16 v[44:47], v[152:155], v[208:211], v[44:47]
	v_mfma_f32_16x16x32_bf16 v[40:43], v[160:163], v[208:211], v[40:43]
	s_setprio 0
	s_setprio 2
	v_mfma_f32_16x16x32_bf16 v[124:127], v[164:167], v[180:183], v[124:127]
	v_mfma_f32_16x16x32_bf16 v[120:123], v[172:175], v[180:183], v[120:123]
	v_mfma_f32_16x16x32_bf16 v[116:119], v[164:167], v[188:191], v[116:119]
	v_mfma_f32_16x16x32_bf16 v[112:115], v[172:175], v[188:191], v[112:115]
	v_mfma_f32_16x16x32_bf16 v[108:111], v[164:167], v[196:199], v[108:111]
	v_mfma_f32_16x16x32_bf16 v[104:107], v[172:175], v[196:199], v[104:107]
	v_mfma_f32_16x16x32_bf16 v[100:103], v[164:167], v[204:207], v[100:103]
	v_mfma_f32_16x16x32_bf16 v[96:99], v[172:175], v[204:207], v[96:99]
	v_mfma_f32_16x16x32_bf16 v[124:127], v[168:171], v[184:187], v[124:127]
	v_mfma_f32_16x16x32_bf16 v[120:123], v[176:179], v[184:187], v[120:123]
	v_mfma_f32_16x16x32_bf16 v[116:119], v[168:171], v[192:195], v[116:119]
	v_mfma_f32_16x16x32_bf16 v[112:115], v[176:179], v[192:195], v[112:115]
	v_mfma_f32_16x16x32_bf16 v[108:111], v[168:171], v[200:203], v[108:111]
	v_mfma_f32_16x16x32_bf16 v[104:107], v[176:179], v[200:203], v[104:107]
	v_mfma_f32_16x16x32_bf16 v[100:103], v[168:171], v[208:211], v[100:103]
	s_setprio 3
	s_barrier
; #define PG8_STAGE(bufoff, gbase, voff) do { _Pragma("unroll") for (int _i = 0; _i < 2; ++_i) \
;         __builtin_amdgcn_global_load_lds((const unsigned*)((const char*)(gbase) + (voff)[_i]), (PG8_LAS unsigned*)(lds + (bufoff) + ldsw + _i * 8192), 16, 0, 0); } while (0)
; #define PG8_LDA(dst, b, h) do { _Pragma("unroll") for (int m = 0; m < 4; ++m) _Pragma("unroll") for (int k = 0; k < 2; ++k) dst[m][k] = *(const PG8_LAS bf16x8*)(lds + PG8_SA(b, h) + aoff + m * 2048 + k * 1024); } while (0)
; #define PG8_MMA(ai, bj, At, Bt) do { __builtin_amdgcn_s_setprio(1); _Pragma("unroll") for (int m = 0; m < 4; ++m) _Pragma("unroll") for (int n = 0; n < 2; ++n) _Pragma("unroll") for (int k = 0; k < 2; ++k) \
;         acc[ai][bj][m][n] = __builtin_amdgcn_mfma_f32_16x16x32_bf16(Bt[n][k], At[m][k], acc[ai][bj][m][n], 0, 0, 0); __builtin_amdgcn_s_setprio(0); } while (0)
; #define PG8_WAIT_V(n) asm volatile("s_waitcnt vmcnt(" #n ")" ::: "memory")
; #define PG8_WAIT_L(n) asm volatile("s_waitcnt lgkmcnt(" #n ")" ::: "memory")
; #define PG8_BAR __builtin_amdgcn_s_barrier()
; #define PG8_SCHED __builtin_amdgcn_sched_barrier(0)
; template <class Epi, class Sched, bool ALIGN_EPI = false, bool SP2 = false>
; __device__ __forceinline__ void gemm_phase(PG8_LAS unsigned char* lds, const Gemm g, const Sched& S, const Epi& E, const int wv  ) {
;     ...
;             PG8_LDA(At, 1, 1); PG8_STAGE(PG8_SB(1, 0), b3, voffB); PG8_STAGE(PG8_SB(1, 1), b3 + hstepB, voffB); PG8_STAGE(PG8_SA(1, 0), a3, voffA);
;             PG8_WAIT_V(8); PG8_WAIT_L(0); PG8_BAR; PG8_MMA(1, 0, At, B0); PG8_MMA(1, 1, At, B1); PG8_BAR; PG8_SCHED;
;     ...
;         if constexpr (ALIGN_EPI) { if (wr == 0) PG8_BAR; }
	v_mfma_f32_16x16x32_bf16 v[96:99], v[176:179], v[208:211], v[96:99]
	s_setprio 0
	s_add_i32 s62, s93, s69
	v_lshl_add_u64 v[212:213], v[212:213], 0, s[8:9]
	s_mov_b32 m0, s62
	ds_read_b128 v[180:183], v150 offset:49152
	ds_read_b128 v[184:187], v150 offset:50176
	ds_read_b128 v[188:191], v150 offset:51200
	ds_read_b128 v[192:195], v150 offset:52224
	ds_read_b128 v[196:199], v150 offset:53248
	ds_read_b128 v[200:203], v150 offset:54272
	ds_read_b128 v[204:207], v150 offset:55296
	ds_read_b128 v[208:211], v150 offset:56320
	global_load_lds_dwordx4 v[212:213], off
	s_add_i32 m0, s62, 0x2000
	s_add_u32 s60, s60, 0x100080
	v_lshl_add_u64 v[212:213], v[214:215], 0, s[8:9]
	s_addc_u32 s61, s61, 0
	s_add_i32 s62, s94, s69
	global_load_lds_dwordx4 v[212:213], off
	v_lshl_add_u64 v[212:213], s[60:61], 0, v[132:133]
	s_mov_b32 m0, s62
	s_nop 0
	global_load_lds_dwordx4 v[212:213], off
	v_lshl_add_u64 v[212:213], s[60:61], 0, v[128:129]
	s_add_i32 m0, s62, 0x2000
	s_nop 0
	global_load_lds_dwordx4 v[212:213], off
	v_lshl_add_u64 v[212:213], v[216:217], 0, s[8:9]
	s_mov_b32 m0, s81
	s_nop 0
	global_load_lds_dwordx4 v[212:213], off
	v_lshl_add_u64 v[212:213], v[218:219], 0, s[8:9]
	s_mov_b32 m0, s82
	s_nop 0
	global_load_lds_dwordx4 v[212:213], off
	s_waitcnt vmcnt(8)
	s_waitcnt lgkmcnt(0)
	s_barrier
	s_setprio 2
	s_waitcnt lgkmcnt(0)
	v_mfma_f32_16x16x32_bf16 v[28:31], v[142:145], v[180:183], v[28:31]
	v_mfma_f32_16x16x32_bf16 v[24:27], v[156:159], v[180:183], v[24:27]
	v_mfma_f32_16x16x32_bf16 v[20:23], v[142:145], v[188:191], v[20:23]
	v_mfma_f32_16x16x32_bf16 v[16:19], v[156:159], v[188:191], v[16:19]
	v_mfma_f32_16x16x32_bf16 v[12:15], v[142:145], v[196:199], v[12:15]
	v_mfma_f32_16x16x32_bf16 v[8:11], v[156:159], v[196:199], v[8:11]
	v_mfma_f32_16x16x32_bf16 v[4:7], v[142:145], v[204:207], v[4:7]
	v_mfma_f32_16x16x32_bf16 v[0:3], v[156:159], v[204:207], v[0:3]
	v_mfma_f32_16x16x32_bf16 v[28:31], v[152:155], v[184:187], v[28:31]
	v_mfma_f32_16x16x32_bf16 v[24:27], v[160:163], v[184:187], v[24:27]
	v_mfma_f32_16x16x32_bf16 v[20:23], v[152:155], v[192:195], v[20:23]
	v_mfma_f32_16x16x32_bf16 v[16:19], v[160:163], v[192:195], v[16:19]
	v_mfma_f32_16x16x32_bf16 v[12:15], v[152:155], v[200:203], v[12:15]
	v_mfma_f32_16x16x32_bf16 v[8:11], v[160:163], v[200:203], v[8:11]
	v_mfma_f32_16x16x32_bf16 v[4:7], v[152:155], v[208:211], v[4:7]
	v_mfma_f32_16x16x32_bf16 v[0:3], v[160:163], v[208:211], v[0:3]
	s_setprio 0
	s_setprio 2
	v_mfma_f32_16x16x32_bf16 v[92:95], v[164:167], v[180:183], v[92:95]
	v_mfma_f32_16x16x32_bf16 v[88:91], v[172:175], v[180:183], v[88:91]
	v_mfma_f32_16x16x32_bf16 v[84:87], v[164:167], v[188:191], v[84:87]
	v_mfma_f32_16x16x32_bf16 v[80:83], v[172:175], v[188:191], v[80:83]
	v_mfma_f32_16x16x32_bf16 v[60:63], v[164:167], v[196:199], v[60:63]
	v_mfma_f32_16x16x32_bf16 v[48:51], v[172:175], v[196:199], v[48:51]
	v_mfma_f32_16x16x32_bf16 v[36:39], v[164:167], v[204:207], v[36:39]
	v_mfma_f32_16x16x32_bf16 v[32:35], v[172:175], v[204:207], v[32:35]
	v_mfma_f32_16x16x32_bf16 v[92:95], v[168:171], v[184:187], v[92:95]
	v_mfma_f32_16x16x32_bf16 v[88:91], v[176:179], v[184:187], v[88:91]
	v_mfma_f32_16x16x32_bf16 v[84:87], v[168:171], v[192:195], v[84:87]
	v_mfma_f32_16x16x32_bf16 v[80:83], v[176:179], v[192:195], v[80:83]
	v_mfma_f32_16x16x32_bf16 v[60:63], v[168:171], v[200:203], v[60:63]
	v_mfma_f32_16x16x32_bf16 v[48:51], v[176:179], v[200:203], v[48:51]
	v_mfma_f32_16x16x32_bf16 v[36:39], v[168:171], v[208:211], v[36:39]
	s_setprio 3
	s_barrier
	v_mfma_f32_16x16x32_bf16 v[32:35], v[176:179], v[208:211], v[32:35]
	s_setprio 0
	s_add_i32 s92, s92, 2
	s_add_u32 s58, s58, 0x100
	s_addc_u32 s59, s59, 0
	s_add_u32 s90, s90, 0x100
	s_addc_u32 s91, s91, 0
	s_cmp_gt_u32 s92, 61
	s_cbranch_scc0 .LBB0_892
	s_and_b64 vcc, exec, s[10:11]
	s_cbranch_vccz .LBB0_895
	s_barrier

; #define PG8_STAGE(bufoff, gbase, voff) do { _Pragma("unroll") for (int _i = 0; _i < 2; ++_i) \
;         __builtin_amdgcn_global_load_lds((const unsigned*)((const char*)(gbase) + (voff)[_i]), (PG8_LAS unsigned*)(lds + (bufoff) + ldsw + _i * 8192), 16, 0, 0); } while (0)
; #define PG8_LDA(dst, b, h) do { _Pragma("unroll") for (int m = 0; m < 4; ++m) _Pragma("unroll") for (int k = 0; k < 2; ++k) dst[m][k] = *(const PG8_LAS bf16x8*)(lds + PG8_SA(b, h) + aoff + m * 2048 + k * 1024); } while (0)
; #define PG8_LDB(dst, b, h) do { _Pragma("unroll") for (int n = 0; n < 2; ++n) _Pragma("unroll") for (int k = 0; k < 2; ++k) dst[n][k] = *(const PG8_LAS bf16x8*)(lds + PG8_SB(b, h) + boff + n * 2048 + k * 1024); } while (0)
; #define PG8_MMA(ai, bj, At, Bt) do { __builtin_amdgcn_s_setprio(1); _Pragma("unroll") for (int m = 0; m < 4; ++m) _Pragma("unroll") for (int n = 0; n < 2; ++n) _Pragma("unroll") for (int k = 0; k < 2; ++k) \
;         acc[ai][bj][m][n] = __builtin_amdgcn_mfma_f32_16x16x32_bf16(Bt[n][k], At[m][k], acc[ai][bj][m][n], 0, 0, 0); __builtin_amdgcn_s_setprio(0); } while (0)
; #define PG8_WAIT_V(n) asm volatile("s_waitcnt vmcnt(" #n ")" ::: "memory")
; #define PG8_WAIT_L(n) asm volatile("s_waitcnt lgkmcnt(" #n ")" ::: "memory")
; #define PG8_BAR __builtin_amdgcn_s_barrier()
; #define PG8_SCHED __builtin_amdgcn_sched_barrier(0)
; template <class Epi, class Sched, bool ALIGN_EPI = false, bool SP2 = false>
; __device__ __forceinline__ void gemm_phase(PG8_LAS unsigned char* lds, const Gemm g, const Sched& S, const Epi& E, const int wv  ) {
;     ...
;             const bool last = (t == nt - 2);
;             const char* a1 = cA + (size_t)(t + 1) * kstep;
;             const char* a2 = last ? nA : cA + (size_t)(t + 2) * kstep; const char* b2 = last ? nB : cB + (size_t)(t + 2) * kstep;
;             const char* a3 = a2 + kstep; const char* b3 = b2 + kstep;
;             if (last && has_next) S.a_ready(nxt);
;             if constexpr (SP2) {
;             PG8_LDB(B0, 0, 0); PG8_LDB(B1, 0, 1); PG8_SCHED; PG8_LDA(At, 0, 0); PG8_STAGE(PG8_SA(1, 1), a1 + hstepA, voffA);
;             PG8_WAIT_V(8); PG8_WAIT_L(0); PG8_BAR; PG8_MMA(0, 0, At, B0); PG8_MMA(0, 1, At, B1); PG8_BAR; PG8_SCHED;
;             PG8_LDA(At, 0, 1); PG8_STAGE(PG8_SB(0, 0), b2, voffB); PG8_STAGE(PG8_SB(0, 1), b2 + hstepB, voffB); PG8_STAGE(PG8_SA(0, 0), a2, voffA);
.LBB0_1049:
	ds_read_b128 v[146:149], v152
	ds_read_b128 v[156:159], v152 offset:1024
	ds_read_b128 v[160:163], v152 offset:2048
	ds_read_b128 v[164:167], v152 offset:3072
	ds_read_b128 v[168:171], v153
	ds_read_b128 v[172:175], v153 offset:1024
	ds_read_b128 v[176:179], v153 offset:2048
	ds_read_b128 v[180:183], v153 offset:3072
	s_add_u32 s60, s58, 0xfffc0080
	s_addc_u32 s61, s59, -1
	s_cmp_eq_u32 s87, 12
	s_cselect_b32 s63, s51, s61
	s_cselect_b32 s62, s83, s60
	s_cselect_b32 s61, s49, s86
	s_cselect_b32 s60, s84, s85
	v_lshl_add_u64 v[216:217], s[58:59], 0, v[138:139]
	s_add_i32 m0, s68, 0xc000
	ds_read_b128 v[184:187], v154
	ds_read_b128 v[188:191], v154 offset:1024
	ds_read_b128 v[192:195], v154 offset:2048
	ds_read_b128 v[196:199], v154 offset:3072
	ds_read_b128 v[200:203], v154 offset:4096
	ds_read_b128 v[204:207], v154 offset:5120
	ds_read_b128 v[208:211], v154 offset:6144
	ds_read_b128 v[212:215], v154 offset:7168
	global_load_lds_dwordx4 v[216:217], off
	v_lshl_add_u64 v[216:217], s[58:59], 0, v[140:141]
	s_add_i32 m0, s68, 0xe000
	s_nop 0
	global_load_lds_dwordx4 v[216:217], off
	s_waitcnt vmcnt(8)
	s_waitcnt lgkmcnt(0)
	s_barrier
	s_setprio 2
	s_waitcnt lgkmcnt(0)
	v_mfma_f32_16x16x32_bf16 v[76:79], v[146:149], v[184:187], v[76:79]
	v_mfma_f32_16x16x32_bf16 v[72:75], v[160:163], v[184:187], v[72:75]
	v_mfma_f32_16x16x32_bf16 v[68:71], v[146:149], v[192:195], v[68:71]
	v_mfma_f32_16x16x32_bf16 v[64:67], v[160:163], v[192:195], v[64:67]
	v_mfma_f32_16x16x32_bf16 v[56:59], v[146:149], v[200:203], v[56:59]
	v_mfma_f32_16x16x32_bf16 v[52:55], v[160:163], v[200:203], v[52:55]
	v_mfma_f32_16x16x32_bf16 v[44:47], v[146:149], v[208:211], v[44:47]
	v_mfma_f32_16x16x32_bf16 v[40:43], v[160:163], v[208:211], v[40:43]
	v_mfma_f32_16x16x32_bf16 v[76:79], v[156:159], v[188:191], v[76:79]
	v_mfma_f32_16x16x32_bf16 v[72:75], v[164:167], v[188:191], v[72:75]
	v_mfma_f32_16x16x32_bf16 v[68:71], v[156:159], v[196:199], v[68:71]
	v_mfma_f32_16x16x32_bf16 v[64:67], v[164:167], v[196:199], v[64:67]
	v_mfma_f32_16x16x32_bf16 v[56:59], v[156:159], v[204:207], v[56:59]
	v_mfma_f32_16x16x32_bf16 v[52:55], v[164:167], v[204:207], v[52:55]
	v_mfma_f32_16x16x32_bf16 v[44:47], v[156:159], v[212:215], v[44:47]
	v_mfma_f32_16x16x32_bf16 v[40:43], v[164:167], v[212:215], v[40:43]
	s_setprio 0
	s_setprio 2
	v_mfma_f32_16x16x32_bf16 v[124:127], v[168:171], v[184:187], v[124:127]
	v_mfma_f32_16x16x32_bf16 v[120:123], v[176:179], v[184:187], v[120:123]
	v_mfma_f32_16x16x32_bf16 v[116:119], v[168:171], v[192:195], v[116:119]
	v_mfma_f32_16x16x32_bf16 v[112:115], v[176:179], v[192:195], v[112:115]
	v_mfma_f32_16x16x32_bf16 v[108:111], v[168:171], v[200:203], v[108:111]
	v_mfma_f32_16x16x32_bf16 v[104:107], v[176:179], v[200:203], v[104:107]
	v_mfma_f32_16x16x32_bf16 v[100:103], v[168:171], v[208:211], v[100:103]
	v_mfma_f32_16x16x32_bf16 v[96:99], v[176:179], v[208:211], v[96:99]
	v_mfma_f32_16x16x32_bf16 v[124:127], v[172:175], v[188:191], v[124:127]
	v_mfma_f32_16x16x32_bf16 v[120:123], v[180:183], v[188:191], v[120:123]
	v_mfma_f32_16x16x32_bf16 v[116:119], v[172:175], v[196:199], v[116:119]
	v_mfma_f32_16x16x32_bf16 v[112:115], v[180:183], v[196:199], v[112:115]
	v_mfma_f32_16x16x32_bf16 v[108:111], v[172:175], v[204:207], v[108:111]
	v_mfma_f32_16x16x32_bf16 v[104:107], v[180:183], v[204:207], v[104:107]
	v_mfma_f32_16x16x32_bf16 v[100:103], v[172:175], v[212:215], v[100:103]
	s_setprio 3
	s_barrier
	v_mfma_f32_16x16x32_bf16 v[96:99], v[180:183], v[212:215], v[96:99]
	s_setprio 0
	s_add_i32 s90, s77, s67
	v_lshl_add_u64 v[216:217], s[60:61], 0, v[130:131]
	s_mov_b32 m0, s90
	ds_read_b128 v[184:187], v154 offset:16384
	ds_read_b128 v[188:191], v154 offset:17408
	ds_read_b128 v[192:195], v154 offset:18432
	ds_read_b128 v[196:199], v154 offset:19456
	ds_read_b128 v[200:203], v154 offset:20480
	ds_read_b128 v[204:207], v154 offset:21504
	ds_read_b128 v[208:211], v154 offset:22528
	ds_read_b128 v[212:215], v154 offset:23552
	global_load_lds_dwordx4 v[216:217], off
	s_add_i32 m0, s90, 0x2000
	s_add_u32 s90, s60, 0x40000
	v_lshl_add_u64 v[218:219], s[60:61], 0, v[134:135]
	s_addc_u32 s91, s61, 0
	s_add_i32 s92, s78, s67
	global_load_lds_dwordx4 v[218:219], off
	v_lshl_add_u64 v[220:221], s[90:91], 0, v[130:131]
	s_mov_b32 m0, s92
	v_lshl_add_u64 v[222:223], s[62:63], 0, v[132:133]
	global_load_lds_dwordx4 v[220:221], off
	v_lshl_add_u64 v[220:221], s[90:91], 0, v[134:135]
	s_add_i32 m0, s92, 0x2000
	s_nop 0
	global_load_lds_dwordx4 v[220:221], off
	v_lshl_add_u64 v[220:221], s[62:63], 0, v[128:129]
	s_mov_b32 m0, s68
	s_nop 0
	global_load_lds_dwordx4 v[220:221], off
	s_mov_b32 m0, s69
	s_nop 0
	global_load_lds_dwordx4 v[222:223], off
	s_waitcnt vmcnt(8)
	s_waitcnt lgkmcnt(0)
	s_barrier
; #define PG8_STAGE(bufoff, gbase, voff) do { _Pragma("unroll") for (int _i = 0; _i < 2; ++_i) \
;         __builtin_amdgcn_global_load_lds((const unsigned*)((const char*)(gbase) + (voff)[_i]), (PG8_LAS unsigned*)(lds + (bufoff) + ldsw + _i * 8192), 16, 0, 0); } while (0)
; #define PG8_LDA(dst, b, h) do { _Pragma("unroll") for (int m = 0; m < 4; ++m) _Pragma("unroll") for (int k = 0; k < 2; ++k) dst[m][k] = *(const PG8_LAS bf16x8*)(lds + PG8_SA(b, h) + aoff + m * 2048 + k * 1024); } while (0)
; #define PG8_LDB(dst, b, h) do { _Pragma("unroll") for (int n = 0; n < 2; ++n) _Pragma("unroll") for (int k = 0; k < 2; ++k) dst[n][k] = *(const PG8_LAS bf16x8*)(lds + PG8_SB(b, h) + boff + n * 2048 + k * 1024); } while (0)
; #define PG8_MMA(ai, bj, At, Bt) do { __builtin_amdgcn_s_setprio(1); _Pragma("unroll") for (int m = 0; m < 4; ++m) _Pragma("unroll") for (int n = 0; n < 2; ++n) _Pragma("unroll") for (int k = 0; k < 2; ++k) \
;         acc[ai][bj][m][n] = __builtin_amdgcn_mfma_f32_16x16x32_bf16(Bt[n][k], At[m][k], acc[ai][bj][m][n], 0, 0, 0); __builtin_amdgcn_s_setprio(0); } while (0)
; #define PG8_WAIT_V(n) asm volatile("s_waitcnt vmcnt(" #n ")" ::: "memory")
; #define PG8_WAIT_L(n) asm volatile("s_waitcnt lgkmcnt(" #n ")" ::: "memory")
; #define PG8_BAR __builtin_amdgcn_s_barrier()
; #define PG8_SCHED __builtin_amdgcn_sched_barrier(0)
; template <class Epi, class Sched, bool ALIGN_EPI = false, bool SP2 = false>
; __device__ __forceinline__ void gemm_phase(PG8_LAS unsigned char* lds, const Gemm g, const Sched& S, const Epi& E, const int wv  ) {
;     ...
;             PG8_WAIT_V(8); PG8_WAIT_L(0); PG8_BAR; PG8_MMA(1, 0, At, B0); PG8_MMA(1, 1, At, B1); PG8_BAR; PG8_SCHED;
;             PG8_LDB(B0, 1, 0); PG8_LDB(B1, 1, 1); PG8_SCHED; PG8_LDA(At, 1, 0); PG8_STAGE(PG8_SA(0, 1), a2 + hstepA, voffA);
;             PG8_WAIT_V(8); PG8_WAIT_L(0); PG8_BAR; PG8_MMA(0, 0, At, B0); PG8_MMA(0, 1, At, B1); PG8_BAR; PG8_SCHED;
	s_setprio 2
	s_waitcnt lgkmcnt(0)
	v_mfma_f32_16x16x32_bf16 v[28:31], v[146:149], v[184:187], v[28:31]
	v_mfma_f32_16x16x32_bf16 v[24:27], v[160:163], v[184:187], v[24:27]
	v_mfma_f32_16x16x32_bf16 v[20:23], v[146:149], v[192:195], v[20:23]
	v_mfma_f32_16x16x32_bf16 v[16:19], v[160:163], v[192:195], v[16:19]
	v_mfma_f32_16x16x32_bf16 v[12:15], v[146:149], v[200:203], v[12:15]
	v_mfma_f32_16x16x32_bf16 v[8:11], v[160:163], v[200:203], v[8:11]
	v_mfma_f32_16x16x32_bf16 v[4:7], v[146:149], v[208:211], v[4:7]
	v_mfma_f32_16x16x32_bf16 v[0:3], v[160:163], v[208:211], v[0:3]
	v_mfma_f32_16x16x32_bf16 v[28:31], v[156:159], v[188:191], v[28:31]
	v_mfma_f32_16x16x32_bf16 v[24:27], v[164:167], v[188:191], v[24:27]
	v_mfma_f32_16x16x32_bf16 v[20:23], v[156:159], v[196:199], v[20:23]
	v_mfma_f32_16x16x32_bf16 v[16:19], v[164:167], v[196:199], v[16:19]
	v_mfma_f32_16x16x32_bf16 v[12:15], v[156:159], v[204:207], v[12:15]
	v_mfma_f32_16x16x32_bf16 v[8:11], v[164:167], v[204:207], v[8:11]
	v_mfma_f32_16x16x32_bf16 v[4:7], v[156:159], v[212:215], v[4:7]
	v_mfma_f32_16x16x32_bf16 v[0:3], v[164:167], v[212:215], v[0:3]
	s_setprio 0
	s_setprio 2
	v_mfma_f32_16x16x32_bf16 v[92:95], v[168:171], v[184:187], v[92:95]
	v_mfma_f32_16x16x32_bf16 v[88:91], v[176:179], v[184:187], v[88:91]
	v_mfma_f32_16x16x32_bf16 v[84:87], v[168:171], v[192:195], v[84:87]
	v_mfma_f32_16x16x32_bf16 v[80:83], v[176:179], v[192:195], v[80:83]
	v_mfma_f32_16x16x32_bf16 v[60:63], v[168:171], v[200:203], v[60:63]
	v_mfma_f32_16x16x32_bf16 v[48:51], v[176:179], v[200:203], v[48:51]
	v_mfma_f32_16x16x32_bf16 v[36:39], v[168:171], v[208:211], v[36:39]
	v_mfma_f32_16x16x32_bf16 v[32:35], v[176:179], v[208:211], v[32:35]
	v_mfma_f32_16x16x32_bf16 v[92:95], v[172:175], v[188:191], v[92:95]
	v_mfma_f32_16x16x32_bf16 v[88:91], v[180:183], v[188:191], v[88:91]
	v_mfma_f32_16x16x32_bf16 v[84:87], v[172:175], v[196:199], v[84:87]
	v_mfma_f32_16x16x32_bf16 v[80:83], v[180:183], v[196:199], v[80:83]
	v_mfma_f32_16x16x32_bf16 v[60:63], v[172:175], v[204:207], v[60:63]
	v_mfma_f32_16x16x32_bf16 v[48:51], v[180:183], v[204:207], v[48:51]
	v_mfma_f32_16x16x32_bf16 v[36:39], v[172:175], v[212:215], v[36:39]
	s_setprio 3
	s_barrier
	v_mfma_f32_16x16x32_bf16 v[32:35], v[180:183], v[212:215], v[32:35]
	s_setprio 0
	s_add_i32 s90, 0, 0x18000
	v_add_u32_e32 v155, s90, v150
	s_add_i32 s91, 0, 0x1c000
	ds_read_b128 v[146:149], v155
	ds_read_b128 v[156:159], v155 offset:1024
	ds_read_b128 v[160:163], v155 offset:2048
	ds_read_b128 v[164:167], v155 offset:3072
	v_add_u32_e32 v155, s91, v150
	ds_read_b128 v[168:171], v155
	ds_read_b128 v[172:175], v155 offset:1024
	ds_read_b128 v[176:179], v155 offset:2048
	ds_read_b128 v[180:183], v155 offset:3072
	s_add_u32 s62, s62, 0x40000
	s_addc_u32 s63, s63, 0
	s_mov_b32 m0, s70
	v_lshl_add_u64 v[224:225], s[62:63], 0, v[128:129]
	ds_read_b128 v[184:187], v154 offset:32768
	ds_read_b128 v[188:191], v154 offset:33792
	ds_read_b128 v[192:195], v154 offset:34816
	ds_read_b128 v[196:199], v154 offset:35840
	ds_read_b128 v[200:203], v154 offset:36864
	ds_read_b128 v[204:207], v154 offset:37888
	ds_read_b128 v[208:211], v154 offset:38912
	ds_read_b128 v[212:215], v154 offset:39936
	global_load_lds_dwordx4 v[224:225], off
	v_lshl_add_u64 v[224:225], s[62:63], 0, v[132:133]
	s_mov_b32 m0, s71
	s_nop 0
	global_load_lds_dwordx4 v[224:225], off
	s_waitcnt vmcnt(8)
	s_waitcnt lgkmcnt(0)
	s_barrier
	s_setprio 2
	s_waitcnt lgkmcnt(0)
	v_mfma_f32_16x16x32_bf16 v[76:79], v[146:149], v[184:187], v[76:79]
	v_mfma_f32_16x16x32_bf16 v[72:75], v[160:163], v[184:187], v[72:75]
	v_mfma_f32_16x16x32_bf16 v[68:71], v[146:149], v[192:195], v[68:71]
	v_mfma_f32_16x16x32_bf16 v[64:67], v[160:163], v[192:195], v[64:67]
	v_mfma_f32_16x16x32_bf16 v[56:59], v[146:149], v[200:203], v[56:59]
	v_mfma_f32_16x16x32_bf16 v[52:55], v[160:163], v[200:203], v[52:55]
	v_mfma_f32_16x16x32_bf16 v[44:47], v[146:149], v[208:211], v[44:47]
	v_mfma_f32_16x16x32_bf16 v[40:43], v[160:163], v[208:211], v[40:43]
	v_mfma_f32_16x16x32_bf16 v[76:79], v[156:159], v[188:191], v[76:79]
	v_mfma_f32_16x16x32_bf16 v[72:75], v[164:167], v[188:191], v[72:75]
	v_mfma_f32_16x16x32_bf16 v[68:71], v[156:159], v[196:199], v[68:71]
	v_mfma_f32_16x16x32_bf16 v[64:67], v[164:167], v[196:199], v[64:67]
	v_mfma_f32_16x16x32_bf16 v[56:59], v[156:159], v[204:207], v[56:59]
	v_mfma_f32_16x16x32_bf16 v[52:55], v[164:167], v[204:207], v[52:55]
	v_mfma_f32_16x16x32_bf16 v[44:47], v[156:159], v[212:215], v[44:47]
	v_mfma_f32_16x16x32_bf16 v[40:43], v[164:167], v[212:215], v[40:43]
	s_setprio 0
	s_setprio 2
	v_mfma_f32_16x16x32_bf16 v[124:127], v[168:171], v[184:187], v[124:127]
	v_mfma_f32_16x16x32_bf16 v[120:123], v[176:179], v[184:187], v[120:123]
	v_mfma_f32_16x16x32_bf16 v[116:119], v[168:171], v[192:195], v[116:119]
	v_mfma_f32_16x16x32_bf16 v[112:115], v[176:179], v[192:195], v[112:115]
	v_mfma_f32_16x16x32_bf16 v[108:111], v[168:171], v[200:203], v[108:111]
	v_mfma_f32_16x16x32_bf16 v[104:107], v[176:179], v[200:203], v[104:107]
	v_mfma_f32_16x16x32_bf16 v[100:103], v[168:171], v[208:211], v[100:103]
	v_mfma_f32_16x16x32_bf16 v[96:99], v[176:179], v[208:211], v[96:99]
	v_mfma_f32_16x16x32_bf16 v[124:127], v[172:175], v[188:191], v[124:127]
	v_mfma_f32_16x16x32_bf16 v[120:123], v[180:183], v[188:191], v[120:123]
	v_mfma_f32_16x16x32_bf16 v[116:119], v[172:175], v[196:199], v[116:119]
	v_mfma_f32_16x16x32_bf16 v[112:115], v[180:183], v[196:199], v[112:115]
	v_mfma_f32_16x16x32_bf16 v[108:111], v[172:175], v[204:207], v[108:111]
	v_mfma_f32_16x16x32_bf16 v[104:107], v[180:183], v[204:207], v[104:107]
	v_mfma_f32_16x16x32_bf16 v[100:103], v[172:175], v[212:215], v[100:103]
	s_setprio 3
	s_barrier
; #define PG8_STAGE(bufoff, gbase, voff) do { _Pragma("unroll") for (int _i = 0; _i < 2; ++_i) \
;         __builtin_amdgcn_global_load_lds((const unsigned*)((const char*)(gbase) + (voff)[_i]), (PG8_LAS unsigned*)(lds + (bufoff) + ldsw + _i * 8192), 16, 0, 0); } while (0)
; #define PG8_LDA(dst, b, h) do { _Pragma("unroll") for (int m = 0; m < 4; ++m) _Pragma("unroll") for (int k = 0; k < 2; ++k) dst[m][k] = *(const PG8_LAS bf16x8*)(lds + PG8_SA(b, h) + aoff + m * 2048 + k * 1024); } while (0)
; #define PG8_MMA(ai, bj, At, Bt) do { __builtin_amdgcn_s_setprio(1); _Pragma("unroll") for (int m = 0; m < 4; ++m) _Pragma("unroll") for (int n = 0; n < 2; ++n) _Pragma("unroll") for (int k = 0; k < 2; ++k) \
;         acc[ai][bj][m][n] = __builtin_amdgcn_mfma_f32_16x16x32_bf16(Bt[n][k], At[m][k], acc[ai][bj][m][n], 0, 0, 0); __builtin_amdgcn_s_setprio(0); } while (0)
; #define PG8_WAIT_V(n) asm volatile("s_waitcnt vmcnt(" #n ")" ::: "memory")
; #define PG8_WAIT_L(n) asm volatile("s_waitcnt lgkmcnt(" #n ")" ::: "memory")
; #define PG8_BAR __builtin_amdgcn_s_barrier()
; #define PG8_SCHED __builtin_amdgcn_sched_barrier(0)
; template <class Epi, class Sched, bool ALIGN_EPI = false, bool SP2 = false>
; __device__ __forceinline__ void gemm_phase(PG8_LAS unsigned char* lds, const Gemm g, const Sched& S, const Epi& E, const int wv  ) {
;     ...
;             PG8_LDA(At, 1, 1); PG8_STAGE(PG8_SB(1, 0), b3, voffB); PG8_STAGE(PG8_SB(1, 1), b3 + hstepB, voffB); PG8_STAGE(PG8_SA(1, 0), a3, voffA);
;             PG8_WAIT_V(8); PG8_WAIT_L(0); PG8_BAR; PG8_MMA(1, 0, At, B0); PG8_MMA(1, 1, At, B1); PG8_BAR; PG8_SCHED;
;     ...
;         if constexpr (ALIGN_EPI) { if (wr == 0) PG8_BAR; }
	v_mfma_f32_16x16x32_bf16 v[96:99], v[180:183], v[212:215], v[96:99]
	s_setprio 0
	s_add_i32 s62, s90, s67
	v_lshl_add_u64 v[216:217], v[216:217], 0, s[10:11]
	s_mov_b32 m0, s62
	ds_read_b128 v[184:187], v154 offset:49152
	ds_read_b128 v[188:191], v154 offset:50176
	ds_read_b128 v[192:195], v154 offset:51200
	ds_read_b128 v[196:199], v154 offset:52224
	ds_read_b128 v[200:203], v154 offset:53248
	ds_read_b128 v[204:207], v154 offset:54272
	ds_read_b128 v[208:211], v154 offset:55296
	ds_read_b128 v[212:215], v154 offset:56320
	global_load_lds_dwordx4 v[216:217], off
	s_add_i32 m0, s62, 0x2000
	s_add_u32 s60, s60, 0x40080
	v_lshl_add_u64 v[216:217], v[218:219], 0, s[10:11]
	s_addc_u32 s61, s61, 0
	s_add_i32 s62, s91, s67
	global_load_lds_dwordx4 v[216:217], off
	v_lshl_add_u64 v[216:217], s[60:61], 0, v[130:131]
	s_mov_b32 m0, s62
	s_nop 0
	global_load_lds_dwordx4 v[216:217], off
	v_lshl_add_u64 v[216:217], s[60:61], 0, v[134:135]
	s_add_i32 m0, s62, 0x2000
	s_nop 0
	global_load_lds_dwordx4 v[216:217], off
	v_lshl_add_u64 v[216:217], v[220:221], 0, s[10:11]
	s_mov_b32 m0, s74
	s_nop 0
	global_load_lds_dwordx4 v[216:217], off
	v_lshl_add_u64 v[216:217], v[222:223], 0, s[10:11]
	s_mov_b32 m0, s75
	s_nop 0
	global_load_lds_dwordx4 v[216:217], off
	s_waitcnt vmcnt(8)
	s_waitcnt lgkmcnt(0)
	s_barrier
	s_setprio 2
	s_waitcnt lgkmcnt(0)
	v_mfma_f32_16x16x32_bf16 v[28:31], v[146:149], v[184:187], v[28:31]
	v_mfma_f32_16x16x32_bf16 v[24:27], v[160:163], v[184:187], v[24:27]
	v_mfma_f32_16x16x32_bf16 v[20:23], v[146:149], v[192:195], v[20:23]
	v_mfma_f32_16x16x32_bf16 v[16:19], v[160:163], v[192:195], v[16:19]
	v_mfma_f32_16x16x32_bf16 v[12:15], v[146:149], v[200:203], v[12:15]
	v_mfma_f32_16x16x32_bf16 v[8:11], v[160:163], v[200:203], v[8:11]
	v_mfma_f32_16x16x32_bf16 v[4:7], v[146:149], v[208:211], v[4:7]
	v_mfma_f32_16x16x32_bf16 v[0:3], v[160:163], v[208:211], v[0:3]
	v_mfma_f32_16x16x32_bf16 v[28:31], v[156:159], v[188:191], v[28:31]
	v_mfma_f32_16x16x32_bf16 v[24:27], v[164:167], v[188:191], v[24:27]
	v_mfma_f32_16x16x32_bf16 v[20:23], v[156:159], v[196:199], v[20:23]
	v_mfma_f32_16x16x32_bf16 v[16:19], v[164:167], v[196:199], v[16:19]
	v_mfma_f32_16x16x32_bf16 v[12:15], v[156:159], v[204:207], v[12:15]
	v_mfma_f32_16x16x32_bf16 v[8:11], v[164:167], v[204:207], v[8:11]
	v_mfma_f32_16x16x32_bf16 v[4:7], v[156:159], v[212:215], v[4:7]
	v_mfma_f32_16x16x32_bf16 v[0:3], v[164:167], v[212:215], v[0:3]
	s_setprio 0
	s_setprio 2
	v_mfma_f32_16x16x32_bf16 v[92:95], v[168:171], v[184:187], v[92:95]
	v_mfma_f32_16x16x32_bf16 v[88:91], v[176:179], v[184:187], v[88:91]
	v_mfma_f32_16x16x32_bf16 v[84:87], v[168:171], v[192:195], v[84:87]
	v_mfma_f32_16x16x32_bf16 v[80:83], v[176:179], v[192:195], v[80:83]
	v_mfma_f32_16x16x32_bf16 v[60:63], v[168:171], v[200:203], v[60:63]
	v_mfma_f32_16x16x32_bf16 v[48:51], v[176:179], v[200:203], v[48:51]
	v_mfma_f32_16x16x32_bf16 v[36:39], v[168:171], v[208:211], v[36:39]
	v_mfma_f32_16x16x32_bf16 v[32:35], v[176:179], v[208:211], v[32:35]
	v_mfma_f32_16x16x32_bf16 v[92:95], v[172:175], v[188:191], v[92:95]
	v_mfma_f32_16x16x32_bf16 v[88:91], v[180:183], v[188:191], v[88:91]
	v_mfma_f32_16x16x32_bf16 v[84:87], v[172:175], v[196:199], v[84:87]
	v_mfma_f32_16x16x32_bf16 v[80:83], v[180:183], v[196:199], v[80:83]
	v_mfma_f32_16x16x32_bf16 v[60:63], v[172:175], v[204:207], v[60:63]
	v_mfma_f32_16x16x32_bf16 v[48:51], v[180:183], v[204:207], v[48:51]
	v_mfma_f32_16x16x32_bf16 v[36:39], v[172:175], v[212:215], v[36:39]
	s_setprio 3
	s_barrier
	v_mfma_f32_16x16x32_bf16 v[32:35], v[180:183], v[212:215], v[32:35]
	s_setprio 0
	s_add_i32 s87, s87, 2
	s_add_u32 s58, s58, 0x100
	s_addc_u32 s59, s59, 0
	s_add_u32 s85, s85, 0x100
	s_addc_u32 s86, s86, 0
	s_cmp_gt_u32 s87, 13
	s_cbranch_scc0 .LBB0_1049
	s_and_b64 vcc, exec, s[12:13]
	s_cbranch_vccz .LBB0_1052
	s_barrier

; #define PG8_STAGE(bufoff, gbase, voff) do { _Pragma("unroll") for (int _i = 0; _i < 2; ++_i) \
;         __builtin_amdgcn_global_load_lds((const unsigned*)((const char*)(gbase) + (voff)[_i]), (PG8_LAS unsigned*)(lds + (bufoff) + ldsw + _i * 8192), 16, 0, 0); } while (0)
; #define PG8_LDA(dst, b, h) do { _Pragma("unroll") for (int m = 0; m < 4; ++m) _Pragma("unroll") for (int k = 0; k < 2; ++k) dst[m][k] = *(const PG8_LAS bf16x8*)(lds + PG8_SA(b, h) + aoff + m * 2048 + k * 1024); } while (0)
; #define PG8_LDB(dst, b, h) do { _Pragma("unroll") for (int n = 0; n < 2; ++n) _Pragma("unroll") for (int k = 0; k < 2; ++k) dst[n][k] = *(const PG8_LAS bf16x8*)(lds + PG8_SB(b, h) + boff + n * 2048 + k * 1024); } while (0)
; #define PG8_MMA(ai, bj, At, Bt) do { __builtin_amdgcn_s_setprio(1); _Pragma("unroll") for (int m = 0; m < 4; ++m) _Pragma("unroll") for (int n = 0; n < 2; ++n) _Pragma("unroll") for (int k = 0; k < 2; ++k) \
;         acc[ai][bj][m][n] = __builtin_amdgcn_mfma_f32_16x16x32_bf16(Bt[n][k], At[m][k], acc[ai][bj][m][n], 0, 0, 0); __builtin_amdgcn_s_setprio(0); } while (0)
; #define PG8_WAIT_V(n) asm volatile("s_waitcnt vmcnt(" #n ")" ::: "memory")
; #define PG8_WAIT_L(n) asm volatile("s_waitcnt lgkmcnt(" #n ")" ::: "memory")
; #define PG8_BAR __builtin_amdgcn_s_barrier()
; #define PG8_SCHED __builtin_amdgcn_sched_barrier(0)
; template <class Epi, class Sched, bool ALIGN_EPI = false, bool SP2 = false>
; __device__ __forceinline__ void gemm_phase(PG8_LAS unsigned char* lds, const Gemm g, const Sched& S, const Epi& E, const int wv  ) {
;     ...
;             const bool last = (t == nt - 2);
;             const char* a1 = cA + (size_t)(t + 1) * kstep;
;             const char* a2 = last ? nA : cA + (size_t)(t + 2) * kstep; const char* b2 = last ? nB : cB + (size_t)(t + 2) * kstep;
;             const char* a3 = a2 + kstep; const char* b3 = b2 + kstep;
;             if (last && has_next) S.a_ready(nxt);
;             if constexpr (SP2) {
;             PG8_LDB(B0, 0, 0); PG8_LDB(B1, 0, 1); PG8_SCHED; PG8_LDA(At, 0, 0); PG8_STAGE(PG8_SA(1, 1), a1 + hstepA, voffA);
;             PG8_WAIT_V(8); PG8_WAIT_L(0); PG8_BAR; PG8_MMA(0, 0, At, B0); PG8_MMA(0, 1, At, B1); PG8_BAR; PG8_SCHED;
;             PG8_LDA(At, 0, 1); PG8_STAGE(PG8_SB(0, 0), b2, voffB); PG8_STAGE(PG8_SB(0, 1), b2 + hstepB, voffB); PG8_STAGE(PG8_SA(0, 0), a2, voffA);
.LBB0_1187:
	ds_read_b128 v[44:47], v196
	ds_read_b128 v[48:51], v196 offset:1024
	ds_read_b128 v[52:55], v196 offset:2048
	ds_read_b128 v[56:59], v196 offset:3072
	ds_read_b128 v[60:63], v197
	ds_read_b128 v[68:71], v197 offset:1024
	ds_read_b128 v[72:75], v197 offset:2048
	ds_read_b128 v[76:79], v197 offset:3072
	s_add_u32 s68, s66, 0xfff00080
	s_addc_u32 s69, s67, -1
	s_cmp_eq_u32 s94, 60
	s_cselect_b32 s71, s57, s69
	s_cselect_b32 s70, s63, s68
	s_cselect_b32 s69, s55, s93
	s_cselect_b32 s68, s65, s92
	v_lshl_add_u64 v[224:225], s[66:67], 0, v[172:173]
	s_add_i32 m0, s75, 0xc000
	ds_read_b128 v[180:183], v198
	ds_read_b128 v[184:187], v198 offset:1024
	ds_read_b128 v[200:203], v198 offset:2048
	ds_read_b128 v[204:207], v198 offset:3072
	ds_read_b128 v[208:211], v198 offset:4096
	ds_read_b128 v[212:215], v198 offset:5120
	ds_read_b128 v[216:219], v198 offset:6144
	ds_read_b128 v[220:223], v198 offset:7168
	global_load_lds_dwordx4 v[224:225], off
	v_lshl_add_u64 v[224:225], s[66:67], 0, v[174:175]
	s_add_i32 m0, s75, 0xe000
	s_nop 0
	global_load_lds_dwordx4 v[224:225], off
	s_waitcnt vmcnt(8)
	s_waitcnt lgkmcnt(0)
	s_barrier
	s_setprio 2
	s_waitcnt lgkmcnt(0)
	v_mfma_f32_16x16x32_bf16 v[104:107], v[44:47], v[180:183], v[104:107]
	v_mfma_f32_16x16x32_bf16 v[100:103], v[52:55], v[180:183], v[100:103]
	v_mfma_f32_16x16x32_bf16 v[156:159], v[44:47], v[200:203], v[156:159]
	v_mfma_f32_16x16x32_bf16 v[148:151], v[52:55], v[200:203], v[148:151]
	v_mfma_f32_16x16x32_bf16 v[140:143], v[44:47], v[208:211], v[140:143]
	v_mfma_f32_16x16x32_bf16 v[132:135], v[52:55], v[208:211], v[132:135]
	v_mfma_f32_16x16x32_bf16 v[124:127], v[44:47], v[216:219], v[124:127]
	v_mfma_f32_16x16x32_bf16 v[120:123], v[52:55], v[216:219], v[120:123]
	v_mfma_f32_16x16x32_bf16 v[104:107], v[48:51], v[184:187], v[104:107]
	v_mfma_f32_16x16x32_bf16 v[100:103], v[56:59], v[184:187], v[100:103]
	v_mfma_f32_16x16x32_bf16 v[156:159], v[48:51], v[204:207], v[156:159]
	v_mfma_f32_16x16x32_bf16 v[148:151], v[56:59], v[204:207], v[148:151]
	v_mfma_f32_16x16x32_bf16 v[140:143], v[48:51], v[212:215], v[140:143]
	v_mfma_f32_16x16x32_bf16 v[132:135], v[56:59], v[212:215], v[132:135]
	v_mfma_f32_16x16x32_bf16 v[124:127], v[48:51], v[220:223], v[124:127]
	v_mfma_f32_16x16x32_bf16 v[120:123], v[56:59], v[220:223], v[120:123]
	s_setprio 0
	s_setprio 2
	v_mfma_f32_16x16x32_bf16 v[92:95], v[60:63], v[180:183], v[92:95]
	v_mfma_f32_16x16x32_bf16 v[88:91], v[72:75], v[180:183], v[88:91]
	v_mfma_f32_16x16x32_bf16 v[152:155], v[60:63], v[200:203], v[152:155]
	v_mfma_f32_16x16x32_bf16 v[144:147], v[72:75], v[200:203], v[144:147]
	v_mfma_f32_16x16x32_bf16 v[136:139], v[60:63], v[208:211], v[136:139]
	v_mfma_f32_16x16x32_bf16 v[128:131], v[72:75], v[208:211], v[128:131]
	v_mfma_f32_16x16x32_bf16 v[116:119], v[60:63], v[216:219], v[116:119]
	v_mfma_f32_16x16x32_bf16 v[112:115], v[72:75], v[216:219], v[112:115]
	v_mfma_f32_16x16x32_bf16 v[92:95], v[68:71], v[184:187], v[92:95]
	v_mfma_f32_16x16x32_bf16 v[88:91], v[76:79], v[184:187], v[88:91]
	v_mfma_f32_16x16x32_bf16 v[152:155], v[68:71], v[204:207], v[152:155]
	v_mfma_f32_16x16x32_bf16 v[144:147], v[76:79], v[204:207], v[144:147]
	v_mfma_f32_16x16x32_bf16 v[136:139], v[68:71], v[212:215], v[136:139]
	v_mfma_f32_16x16x32_bf16 v[128:131], v[76:79], v[212:215], v[128:131]
	v_mfma_f32_16x16x32_bf16 v[116:119], v[68:71], v[220:223], v[116:119]
	s_setprio 3
	s_barrier
	v_mfma_f32_16x16x32_bf16 v[112:115], v[76:79], v[220:223], v[112:115]
	s_setprio 0
	s_add_i32 s95, s87, s74
	v_lshl_add_u64 v[228:229], s[68:69], 0, v[162:163]
	s_mov_b32 m0, s95
	ds_read_b128 v[180:183], v198 offset:16384
	ds_read_b128 v[184:187], v198 offset:17408
	ds_read_b128 v[200:203], v198 offset:18432
	ds_read_b128 v[204:207], v198 offset:19456
	ds_read_b128 v[208:211], v198 offset:20480
	ds_read_b128 v[212:215], v198 offset:21504
	ds_read_b128 v[216:219], v198 offset:22528
	ds_read_b128 v[220:223], v198 offset:23552
	global_load_lds_dwordx4 v[228:229], off
	s_add_i32 m0, s95, 0x2000
	s_add_u32 s96, s68, 0x100000
	v_lshl_add_u64 v[230:231], s[68:69], 0, v[166:167]
	s_addc_u32 s97, s69, 0
	s_add_i32 s95, s90, s74
	global_load_lds_dwordx4 v[230:231], off
	v_lshl_add_u64 v[224:225], s[96:97], 0, v[162:163]
	s_mov_b32 m0, s95
	v_lshl_add_u64 v[232:233], s[70:71], 0, v[160:161]
	global_load_lds_dwordx4 v[224:225], off
	v_lshl_add_u64 v[224:225], s[96:97], 0, v[166:167]
	s_add_i32 m0, s95, 0x2000
	v_lshl_add_u64 v[234:235], s[70:71], 0, v[164:165]
	global_load_lds_dwordx4 v[224:225], off
	s_mov_b32 m0, s75
	s_nop 0
	global_load_lds_dwordx4 v[232:233], off
	s_mov_b32 m0, s76
	s_nop 0
	global_load_lds_dwordx4 v[234:235], off
	s_waitcnt vmcnt(8)
	s_waitcnt lgkmcnt(0)
	s_barrier
; #define PG8_STAGE(bufoff, gbase, voff) do { _Pragma("unroll") for (int _i = 0; _i < 2; ++_i) \
;         __builtin_amdgcn_global_load_lds((const unsigned*)((const char*)(gbase) + (voff)[_i]), (PG8_LAS unsigned*)(lds + (bufoff) + ldsw + _i * 8192), 16, 0, 0); } while (0)
; #define PG8_LDA(dst, b, h) do { _Pragma("unroll") for (int m = 0; m < 4; ++m) _Pragma("unroll") for (int k = 0; k < 2; ++k) dst[m][k] = *(const PG8_LAS bf16x8*)(lds + PG8_SA(b, h) + aoff + m * 2048 + k * 1024); } while (0)
; #define PG8_LDB(dst, b, h) do { _Pragma("unroll") for (int n = 0; n < 2; ++n) _Pragma("unroll") for (int k = 0; k < 2; ++k) dst[n][k] = *(const PG8_LAS bf16x8*)(lds + PG8_SB(b, h) + boff + n * 2048 + k * 1024); } while (0)
; #define PG8_MMA(ai, bj, At, Bt) do { __builtin_amdgcn_s_setprio(1); _Pragma("unroll") for (int m = 0; m < 4; ++m) _Pragma("unroll") for (int n = 0; n < 2; ++n) _Pragma("unroll") for (int k = 0; k < 2; ++k) \
;         acc[ai][bj][m][n] = __builtin_amdgcn_mfma_f32_16x16x32_bf16(Bt[n][k], At[m][k], acc[ai][bj][m][n], 0, 0, 0); __builtin_amdgcn_s_setprio(0); } while (0)
; #define PG8_WAIT_V(n) asm volatile("s_waitcnt vmcnt(" #n ")" ::: "memory")
; #define PG8_WAIT_L(n) asm volatile("s_waitcnt lgkmcnt(" #n ")" ::: "memory")
; #define PG8_BAR __builtin_amdgcn_s_barrier()
; #define PG8_SCHED __builtin_amdgcn_sched_barrier(0)
; template <class Epi, class Sched, bool ALIGN_EPI = false, bool SP2 = false>
; __device__ __forceinline__ void gemm_phase(PG8_LAS unsigned char* lds, const Gemm g, const Sched& S, const Epi& E, const int wv  ) {
;     ...
;             PG8_WAIT_V(8); PG8_WAIT_L(0); PG8_BAR; PG8_MMA(1, 0, At, B0); PG8_MMA(1, 1, At, B1); PG8_BAR; PG8_SCHED;
;             PG8_LDB(B0, 1, 0); PG8_LDB(B1, 1, 1); PG8_SCHED; PG8_LDA(At, 1, 0); PG8_STAGE(PG8_SA(0, 1), a2 + hstepA, voffA);
;             PG8_WAIT_V(8); PG8_WAIT_L(0); PG8_BAR; PG8_MMA(0, 0, At, B0); PG8_MMA(0, 1, At, B1); PG8_BAR; PG8_SCHED;
	s_setprio 2
	s_waitcnt lgkmcnt(0)
	v_mfma_f32_16x16x32_bf16 v[108:111], v[44:47], v[180:183], v[108:111]
	v_mfma_f32_16x16x32_bf16 v[96:99], v[52:55], v[180:183], v[96:99]
	v_mfma_f32_16x16x32_bf16 v[64:67], v[44:47], v[200:203], v[64:67]
	v_mfma_f32_16x16x32_bf16 v[36:39], v[52:55], v[200:203], v[36:39]
	v_mfma_f32_16x16x32_bf16 v[28:31], v[44:47], v[208:211], v[28:31]
	v_mfma_f32_16x16x32_bf16 v[20:23], v[52:55], v[208:211], v[20:23]
	v_mfma_f32_16x16x32_bf16 v[12:15], v[44:47], v[216:219], v[12:15]
	v_mfma_f32_16x16x32_bf16 v[4:7], v[52:55], v[216:219], v[4:7]
	v_mfma_f32_16x16x32_bf16 v[108:111], v[48:51], v[184:187], v[108:111]
	v_mfma_f32_16x16x32_bf16 v[96:99], v[56:59], v[184:187], v[96:99]
	v_mfma_f32_16x16x32_bf16 v[64:67], v[48:51], v[204:207], v[64:67]
	v_mfma_f32_16x16x32_bf16 v[36:39], v[56:59], v[204:207], v[36:39]
	v_mfma_f32_16x16x32_bf16 v[28:31], v[48:51], v[212:215], v[28:31]
	v_mfma_f32_16x16x32_bf16 v[20:23], v[56:59], v[212:215], v[20:23]
	v_mfma_f32_16x16x32_bf16 v[12:15], v[48:51], v[220:223], v[12:15]
	v_mfma_f32_16x16x32_bf16 v[4:7], v[56:59], v[220:223], v[4:7]
	s_setprio 0
	s_setprio 2
	v_mfma_f32_16x16x32_bf16 v[40:43], v[60:63], v[200:203], v[40:43]
	v_mfma_f32_16x16x32_bf16 v[32:35], v[72:75], v[200:203], v[32:35]
	v_mfma_f32_16x16x32_bf16 v[24:27], v[60:63], v[208:211], v[24:27]
	v_mfma_f32_16x16x32_bf16 v[16:19], v[72:75], v[208:211], v[16:19]
	v_mfma_f32_16x16x32_bf16 v[8:11], v[60:63], v[216:219], v[8:11]
	v_mfma_f32_16x16x32_bf16 v[0:3], v[72:75], v[216:219], v[0:3]
	v_mfma_f32_16x16x32_bf16 v[44:47], v[60:63], v[180:183], v[84:87]
	v_mfma_f32_16x16x32_bf16 v[48:51], v[72:75], v[180:183], v[80:83]
	v_mfma_f32_16x16x32_bf16 v[40:43], v[68:71], v[204:207], v[40:43]
	v_mfma_f32_16x16x32_bf16 v[32:35], v[76:79], v[204:207], v[32:35]
	v_mfma_f32_16x16x32_bf16 v[24:27], v[68:71], v[212:215], v[24:27]
	v_mfma_f32_16x16x32_bf16 v[16:19], v[76:79], v[212:215], v[16:19]
	v_mfma_f32_16x16x32_bf16 v[8:11], v[68:71], v[220:223], v[8:11]
	v_mfma_f32_16x16x32_bf16 v[0:3], v[76:79], v[220:223], v[0:3]
	v_mfma_f32_16x16x32_bf16 v[44:47], v[68:71], v[184:187], v[44:47]
	s_setprio 3
	s_barrier
	v_mfma_f32_16x16x32_bf16 v[48:51], v[76:79], v[184:187], v[48:51]
	s_setprio 0
	s_add_i32 s95, 0, 0x18000
	s_add_i32 s96, 0, 0x1c000
	v_add_u32_e32 v68, s95, v190
	v_add_u32_e32 v80, s96, v190
	ds_read_b128 v[52:55], v68
	ds_read_b128 v[56:59], v68 offset:1024
	ds_read_b128 v[60:63], v68 offset:2048
	ds_read_b128 v[68:71], v68 offset:3072
	ds_read_b128 v[72:75], v80
	ds_read_b128 v[76:79], v80 offset:1024
	ds_read_b128 v[180:183], v80 offset:2048
	ds_read_b128 v[184:187], v80 offset:3072
	s_add_u32 s70, s70, 0x100000
	s_addc_u32 s71, s71, 0
	s_mov_b32 m0, s77
	v_lshl_add_u64 v[224:225], s[70:71], 0, v[160:161]
	ds_read_b128 v[80:83], v198 offset:32768
	ds_read_b128 v[84:87], v198 offset:33792
	ds_read_b128 v[200:203], v198 offset:34816
	ds_read_b128 v[204:207], v198 offset:35840
	ds_read_b128 v[208:211], v198 offset:36864
	ds_read_b128 v[212:215], v198 offset:37888
	ds_read_b128 v[216:219], v198 offset:38912
	ds_read_b128 v[220:223], v198 offset:39936
	global_load_lds_dwordx4 v[224:225], off
	v_lshl_add_u64 v[224:225], s[70:71], 0, v[164:165]
	s_mov_b32 m0, s78
	s_nop 0
	global_load_lds_dwordx4 v[224:225], off
	s_waitcnt vmcnt(8)
	s_waitcnt lgkmcnt(0)
	s_barrier
	s_setprio 2
	s_waitcnt lgkmcnt(0)
	v_mfma_f32_16x16x32_bf16 v[104:107], v[52:55], v[80:83], v[104:107]
	v_mfma_f32_16x16x32_bf16 v[100:103], v[60:63], v[80:83], v[100:103]
	v_mfma_f32_16x16x32_bf16 v[156:159], v[52:55], v[200:203], v[156:159]
	v_mfma_f32_16x16x32_bf16 v[148:151], v[60:63], v[200:203], v[148:151]
	v_mfma_f32_16x16x32_bf16 v[140:143], v[52:55], v[208:211], v[140:143]
	v_mfma_f32_16x16x32_bf16 v[132:135], v[60:63], v[208:211], v[132:135]
	v_mfma_f32_16x16x32_bf16 v[124:127], v[52:55], v[216:219], v[124:127]
	v_mfma_f32_16x16x32_bf16 v[120:123], v[60:63], v[216:219], v[120:123]
	v_mfma_f32_16x16x32_bf16 v[104:107], v[56:59], v[84:87], v[104:107]
	v_mfma_f32_16x16x32_bf16 v[100:103], v[68:71], v[84:87], v[100:103]
	v_mfma_f32_16x16x32_bf16 v[156:159], v[56:59], v[204:207], v[156:159]
	v_mfma_f32_16x16x32_bf16 v[148:151], v[68:71], v[204:207], v[148:151]
	v_mfma_f32_16x16x32_bf16 v[140:143], v[56:59], v[212:215], v[140:143]
	v_mfma_f32_16x16x32_bf16 v[132:135], v[68:71], v[212:215], v[132:135]
	v_mfma_f32_16x16x32_bf16 v[124:127], v[56:59], v[220:223], v[124:127]
	v_mfma_f32_16x16x32_bf16 v[120:123], v[68:71], v[220:223], v[120:123]
	s_setprio 0
	s_setprio 2
	v_mfma_f32_16x16x32_bf16 v[92:95], v[72:75], v[80:83], v[92:95]
	v_mfma_f32_16x16x32_bf16 v[80:83], v[180:183], v[80:83], v[88:91]
	v_mfma_f32_16x16x32_bf16 v[88:91], v[184:187], v[84:87], v[80:83]
	v_mfma_f32_16x16x32_bf16 v[80:83], v[72:75], v[200:203], v[152:155]
	v_mfma_f32_16x16x32_bf16 v[152:155], v[76:79], v[204:207], v[80:83]
	v_mfma_f32_16x16x32_bf16 v[80:83], v[180:183], v[200:203], v[144:147]
	v_mfma_f32_16x16x32_bf16 v[144:147], v[184:187], v[204:207], v[80:83]
	v_mfma_f32_16x16x32_bf16 v[80:83], v[72:75], v[208:211], v[136:139]
	v_mfma_f32_16x16x32_bf16 v[136:139], v[76:79], v[212:215], v[80:83]
	v_mfma_f32_16x16x32_bf16 v[80:83], v[180:183], v[208:211], v[128:131]
	v_mfma_f32_16x16x32_bf16 v[128:131], v[184:187], v[212:215], v[80:83]
	v_mfma_f32_16x16x32_bf16 v[80:83], v[72:75], v[216:219], v[116:119]
	v_mfma_f32_16x16x32_bf16 v[116:119], v[76:79], v[220:223], v[80:83]
	v_mfma_f32_16x16x32_bf16 v[80:83], v[180:183], v[216:219], v[112:115]
	v_mfma_f32_16x16x32_bf16 v[92:95], v[76:79], v[84:87], v[92:95]
	s_setprio 3
	s_barrier
; #define PG8_STAGE(bufoff, gbase, voff) do { _Pragma("unroll") for (int _i = 0; _i < 2; ++_i) \
;         __builtin_amdgcn_global_load_lds((const unsigned*)((const char*)(gbase) + (voff)[_i]), (PG8_LAS unsigned*)(lds + (bufoff) + ldsw + _i * 8192), 16, 0, 0); } while (0)
; #define PG8_LDA(dst, b, h) do { _Pragma("unroll") for (int m = 0; m < 4; ++m) _Pragma("unroll") for (int k = 0; k < 2; ++k) dst[m][k] = *(const PG8_LAS bf16x8*)(lds + PG8_SA(b, h) + aoff + m * 2048 + k * 1024); } while (0)
; #define PG8_MMA(ai, bj, At, Bt) do { __builtin_amdgcn_s_setprio(1); _Pragma("unroll") for (int m = 0; m < 4; ++m) _Pragma("unroll") for (int n = 0; n < 2; ++n) _Pragma("unroll") for (int k = 0; k < 2; ++k) \
;         acc[ai][bj][m][n] = __builtin_amdgcn_mfma_f32_16x16x32_bf16(Bt[n][k], At[m][k], acc[ai][bj][m][n], 0, 0, 0); __builtin_amdgcn_s_setprio(0); } while (0)
; #define PG8_WAIT_V(n) asm volatile("s_waitcnt vmcnt(" #n ")" ::: "memory")
; #define PG8_WAIT_L(n) asm volatile("s_waitcnt lgkmcnt(" #n ")" ::: "memory")
; #define PG8_BAR __builtin_amdgcn_s_barrier()
; #define PG8_SCHED __builtin_amdgcn_sched_barrier(0)
; template <class Epi, class Sched, bool ALIGN_EPI = false, bool SP2 = false>
; __device__ __forceinline__ void gemm_phase(PG8_LAS unsigned char* lds, const Gemm g, const Sched& S, const Epi& E, const int wv  ) {
;     ...
;             PG8_LDA(At, 1, 1); PG8_STAGE(PG8_SB(1, 0), b3, voffB); PG8_STAGE(PG8_SB(1, 1), b3 + hstepB, voffB); PG8_STAGE(PG8_SA(1, 0), a3, voffA);
;             PG8_WAIT_V(8); PG8_WAIT_L(0); PG8_BAR; PG8_MMA(1, 0, At, B0); PG8_MMA(1, 1, At, B1); PG8_BAR; PG8_SCHED;
;     ...
;         if constexpr (ALIGN_EPI) { if (wr == 0) PG8_BAR; }
	v_mfma_f32_16x16x32_bf16 v[112:115], v[184:187], v[220:223], v[80:83]
	s_setprio 0
	s_add_i32 s70, s95, s74
	v_lshl_add_u64 v[84:85], v[228:229], 0, s[18:19]
	s_mov_b32 m0, s70
	s_nop 0
	ds_read_b128 v[80:83], v198 offset:49152
	ds_read_b128 v[200:203], v198 offset:50176
	ds_read_b128 v[204:207], v198 offset:51200
	ds_read_b128 v[208:211], v198 offset:52224
	ds_read_b128 v[212:215], v198 offset:53248
	ds_read_b128 v[216:219], v198 offset:54272
	ds_read_b128 v[220:223], v198 offset:55296
	ds_read_b128 v[224:227], v198 offset:56320
	global_load_lds_dwordx4 v[84:85], off
	s_add_i32 m0, s70, 0x2000
	s_add_u32 s68, s68, 0x100080
	v_lshl_add_u64 v[84:85], v[230:231], 0, s[18:19]
	s_addc_u32 s69, s69, 0
	s_add_i32 s70, s96, s74
	global_load_lds_dwordx4 v[84:85], off
	v_lshl_add_u64 v[84:85], s[68:69], 0, v[162:163]
	s_mov_b32 m0, s70
	s_nop 0
	global_load_lds_dwordx4 v[84:85], off
	v_lshl_add_u64 v[84:85], s[68:69], 0, v[166:167]
	s_add_i32 m0, s70, 0x2000
	s_nop 0
	global_load_lds_dwordx4 v[84:85], off
	v_lshl_add_u64 v[84:85], v[232:233], 0, s[18:19]
	s_mov_b32 m0, s82
	s_nop 0
	global_load_lds_dwordx4 v[84:85], off
	v_lshl_add_u64 v[84:85], v[234:235], 0, s[18:19]
	s_mov_b32 m0, s83
	s_nop 0
	global_load_lds_dwordx4 v[84:85], off
	s_waitcnt vmcnt(8)
	s_waitcnt lgkmcnt(0)
	s_barrier
	s_setprio 2
	s_waitcnt lgkmcnt(0)
	v_mfma_f32_16x16x32_bf16 v[84:87], v[52:55], v[80:83], v[108:111]
	v_mfma_f32_16x16x32_bf16 v[108:111], v[56:59], v[200:203], v[84:87]
	v_mfma_f32_16x16x32_bf16 v[84:87], v[60:63], v[80:83], v[96:99]
	v_mfma_f32_16x16x32_bf16 v[64:67], v[52:55], v[204:207], v[64:67]
	v_mfma_f32_16x16x32_bf16 v[36:39], v[60:63], v[204:207], v[36:39]
	v_mfma_f32_16x16x32_bf16 v[28:31], v[52:55], v[212:215], v[28:31]
	v_mfma_f32_16x16x32_bf16 v[20:23], v[60:63], v[212:215], v[20:23]
	v_mfma_f32_16x16x32_bf16 v[12:15], v[52:55], v[220:223], v[12:15]
	v_mfma_f32_16x16x32_bf16 v[4:7], v[60:63], v[220:223], v[4:7]
	v_mfma_f32_16x16x32_bf16 v[96:99], v[68:71], v[200:203], v[84:87]
	v_mfma_f32_16x16x32_bf16 v[64:67], v[56:59], v[208:211], v[64:67]
	v_mfma_f32_16x16x32_bf16 v[36:39], v[68:71], v[208:211], v[36:39]
	v_mfma_f32_16x16x32_bf16 v[28:31], v[56:59], v[216:219], v[28:31]
	v_mfma_f32_16x16x32_bf16 v[20:23], v[68:71], v[216:219], v[20:23]
	v_mfma_f32_16x16x32_bf16 v[12:15], v[56:59], v[224:227], v[12:15]
	v_mfma_f32_16x16x32_bf16 v[4:7], v[68:71], v[224:227], v[4:7]
	s_setprio 0
	s_setprio 2
	v_mfma_f32_16x16x32_bf16 v[44:47], v[72:75], v[80:83], v[44:47]
	v_mfma_f32_16x16x32_bf16 v[84:87], v[76:79], v[200:203], v[44:47]
	v_mfma_f32_16x16x32_bf16 v[44:47], v[180:183], v[80:83], v[48:51]
	v_mfma_f32_16x16x32_bf16 v[40:43], v[72:75], v[204:207], v[40:43]
	v_mfma_f32_16x16x32_bf16 v[32:35], v[180:183], v[204:207], v[32:35]
	v_mfma_f32_16x16x32_bf16 v[24:27], v[72:75], v[212:215], v[24:27]
	v_mfma_f32_16x16x32_bf16 v[16:19], v[180:183], v[212:215], v[16:19]
	v_mfma_f32_16x16x32_bf16 v[8:11], v[72:75], v[220:223], v[8:11]
	v_mfma_f32_16x16x32_bf16 v[0:3], v[180:183], v[220:223], v[0:3]
	v_mfma_f32_16x16x32_bf16 v[80:83], v[184:187], v[200:203], v[44:47]
	v_mfma_f32_16x16x32_bf16 v[40:43], v[76:79], v[208:211], v[40:43]
	v_mfma_f32_16x16x32_bf16 v[32:35], v[184:187], v[208:211], v[32:35]
	v_mfma_f32_16x16x32_bf16 v[24:27], v[76:79], v[216:219], v[24:27]
	v_mfma_f32_16x16x32_bf16 v[16:19], v[184:187], v[216:219], v[16:19]
	v_mfma_f32_16x16x32_bf16 v[8:11], v[76:79], v[224:227], v[8:11]
	s_setprio 3
	s_barrier
	v_mfma_f32_16x16x32_bf16 v[0:3], v[184:187], v[224:227], v[0:3]
	s_setprio 0
	s_add_i32 s94, s94, 2
	s_add_u32 s66, s66, 0x100
	s_addc_u32 s67, s67, 0
	s_add_u32 s92, s92, 0x100
	s_addc_u32 s93, s93, 0
	s_cmp_gt_u32 s94, 61
	s_cbranch_scc0 .LBB0_1187
	s_and_b64 vcc, exec, s[20:21]
	s_cbranch_vccz .LBB0_1190
	s_barrier

; #define PG8_STAGE(bufoff, gbase, voff) do { _Pragma("unroll") for (int _i = 0; _i < 2; ++_i) \
;         __builtin_amdgcn_global_load_lds((const unsigned*)((const char*)(gbase) + (voff)[_i]), (PG8_LAS unsigned*)(lds + (bufoff) + ldsw + _i * 8192), 16, 0, 0); } while (0)
; #define PG8_LDA(dst, b, h) do { _Pragma("unroll") for (int m = 0; m < 4; ++m) _Pragma("unroll") for (int k = 0; k < 2; ++k) dst[m][k] = *(const PG8_LAS bf16x8*)(lds + PG8_SA(b, h) + aoff + m * 2048 + k * 1024); } while (0)
; #define PG8_LDB(dst, b, h) do { _Pragma("unroll") for (int n = 0; n < 2; ++n) _Pragma("unroll") for (int k = 0; k < 2; ++k) dst[n][k] = *(const PG8_LAS bf16x8*)(lds + PG8_SB(b, h) + boff + n * 2048 + k * 1024); } while (0)
; #define PG8_MMA(ai, bj, At, Bt) do { __builtin_amdgcn_s_setprio(1); _Pragma("unroll") for (int m = 0; m < 4; ++m) _Pragma("unroll") for (int n = 0; n < 2; ++n) _Pragma("unroll") for (int k = 0; k < 2; ++k) \
;         acc[ai][bj][m][n] = __builtin_amdgcn_mfma_f32_16x16x32_bf16(Bt[n][k], At[m][k], acc[ai][bj][m][n], 0, 0, 0); __builtin_amdgcn_s_setprio(0); } while (0)
; #define PG8_WAIT_V(n) asm volatile("s_waitcnt vmcnt(" #n ")" ::: "memory")
; #define PG8_WAIT_L(n) asm volatile("s_waitcnt lgkmcnt(" #n ")" ::: "memory")
; #define PG8_BAR __builtin_amdgcn_s_barrier()
; #define PG8_SCHED __builtin_amdgcn_sched_barrier(0)
; template <class Epi, class Sched, bool ALIGN_EPI = false, bool SP2 = false>
; __device__ __forceinline__ void gemm_phase(PG8_LAS unsigned char* lds, const Gemm g, const Sched& S, const Epi& E, const int wv  ) {
;     ...
;             const bool last = (t == nt - 2);
;             const char* a1 = cA + (size_t)(t + 1) * kstep;
;             const char* a2 = last ? nA : cA + (size_t)(t + 2) * kstep; const char* b2 = last ? nB : cB + (size_t)(t + 2) * kstep;
;             const char* a3 = a2 + kstep; const char* b3 = b2 + kstep;
;             if (last && has_next) S.a_ready(nxt);
;             if constexpr (SP2) {
;             PG8_LDB(B0, 0, 0); PG8_LDB(B1, 0, 1); PG8_SCHED; PG8_LDA(At, 0, 0); PG8_STAGE(PG8_SA(1, 1), a1 + hstepA, voffA);
;             PG8_WAIT_V(8); PG8_WAIT_L(0); PG8_BAR; PG8_MMA(0, 0, At, B0); PG8_MMA(0, 1, At, B1); PG8_BAR; PG8_SCHED;
;             PG8_LDA(At, 0, 1); PG8_STAGE(PG8_SB(0, 0), b2, voffB); PG8_STAGE(PG8_SB(0, 1), b2 + hstepB, voffB); PG8_STAGE(PG8_SA(0, 0), a2, voffA);
.LBB0_1544:
	ds_read_b128 v[146:149], v152
	ds_read_b128 v[156:159], v152 offset:1024
	ds_read_b128 v[160:163], v152 offset:2048
	ds_read_b128 v[164:167], v152 offset:3072
	ds_read_b128 v[168:171], v153
	ds_read_b128 v[172:175], v153 offset:1024
	ds_read_b128 v[176:179], v153 offset:2048
	ds_read_b128 v[180:183], v153 offset:3072
	s_add_u32 s54, s52, 0x100
	s_addc_u32 s55, s53, 0
	s_cmpk_eq_i32 s85, 0xa8
	s_cselect_b32 s59, s7, s55
	s_cselect_b32 s58, s6, s54
	s_cselect_b32 s57, s51, s84
	s_cselect_b32 s56, s50, s83
	v_lshl_add_u64 v[216:217], s[52:53], 0, v[138:139]
	s_add_i32 m0, s64, 0xc000
	ds_read_b128 v[184:187], v154
	ds_read_b128 v[188:191], v154 offset:1024
	ds_read_b128 v[192:195], v154 offset:2048
	ds_read_b128 v[196:199], v154 offset:3072
	ds_read_b128 v[200:203], v154 offset:4096
	ds_read_b128 v[204:207], v154 offset:5120
	ds_read_b128 v[208:211], v154 offset:6144
	ds_read_b128 v[212:215], v154 offset:7168
	global_load_lds_dwordx4 v[216:217], off
	v_lshl_add_u64 v[216:217], s[52:53], 0, v[140:141]
	s_add_i32 m0, s64, 0xe000
	s_nop 0
	global_load_lds_dwordx4 v[216:217], off
	s_waitcnt vmcnt(8)
	s_waitcnt lgkmcnt(0)
	s_barrier
	s_setprio 2
	s_waitcnt lgkmcnt(0)
	v_mfma_f32_16x16x32_bf16 v[76:79], v[146:149], v[184:187], v[76:79]
	v_mfma_f32_16x16x32_bf16 v[72:75], v[160:163], v[184:187], v[72:75]
	v_mfma_f32_16x16x32_bf16 v[68:71], v[146:149], v[192:195], v[68:71]
	v_mfma_f32_16x16x32_bf16 v[64:67], v[160:163], v[192:195], v[64:67]
	v_mfma_f32_16x16x32_bf16 v[56:59], v[146:149], v[200:203], v[56:59]
	v_mfma_f32_16x16x32_bf16 v[52:55], v[160:163], v[200:203], v[52:55]
	v_mfma_f32_16x16x32_bf16 v[44:47], v[146:149], v[208:211], v[44:47]
	v_mfma_f32_16x16x32_bf16 v[40:43], v[160:163], v[208:211], v[40:43]
	v_mfma_f32_16x16x32_bf16 v[76:79], v[156:159], v[188:191], v[76:79]
	v_mfma_f32_16x16x32_bf16 v[72:75], v[164:167], v[188:191], v[72:75]
	v_mfma_f32_16x16x32_bf16 v[68:71], v[156:159], v[196:199], v[68:71]
	v_mfma_f32_16x16x32_bf16 v[64:67], v[164:167], v[196:199], v[64:67]
	v_mfma_f32_16x16x32_bf16 v[56:59], v[156:159], v[204:207], v[56:59]
	v_mfma_f32_16x16x32_bf16 v[52:55], v[164:167], v[204:207], v[52:55]
	v_mfma_f32_16x16x32_bf16 v[44:47], v[156:159], v[212:215], v[44:47]
	v_mfma_f32_16x16x32_bf16 v[40:43], v[164:167], v[212:215], v[40:43]
	s_setprio 0
	s_setprio 2
	v_mfma_f32_16x16x32_bf16 v[124:127], v[168:171], v[184:187], v[124:127]
	v_mfma_f32_16x16x32_bf16 v[120:123], v[176:179], v[184:187], v[120:123]
	v_mfma_f32_16x16x32_bf16 v[116:119], v[168:171], v[192:195], v[116:119]
	v_mfma_f32_16x16x32_bf16 v[112:115], v[176:179], v[192:195], v[112:115]
	v_mfma_f32_16x16x32_bf16 v[108:111], v[168:171], v[200:203], v[108:111]
	v_mfma_f32_16x16x32_bf16 v[104:107], v[176:179], v[200:203], v[104:107]
	v_mfma_f32_16x16x32_bf16 v[100:103], v[168:171], v[208:211], v[100:103]
	v_mfma_f32_16x16x32_bf16 v[96:99], v[176:179], v[208:211], v[96:99]
	v_mfma_f32_16x16x32_bf16 v[124:127], v[172:175], v[188:191], v[124:127]
	v_mfma_f32_16x16x32_bf16 v[120:123], v[180:183], v[188:191], v[120:123]
	v_mfma_f32_16x16x32_bf16 v[116:119], v[172:175], v[196:199], v[116:119]
	v_mfma_f32_16x16x32_bf16 v[112:115], v[180:183], v[196:199], v[112:115]
	v_mfma_f32_16x16x32_bf16 v[108:111], v[172:175], v[204:207], v[108:111]
	v_mfma_f32_16x16x32_bf16 v[104:107], v[180:183], v[204:207], v[104:107]
	v_mfma_f32_16x16x32_bf16 v[100:103], v[172:175], v[212:215], v[100:103]
	s_setprio 3
	s_barrier
	v_mfma_f32_16x16x32_bf16 v[96:99], v[180:183], v[212:215], v[96:99]
	s_setprio 0
	s_add_i32 s52, s73, s63
	v_lshl_add_u64 v[216:217], s[56:57], 0, v[130:131]
	s_mov_b32 m0, s52
	ds_read_b128 v[184:187], v154 offset:16384
	ds_read_b128 v[188:191], v154 offset:17408
	ds_read_b128 v[192:195], v154 offset:18432
	ds_read_b128 v[196:199], v154 offset:19456
	ds_read_b128 v[200:203], v154 offset:20480
	ds_read_b128 v[204:207], v154 offset:21504
	ds_read_b128 v[208:211], v154 offset:22528
	ds_read_b128 v[212:215], v154 offset:23552
	global_load_lds_dwordx4 v[216:217], off
	s_add_i32 m0, s52, 0x2000
	s_add_u32 s52, s56, 0x2b0000
	v_lshl_add_u64 v[218:219], s[56:57], 0, v[134:135]
	s_addc_u32 s53, s57, 0
	s_add_i32 s86, s74, s63
	global_load_lds_dwordx4 v[218:219], off
	v_lshl_add_u64 v[220:221], s[52:53], 0, v[130:131]
	s_mov_b32 m0, s86
	v_lshl_add_u64 v[222:223], s[58:59], 0, v[132:133]
	global_load_lds_dwordx4 v[220:221], off
	v_lshl_add_u64 v[220:221], s[52:53], 0, v[134:135]
	s_add_i32 m0, s86, 0x2000
	s_nop 0
	global_load_lds_dwordx4 v[220:221], off
	v_lshl_add_u64 v[220:221], s[58:59], 0, v[128:129]
	s_mov_b32 m0, s64
	s_nop 0
	global_load_lds_dwordx4 v[220:221], off
	s_mov_b32 m0, s65
	s_nop 0
	global_load_lds_dwordx4 v[222:223], off
	s_waitcnt vmcnt(8)
	s_waitcnt lgkmcnt(0)
	s_barrier
; #define PG8_STAGE(bufoff, gbase, voff) do { _Pragma("unroll") for (int _i = 0; _i < 2; ++_i) \
;         __builtin_amdgcn_global_load_lds((const unsigned*)((const char*)(gbase) + (voff)[_i]), (PG8_LAS unsigned*)(lds + (bufoff) + ldsw + _i * 8192), 16, 0, 0); } while (0)
; #define PG8_LDA(dst, b, h) do { _Pragma("unroll") for (int m = 0; m < 4; ++m) _Pragma("unroll") for (int k = 0; k < 2; ++k) dst[m][k] = *(const PG8_LAS bf16x8*)(lds + PG8_SA(b, h) + aoff + m * 2048 + k * 1024); } while (0)
; #define PG8_LDB(dst, b, h) do { _Pragma("unroll") for (int n = 0; n < 2; ++n) _Pragma("unroll") for (int k = 0; k < 2; ++k) dst[n][k] = *(const PG8_LAS bf16x8*)(lds + PG8_SB(b, h) + boff + n * 2048 + k * 1024); } while (0)
; #define PG8_MMA(ai, bj, At, Bt) do { __builtin_amdgcn_s_setprio(1); _Pragma("unroll") for (int m = 0; m < 4; ++m) _Pragma("unroll") for (int n = 0; n < 2; ++n) _Pragma("unroll") for (int k = 0; k < 2; ++k) \
;         acc[ai][bj][m][n] = __builtin_amdgcn_mfma_f32_16x16x32_bf16(Bt[n][k], At[m][k], acc[ai][bj][m][n], 0, 0, 0); __builtin_amdgcn_s_setprio(0); } while (0)
; #define PG8_WAIT_V(n) asm volatile("s_waitcnt vmcnt(" #n ")" ::: "memory")
; #define PG8_WAIT_L(n) asm volatile("s_waitcnt lgkmcnt(" #n ")" ::: "memory")
; #define PG8_BAR __builtin_amdgcn_s_barrier()
; #define PG8_SCHED __builtin_amdgcn_sched_barrier(0)
; template <class Epi, class Sched, bool ALIGN_EPI = false, bool SP2 = false>
; __device__ __forceinline__ void gemm_phase(PG8_LAS unsigned char* lds, const Gemm g, const Sched& S, const Epi& E, const int wv  ) {
;     ...
;             PG8_WAIT_V(8); PG8_WAIT_L(0); PG8_BAR; PG8_MMA(1, 0, At, B0); PG8_MMA(1, 1, At, B1); PG8_BAR; PG8_SCHED;
;             PG8_LDB(B0, 1, 0); PG8_LDB(B1, 1, 1); PG8_SCHED; PG8_LDA(At, 1, 0); PG8_STAGE(PG8_SA(0, 1), a2 + hstepA, voffA);
;             PG8_WAIT_V(8); PG8_WAIT_L(0); PG8_BAR; PG8_MMA(0, 0, At, B0); PG8_MMA(0, 1, At, B1); PG8_BAR; PG8_SCHED;
	s_setprio 2
	s_waitcnt lgkmcnt(0)
	v_mfma_f32_16x16x32_bf16 v[28:31], v[146:149], v[184:187], v[28:31]
	v_mfma_f32_16x16x32_bf16 v[24:27], v[160:163], v[184:187], v[24:27]
	v_mfma_f32_16x16x32_bf16 v[20:23], v[146:149], v[192:195], v[20:23]
	v_mfma_f32_16x16x32_bf16 v[16:19], v[160:163], v[192:195], v[16:19]
	v_mfma_f32_16x16x32_bf16 v[12:15], v[146:149], v[200:203], v[12:15]
	v_mfma_f32_16x16x32_bf16 v[8:11], v[160:163], v[200:203], v[8:11]
	v_mfma_f32_16x16x32_bf16 v[4:7], v[146:149], v[208:211], v[4:7]
	v_mfma_f32_16x16x32_bf16 v[0:3], v[160:163], v[208:211], v[0:3]
	v_mfma_f32_16x16x32_bf16 v[28:31], v[156:159], v[188:191], v[28:31]
	v_mfma_f32_16x16x32_bf16 v[24:27], v[164:167], v[188:191], v[24:27]
	v_mfma_f32_16x16x32_bf16 v[20:23], v[156:159], v[196:199], v[20:23]
	v_mfma_f32_16x16x32_bf16 v[16:19], v[164:167], v[196:199], v[16:19]
	v_mfma_f32_16x16x32_bf16 v[12:15], v[156:159], v[204:207], v[12:15]
	v_mfma_f32_16x16x32_bf16 v[8:11], v[164:167], v[204:207], v[8:11]
	v_mfma_f32_16x16x32_bf16 v[4:7], v[156:159], v[212:215], v[4:7]
	v_mfma_f32_16x16x32_bf16 v[0:3], v[164:167], v[212:215], v[0:3]
	s_setprio 0
	s_setprio 2
	v_mfma_f32_16x16x32_bf16 v[92:95], v[168:171], v[184:187], v[92:95]
	v_mfma_f32_16x16x32_bf16 v[88:91], v[176:179], v[184:187], v[88:91]
	v_mfma_f32_16x16x32_bf16 v[84:87], v[168:171], v[192:195], v[84:87]
	v_mfma_f32_16x16x32_bf16 v[80:83], v[176:179], v[192:195], v[80:83]
	v_mfma_f32_16x16x32_bf16 v[60:63], v[168:171], v[200:203], v[60:63]
	v_mfma_f32_16x16x32_bf16 v[48:51], v[176:179], v[200:203], v[48:51]
	v_mfma_f32_16x16x32_bf16 v[36:39], v[168:171], v[208:211], v[36:39]
	v_mfma_f32_16x16x32_bf16 v[32:35], v[176:179], v[208:211], v[32:35]
	v_mfma_f32_16x16x32_bf16 v[92:95], v[172:175], v[188:191], v[92:95]
	v_mfma_f32_16x16x32_bf16 v[88:91], v[180:183], v[188:191], v[88:91]
	v_mfma_f32_16x16x32_bf16 v[84:87], v[172:175], v[196:199], v[84:87]
	v_mfma_f32_16x16x32_bf16 v[80:83], v[180:183], v[196:199], v[80:83]
	v_mfma_f32_16x16x32_bf16 v[60:63], v[172:175], v[204:207], v[60:63]
	v_mfma_f32_16x16x32_bf16 v[48:51], v[180:183], v[204:207], v[48:51]
	v_mfma_f32_16x16x32_bf16 v[36:39], v[172:175], v[212:215], v[36:39]
	s_setprio 3
	s_barrier
	v_mfma_f32_16x16x32_bf16 v[32:35], v[180:183], v[212:215], v[32:35]
	s_setprio 0
	s_add_i32 s86, 0, 0x18000
	v_add_u32_e32 v155, s86, v150
	s_add_i32 s87, 0, 0x1c000
	ds_read_b128 v[146:149], v155
	ds_read_b128 v[156:159], v155 offset:1024
	ds_read_b128 v[160:163], v155 offset:2048
	ds_read_b128 v[164:167], v155 offset:3072
	v_add_u32_e32 v155, s87, v150
	ds_read_b128 v[168:171], v155
	ds_read_b128 v[172:175], v155 offset:1024
	ds_read_b128 v[176:179], v155 offset:2048
	ds_read_b128 v[180:183], v155 offset:3072
	s_add_u32 s52, s58, 0x2b0000
	s_addc_u32 s53, s59, 0
	s_mov_b32 m0, s66
	v_lshl_add_u64 v[224:225], s[52:53], 0, v[128:129]
	ds_read_b128 v[184:187], v154 offset:32768
	ds_read_b128 v[188:191], v154 offset:33792
	ds_read_b128 v[192:195], v154 offset:34816
	ds_read_b128 v[196:199], v154 offset:35840
	ds_read_b128 v[200:203], v154 offset:36864
	ds_read_b128 v[204:207], v154 offset:37888
	ds_read_b128 v[208:211], v154 offset:38912
	ds_read_b128 v[212:215], v154 offset:39936
	global_load_lds_dwordx4 v[224:225], off
	v_lshl_add_u64 v[224:225], s[52:53], 0, v[132:133]
	s_mov_b32 m0, s67
	s_nop 0
	global_load_lds_dwordx4 v[224:225], off
	s_waitcnt vmcnt(8)
	s_waitcnt lgkmcnt(0)
	s_barrier
	s_setprio 2
	s_waitcnt lgkmcnt(0)
	v_mfma_f32_16x16x32_bf16 v[76:79], v[146:149], v[184:187], v[76:79]
	v_mfma_f32_16x16x32_bf16 v[72:75], v[160:163], v[184:187], v[72:75]
	v_mfma_f32_16x16x32_bf16 v[68:71], v[146:149], v[192:195], v[68:71]
	v_mfma_f32_16x16x32_bf16 v[64:67], v[160:163], v[192:195], v[64:67]
	v_mfma_f32_16x16x32_bf16 v[56:59], v[146:149], v[200:203], v[56:59]
	v_mfma_f32_16x16x32_bf16 v[52:55], v[160:163], v[200:203], v[52:55]
	v_mfma_f32_16x16x32_bf16 v[44:47], v[146:149], v[208:211], v[44:47]
	v_mfma_f32_16x16x32_bf16 v[40:43], v[160:163], v[208:211], v[40:43]
	v_mfma_f32_16x16x32_bf16 v[76:79], v[156:159], v[188:191], v[76:79]
	v_mfma_f32_16x16x32_bf16 v[72:75], v[164:167], v[188:191], v[72:75]
	v_mfma_f32_16x16x32_bf16 v[68:71], v[156:159], v[196:199], v[68:71]
	v_mfma_f32_16x16x32_bf16 v[64:67], v[164:167], v[196:199], v[64:67]
	v_mfma_f32_16x16x32_bf16 v[56:59], v[156:159], v[204:207], v[56:59]
	v_mfma_f32_16x16x32_bf16 v[52:55], v[164:167], v[204:207], v[52:55]
	v_mfma_f32_16x16x32_bf16 v[44:47], v[156:159], v[212:215], v[44:47]
	v_mfma_f32_16x16x32_bf16 v[40:43], v[164:167], v[212:215], v[40:43]
	s_setprio 0
	s_setprio 2
	v_mfma_f32_16x16x32_bf16 v[124:127], v[168:171], v[184:187], v[124:127]
	v_mfma_f32_16x16x32_bf16 v[120:123], v[176:179], v[184:187], v[120:123]
	v_mfma_f32_16x16x32_bf16 v[116:119], v[168:171], v[192:195], v[116:119]
	v_mfma_f32_16x16x32_bf16 v[112:115], v[176:179], v[192:195], v[112:115]
	v_mfma_f32_16x16x32_bf16 v[108:111], v[168:171], v[200:203], v[108:111]
	v_mfma_f32_16x16x32_bf16 v[104:107], v[176:179], v[200:203], v[104:107]
	v_mfma_f32_16x16x32_bf16 v[100:103], v[168:171], v[208:211], v[100:103]
	v_mfma_f32_16x16x32_bf16 v[96:99], v[176:179], v[208:211], v[96:99]
	v_mfma_f32_16x16x32_bf16 v[124:127], v[172:175], v[188:191], v[124:127]
	v_mfma_f32_16x16x32_bf16 v[120:123], v[180:183], v[188:191], v[120:123]
	v_mfma_f32_16x16x32_bf16 v[116:119], v[172:175], v[196:199], v[116:119]
	v_mfma_f32_16x16x32_bf16 v[112:115], v[180:183], v[196:199], v[112:115]
	v_mfma_f32_16x16x32_bf16 v[108:111], v[172:175], v[204:207], v[108:111]
	v_mfma_f32_16x16x32_bf16 v[104:107], v[180:183], v[204:207], v[104:107]
	v_mfma_f32_16x16x32_bf16 v[100:103], v[172:175], v[212:215], v[100:103]
	s_setprio 3
	s_barrier
; #define PG8_STAGE(bufoff, gbase, voff) do { _Pragma("unroll") for (int _i = 0; _i < 2; ++_i) \
;         __builtin_amdgcn_global_load_lds((const unsigned*)((const char*)(gbase) + (voff)[_i]), (PG8_LAS unsigned*)(lds + (bufoff) + ldsw + _i * 8192), 16, 0, 0); } while (0)
; #define PG8_LDA(dst, b, h) do { _Pragma("unroll") for (int m = 0; m < 4; ++m) _Pragma("unroll") for (int k = 0; k < 2; ++k) dst[m][k] = *(const PG8_LAS bf16x8*)(lds + PG8_SA(b, h) + aoff + m * 2048 + k * 1024); } while (0)
; #define PG8_MMA(ai, bj, At, Bt) do { __builtin_amdgcn_s_setprio(1); _Pragma("unroll") for (int m = 0; m < 4; ++m) _Pragma("unroll") for (int n = 0; n < 2; ++n) _Pragma("unroll") for (int k = 0; k < 2; ++k) \
;         acc[ai][bj][m][n] = __builtin_amdgcn_mfma_f32_16x16x32_bf16(Bt[n][k], At[m][k], acc[ai][bj][m][n], 0, 0, 0); __builtin_amdgcn_s_setprio(0); } while (0)
; #define PG8_WAIT_V(n) asm volatile("s_waitcnt vmcnt(" #n ")" ::: "memory")
; #define PG8_WAIT_L(n) asm volatile("s_waitcnt lgkmcnt(" #n ")" ::: "memory")
; #define PG8_BAR __builtin_amdgcn_s_barrier()
; #define PG8_SCHED __builtin_amdgcn_sched_barrier(0)
; template <class Epi, class Sched, bool ALIGN_EPI = false, bool SP2 = false>
; __device__ __forceinline__ void gemm_phase(PG8_LAS unsigned char* lds, const Gemm g, const Sched& S, const Epi& E, const int wv  ) {
;     ...
;             PG8_LDA(At, 1, 1); PG8_STAGE(PG8_SB(1, 0), b3, voffB); PG8_STAGE(PG8_SB(1, 1), b3 + hstepB, voffB); PG8_STAGE(PG8_SA(1, 0), a3, voffA);
;             PG8_WAIT_V(8); PG8_WAIT_L(0); PG8_BAR; PG8_MMA(1, 0, At, B0); PG8_MMA(1, 1, At, B1); PG8_BAR; PG8_SCHED;
;     ...
;         if constexpr (ALIGN_EPI) { if (wr == 0) PG8_BAR; }
	v_mfma_f32_16x16x32_bf16 v[96:99], v[180:183], v[212:215], v[96:99]
	s_setprio 0
	s_add_i32 s52, s86, s63
	v_lshl_add_u64 v[216:217], v[216:217], 0, s[12:13]
	s_mov_b32 m0, s52
	ds_read_b128 v[184:187], v154 offset:49152
	ds_read_b128 v[188:191], v154 offset:50176
	ds_read_b128 v[192:195], v154 offset:51200
	ds_read_b128 v[196:199], v154 offset:52224
	ds_read_b128 v[200:203], v154 offset:53248
	ds_read_b128 v[204:207], v154 offset:54272
	ds_read_b128 v[208:211], v154 offset:55296
	ds_read_b128 v[212:215], v154 offset:56320
	global_load_lds_dwordx4 v[216:217], off
	s_add_i32 m0, s52, 0x2000
	s_add_u32 s52, s56, 0x2b0080
	v_lshl_add_u64 v[216:217], v[218:219], 0, s[12:13]
	s_addc_u32 s53, s57, 0
	s_add_i32 s56, s87, s63
	global_load_lds_dwordx4 v[216:217], off
	v_lshl_add_u64 v[216:217], s[52:53], 0, v[130:131]
	s_mov_b32 m0, s56
	s_nop 0
	global_load_lds_dwordx4 v[216:217], off
	v_lshl_add_u64 v[216:217], s[52:53], 0, v[134:135]
	s_add_i32 m0, s56, 0x2000
	s_nop 0
	global_load_lds_dwordx4 v[216:217], off
	v_lshl_add_u64 v[216:217], v[220:221], 0, s[12:13]
	s_mov_b32 m0, s70
	s_nop 0
	global_load_lds_dwordx4 v[216:217], off
	v_lshl_add_u64 v[216:217], v[222:223], 0, s[12:13]
	s_mov_b32 m0, s71
	s_nop 0
	global_load_lds_dwordx4 v[216:217], off
	s_waitcnt vmcnt(8)
	s_waitcnt lgkmcnt(0)
	s_barrier
	s_setprio 2
	s_waitcnt lgkmcnt(0)
	v_mfma_f32_16x16x32_bf16 v[28:31], v[146:149], v[184:187], v[28:31]
	v_mfma_f32_16x16x32_bf16 v[24:27], v[160:163], v[184:187], v[24:27]
	v_mfma_f32_16x16x32_bf16 v[20:23], v[146:149], v[192:195], v[20:23]
	v_mfma_f32_16x16x32_bf16 v[16:19], v[160:163], v[192:195], v[16:19]
	v_mfma_f32_16x16x32_bf16 v[12:15], v[146:149], v[200:203], v[12:15]
	v_mfma_f32_16x16x32_bf16 v[8:11], v[160:163], v[200:203], v[8:11]
	v_mfma_f32_16x16x32_bf16 v[4:7], v[146:149], v[208:211], v[4:7]
	v_mfma_f32_16x16x32_bf16 v[0:3], v[160:163], v[208:211], v[0:3]
	v_mfma_f32_16x16x32_bf16 v[28:31], v[156:159], v[188:191], v[28:31]
	v_mfma_f32_16x16x32_bf16 v[24:27], v[164:167], v[188:191], v[24:27]
	v_mfma_f32_16x16x32_bf16 v[20:23], v[156:159], v[196:199], v[20:23]
	v_mfma_f32_16x16x32_bf16 v[16:19], v[164:167], v[196:199], v[16:19]
	v_mfma_f32_16x16x32_bf16 v[12:15], v[156:159], v[204:207], v[12:15]
	v_mfma_f32_16x16x32_bf16 v[8:11], v[164:167], v[204:207], v[8:11]
	v_mfma_f32_16x16x32_bf16 v[4:7], v[156:159], v[212:215], v[4:7]
	v_mfma_f32_16x16x32_bf16 v[0:3], v[164:167], v[212:215], v[0:3]
	s_setprio 0
	s_setprio 2
	v_mfma_f32_16x16x32_bf16 v[92:95], v[168:171], v[184:187], v[92:95]
	v_mfma_f32_16x16x32_bf16 v[88:91], v[176:179], v[184:187], v[88:91]
	v_mfma_f32_16x16x32_bf16 v[84:87], v[168:171], v[192:195], v[84:87]
	v_mfma_f32_16x16x32_bf16 v[80:83], v[176:179], v[192:195], v[80:83]
	v_mfma_f32_16x16x32_bf16 v[60:63], v[168:171], v[200:203], v[60:63]
	v_mfma_f32_16x16x32_bf16 v[48:51], v[176:179], v[200:203], v[48:51]
	v_mfma_f32_16x16x32_bf16 v[36:39], v[168:171], v[208:211], v[36:39]
	v_mfma_f32_16x16x32_bf16 v[32:35], v[176:179], v[208:211], v[32:35]
	v_mfma_f32_16x16x32_bf16 v[92:95], v[172:175], v[188:191], v[92:95]
	v_mfma_f32_16x16x32_bf16 v[88:91], v[180:183], v[188:191], v[88:91]
	v_mfma_f32_16x16x32_bf16 v[84:87], v[172:175], v[196:199], v[84:87]
	v_mfma_f32_16x16x32_bf16 v[80:83], v[180:183], v[196:199], v[80:83]
	v_mfma_f32_16x16x32_bf16 v[60:63], v[172:175], v[204:207], v[60:63]
	v_mfma_f32_16x16x32_bf16 v[48:51], v[180:183], v[204:207], v[48:51]
	v_mfma_f32_16x16x32_bf16 v[36:39], v[172:175], v[212:215], v[36:39]
	s_setprio 3
	s_barrier
	v_mfma_f32_16x16x32_bf16 v[32:35], v[180:183], v[212:215], v[32:35]
	s_setprio 0
	s_add_i32 s85, s85, 2
	s_add_u32 s83, s83, 0x100
	s_addc_u32 s84, s84, 0
	s_cmpk_gt_u32 s85, 0xa9
	s_mov_b64 s[52:53], s[54:55]
	s_cbranch_scc0 .LBB0_1544
	s_and_b64 vcc, exec, s[14:15]
	s_cbranch_vccz .LBB0_1547
	s_barrier

; #define PG8_STAGE(bufoff, gbase, voff) do { _Pragma("unroll") for (int _i = 0; _i < 2; ++_i) \
;         __builtin_amdgcn_global_load_lds((const unsigned*)((const char*)(gbase) + (voff)[_i]), (PG8_LAS unsigned*)(lds + (bufoff) + ldsw + _i * 8192), 16, 0, 0); } while (0)
; #define PG8_LDA(dst, b, h) do { _Pragma("unroll") for (int m = 0; m < 4; ++m) _Pragma("unroll") for (int k = 0; k < 2; ++k) dst[m][k] = *(const PG8_LAS bf16x8*)(lds + PG8_SA(b, h) + aoff + m * 2048 + k * 1024); } while (0)
; #define PG8_LDB(dst, b, h) do { _Pragma("unroll") for (int n = 0; n < 2; ++n) _Pragma("unroll") for (int k = 0; k < 2; ++k) dst[n][k] = *(const PG8_LAS bf16x8*)(lds + PG8_SB(b, h) + boff + n * 2048 + k * 1024); } while (0)
; #define PG8_MMA(ai, bj, At, Bt) do { __builtin_amdgcn_s_setprio(1); _Pragma("unroll") for (int m = 0; m < 4; ++m) _Pragma("unroll") for (int n = 0; n < 2; ++n) _Pragma("unroll") for (int k = 0; k < 2; ++k) \
;         acc[ai][bj][m][n] = __builtin_amdgcn_mfma_f32_16x16x32_bf16(Bt[n][k], At[m][k], acc[ai][bj][m][n], 0, 0, 0); __builtin_amdgcn_s_setprio(0); } while (0)
; #define PG8_WAIT_V(n) asm volatile("s_waitcnt vmcnt(" #n ")" ::: "memory")
; #define PG8_WAIT_L(n) asm volatile("s_waitcnt lgkmcnt(" #n ")" ::: "memory")
; #define PG8_BAR __builtin_amdgcn_s_barrier()
; #define PG8_SCHED __builtin_amdgcn_sched_barrier(0)
; template <class Epi, class Sched, bool ALIGN_EPI = false, bool SP2 = false>
; __device__ __forceinline__ void gemm_phase(PG8_LAS unsigned char* lds, const Gemm g, const Sched& S, const Epi& E, const int wv  ) {
;     ...
;             const bool last = (t == nt - 2);
;             const char* a1 = cA + (size_t)(t + 1) * kstep;
;             const char* a2 = last ? nA : cA + (size_t)(t + 2) * kstep; const char* b2 = last ? nB : cB + (size_t)(t + 2) * kstep;
;             const char* a3 = a2 + kstep; const char* b3 = b2 + kstep;
;             if (last && has_next) S.a_ready(nxt);
;             if constexpr (SP2) {
;             PG8_LDB(B0, 0, 0); PG8_LDB(B1, 0, 1); PG8_SCHED; PG8_LDA(At, 0, 0); PG8_STAGE(PG8_SA(1, 1), a1 + hstepA, voffA);
;             PG8_WAIT_V(8); PG8_WAIT_L(0); PG8_BAR; PG8_MMA(0, 0, At, B0); PG8_MMA(0, 1, At, B1); PG8_BAR; PG8_SCHED;
;             PG8_LDA(At, 0, 1); PG8_STAGE(PG8_SB(0, 0), b2, voffB); PG8_STAGE(PG8_SB(0, 1), b2 + hstepB, voffB); PG8_STAGE(PG8_SA(0, 0), a2, voffA);
.LBB0_1717:
	ds_read_b128 v[146:149], v152
	ds_read_b128 v[156:159], v152 offset:1024
	ds_read_b128 v[160:163], v152 offset:2048
	ds_read_b128 v[164:167], v152 offset:3072
	ds_read_b128 v[168:171], v153
	ds_read_b128 v[172:175], v153 offset:1024
	ds_read_b128 v[176:179], v153 offset:2048
	ds_read_b128 v[180:183], v153 offset:3072
	s_add_u32 s60, s58, 0xfff00080
	s_addc_u32 s61, s59, -1
	s_cmp_eq_u32 s87, 60
	s_cselect_b32 s63, s51, s61
	s_cselect_b32 s62, s83, s60
	s_cselect_b32 s61, s49, s86
	s_cselect_b32 s60, s84, s85
	v_lshl_add_u64 v[216:217], s[58:59], 0, v[138:139]
	s_add_i32 m0, s70, 0xc000
	ds_read_b128 v[184:187], v154
	ds_read_b128 v[188:191], v154 offset:1024
	ds_read_b128 v[192:195], v154 offset:2048
	ds_read_b128 v[196:199], v154 offset:3072
	ds_read_b128 v[200:203], v154 offset:4096
	ds_read_b128 v[204:207], v154 offset:5120
	ds_read_b128 v[208:211], v154 offset:6144
	ds_read_b128 v[212:215], v154 offset:7168
	global_load_lds_dwordx4 v[216:217], off
	v_lshl_add_u64 v[216:217], s[58:59], 0, v[140:141]
	s_add_i32 m0, s70, 0xe000
	s_nop 0
	global_load_lds_dwordx4 v[216:217], off
	s_waitcnt vmcnt(8)
	s_waitcnt lgkmcnt(0)
	s_barrier
	s_setprio 2
	s_waitcnt lgkmcnt(0)
	v_mfma_f32_16x16x32_bf16 v[76:79], v[146:149], v[184:187], v[76:79]
	v_mfma_f32_16x16x32_bf16 v[72:75], v[160:163], v[184:187], v[72:75]
	v_mfma_f32_16x16x32_bf16 v[68:71], v[146:149], v[192:195], v[68:71]
	v_mfma_f32_16x16x32_bf16 v[64:67], v[160:163], v[192:195], v[64:67]
	v_mfma_f32_16x16x32_bf16 v[56:59], v[146:149], v[200:203], v[56:59]
	v_mfma_f32_16x16x32_bf16 v[52:55], v[160:163], v[200:203], v[52:55]
	v_mfma_f32_16x16x32_bf16 v[44:47], v[146:149], v[208:211], v[44:47]
	v_mfma_f32_16x16x32_bf16 v[40:43], v[160:163], v[208:211], v[40:43]
	v_mfma_f32_16x16x32_bf16 v[76:79], v[156:159], v[188:191], v[76:79]
	v_mfma_f32_16x16x32_bf16 v[72:75], v[164:167], v[188:191], v[72:75]
	v_mfma_f32_16x16x32_bf16 v[68:71], v[156:159], v[196:199], v[68:71]
	v_mfma_f32_16x16x32_bf16 v[64:67], v[164:167], v[196:199], v[64:67]
	v_mfma_f32_16x16x32_bf16 v[56:59], v[156:159], v[204:207], v[56:59]
	v_mfma_f32_16x16x32_bf16 v[52:55], v[164:167], v[204:207], v[52:55]
	v_mfma_f32_16x16x32_bf16 v[44:47], v[156:159], v[212:215], v[44:47]
	v_mfma_f32_16x16x32_bf16 v[40:43], v[164:167], v[212:215], v[40:43]
	s_setprio 0
	s_setprio 2
	v_mfma_f32_16x16x32_bf16 v[124:127], v[168:171], v[184:187], v[124:127]
	v_mfma_f32_16x16x32_bf16 v[120:123], v[176:179], v[184:187], v[120:123]
	v_mfma_f32_16x16x32_bf16 v[116:119], v[168:171], v[192:195], v[116:119]
	v_mfma_f32_16x16x32_bf16 v[112:115], v[176:179], v[192:195], v[112:115]
	v_mfma_f32_16x16x32_bf16 v[108:111], v[168:171], v[200:203], v[108:111]
	v_mfma_f32_16x16x32_bf16 v[104:107], v[176:179], v[200:203], v[104:107]
	v_mfma_f32_16x16x32_bf16 v[100:103], v[168:171], v[208:211], v[100:103]
	v_mfma_f32_16x16x32_bf16 v[96:99], v[176:179], v[208:211], v[96:99]
	v_mfma_f32_16x16x32_bf16 v[124:127], v[172:175], v[188:191], v[124:127]
	v_mfma_f32_16x16x32_bf16 v[120:123], v[180:183], v[188:191], v[120:123]
	v_mfma_f32_16x16x32_bf16 v[116:119], v[172:175], v[196:199], v[116:119]
	v_mfma_f32_16x16x32_bf16 v[112:115], v[180:183], v[196:199], v[112:115]
	v_mfma_f32_16x16x32_bf16 v[108:111], v[172:175], v[204:207], v[108:111]
	v_mfma_f32_16x16x32_bf16 v[104:107], v[180:183], v[204:207], v[104:107]
	v_mfma_f32_16x16x32_bf16 v[100:103], v[172:175], v[212:215], v[100:103]
	s_setprio 3
	s_barrier
	v_mfma_f32_16x16x32_bf16 v[96:99], v[180:183], v[212:215], v[96:99]
	s_setprio 0
	s_add_i32 s90, s77, s69
	v_lshl_add_u64 v[216:217], s[60:61], 0, v[130:131]
	s_mov_b32 m0, s90
	ds_read_b128 v[184:187], v154 offset:16384
	ds_read_b128 v[188:191], v154 offset:17408
	ds_read_b128 v[192:195], v154 offset:18432
	ds_read_b128 v[196:199], v154 offset:19456
	ds_read_b128 v[200:203], v154 offset:20480
	ds_read_b128 v[204:207], v154 offset:21504
	ds_read_b128 v[208:211], v154 offset:22528
	ds_read_b128 v[212:215], v154 offset:23552
	global_load_lds_dwordx4 v[216:217], off
	s_add_i32 m0, s90, 0x2000
	s_add_u32 s90, s60, 0x100000
	v_lshl_add_u64 v[218:219], s[60:61], 0, v[134:135]
	s_addc_u32 s91, s61, 0
	s_add_i32 s92, s78, s69
	global_load_lds_dwordx4 v[218:219], off
	v_lshl_add_u64 v[220:221], s[90:91], 0, v[130:131]
	s_mov_b32 m0, s92
	v_lshl_add_u64 v[222:223], s[62:63], 0, v[132:133]
	global_load_lds_dwordx4 v[220:221], off
	v_lshl_add_u64 v[220:221], s[90:91], 0, v[134:135]
	s_add_i32 m0, s92, 0x2000
	s_nop 0
	global_load_lds_dwordx4 v[220:221], off
	v_lshl_add_u64 v[220:221], s[62:63], 0, v[128:129]
	s_mov_b32 m0, s70
	s_nop 0
	global_load_lds_dwordx4 v[220:221], off
	s_mov_b32 m0, s71
	s_nop 0
	global_load_lds_dwordx4 v[222:223], off
	s_waitcnt vmcnt(8)
	s_waitcnt lgkmcnt(0)
	s_barrier
; #define PG8_STAGE(bufoff, gbase, voff) do { _Pragma("unroll") for (int _i = 0; _i < 2; ++_i) \
;         __builtin_amdgcn_global_load_lds((const unsigned*)((const char*)(gbase) + (voff)[_i]), (PG8_LAS unsigned*)(lds + (bufoff) + ldsw + _i * 8192), 16, 0, 0); } while (0)
; #define PG8_LDA(dst, b, h) do { _Pragma("unroll") for (int m = 0; m < 4; ++m) _Pragma("unroll") for (int k = 0; k < 2; ++k) dst[m][k] = *(const PG8_LAS bf16x8*)(lds + PG8_SA(b, h) + aoff + m * 2048 + k * 1024); } while (0)
; #define PG8_LDB(dst, b, h) do { _Pragma("unroll") for (int n = 0; n < 2; ++n) _Pragma("unroll") for (int k = 0; k < 2; ++k) dst[n][k] = *(const PG8_LAS bf16x8*)(lds + PG8_SB(b, h) + boff + n * 2048 + k * 1024); } while (0)
; #define PG8_MMA(ai, bj, At, Bt) do { __builtin_amdgcn_s_setprio(1); _Pragma("unroll") for (int m = 0; m < 4; ++m) _Pragma("unroll") for (int n = 0; n < 2; ++n) _Pragma("unroll") for (int k = 0; k < 2; ++k) \
;         acc[ai][bj][m][n] = __builtin_amdgcn_mfma_f32_16x16x32_bf16(Bt[n][k], At[m][k], acc[ai][bj][m][n], 0, 0, 0); __builtin_amdgcn_s_setprio(0); } while (0)
; #define PG8_WAIT_V(n) asm volatile("s_waitcnt vmcnt(" #n ")" ::: "memory")
; #define PG8_WAIT_L(n) asm volatile("s_waitcnt lgkmcnt(" #n ")" ::: "memory")
; #define PG8_BAR __builtin_amdgcn_s_barrier()
; #define PG8_SCHED __builtin_amdgcn_sched_barrier(0)
; template <class Epi, class Sched, bool ALIGN_EPI = false, bool SP2 = false>
; __device__ __forceinline__ void gemm_phase(PG8_LAS unsigned char* lds, const Gemm g, const Sched& S, const Epi& E, const int wv  ) {
;     ...
;             PG8_WAIT_V(8); PG8_WAIT_L(0); PG8_BAR; PG8_MMA(1, 0, At, B0); PG8_MMA(1, 1, At, B1); PG8_BAR; PG8_SCHED;
;             PG8_LDB(B0, 1, 0); PG8_LDB(B1, 1, 1); PG8_SCHED; PG8_LDA(At, 1, 0); PG8_STAGE(PG8_SA(0, 1), a2 + hstepA, voffA);
;             PG8_WAIT_V(8); PG8_WAIT_L(0); PG8_BAR; PG8_MMA(0, 0, At, B0); PG8_MMA(0, 1, At, B1); PG8_BAR; PG8_SCHED;
	s_setprio 2
	s_waitcnt lgkmcnt(0)
	v_mfma_f32_16x16x32_bf16 v[28:31], v[146:149], v[184:187], v[28:31]
	v_mfma_f32_16x16x32_bf16 v[24:27], v[160:163], v[184:187], v[24:27]
	v_mfma_f32_16x16x32_bf16 v[20:23], v[146:149], v[192:195], v[20:23]
	v_mfma_f32_16x16x32_bf16 v[16:19], v[160:163], v[192:195], v[16:19]
	v_mfma_f32_16x16x32_bf16 v[12:15], v[146:149], v[200:203], v[12:15]
	v_mfma_f32_16x16x32_bf16 v[8:11], v[160:163], v[200:203], v[8:11]
	v_mfma_f32_16x16x32_bf16 v[4:7], v[146:149], v[208:211], v[4:7]
	v_mfma_f32_16x16x32_bf16 v[0:3], v[160:163], v[208:211], v[0:3]
	v_mfma_f32_16x16x32_bf16 v[28:31], v[156:159], v[188:191], v[28:31]
	v_mfma_f32_16x16x32_bf16 v[24:27], v[164:167], v[188:191], v[24:27]
	v_mfma_f32_16x16x32_bf16 v[20:23], v[156:159], v[196:199], v[20:23]
	v_mfma_f32_16x16x32_bf16 v[16:19], v[164:167], v[196:199], v[16:19]
	v_mfma_f32_16x16x32_bf16 v[12:15], v[156:159], v[204:207], v[12:15]
	v_mfma_f32_16x16x32_bf16 v[8:11], v[164:167], v[204:207], v[8:11]
	v_mfma_f32_16x16x32_bf16 v[4:7], v[156:159], v[212:215], v[4:7]
	v_mfma_f32_16x16x32_bf16 v[0:3], v[164:167], v[212:215], v[0:3]
	s_setprio 0
	s_setprio 2
	v_mfma_f32_16x16x32_bf16 v[92:95], v[168:171], v[184:187], v[92:95]
	v_mfma_f32_16x16x32_bf16 v[88:91], v[176:179], v[184:187], v[88:91]
	v_mfma_f32_16x16x32_bf16 v[84:87], v[168:171], v[192:195], v[84:87]
	v_mfma_f32_16x16x32_bf16 v[80:83], v[176:179], v[192:195], v[80:83]
	v_mfma_f32_16x16x32_bf16 v[60:63], v[168:171], v[200:203], v[60:63]
	v_mfma_f32_16x16x32_bf16 v[48:51], v[176:179], v[200:203], v[48:51]
	v_mfma_f32_16x16x32_bf16 v[36:39], v[168:171], v[208:211], v[36:39]
	v_mfma_f32_16x16x32_bf16 v[32:35], v[176:179], v[208:211], v[32:35]
	v_mfma_f32_16x16x32_bf16 v[92:95], v[172:175], v[188:191], v[92:95]
	v_mfma_f32_16x16x32_bf16 v[88:91], v[180:183], v[188:191], v[88:91]
	v_mfma_f32_16x16x32_bf16 v[84:87], v[172:175], v[196:199], v[84:87]
	v_mfma_f32_16x16x32_bf16 v[80:83], v[180:183], v[196:199], v[80:83]
	v_mfma_f32_16x16x32_bf16 v[60:63], v[172:175], v[204:207], v[60:63]
	v_mfma_f32_16x16x32_bf16 v[48:51], v[180:183], v[204:207], v[48:51]
	v_mfma_f32_16x16x32_bf16 v[36:39], v[172:175], v[212:215], v[36:39]
	s_setprio 3
	s_barrier
	v_mfma_f32_16x16x32_bf16 v[32:35], v[180:183], v[212:215], v[32:35]
	s_setprio 0
	s_add_i32 s90, 0, 0x18000
	v_add_u32_e32 v155, s90, v150
	s_add_i32 s91, 0, 0x1c000
	ds_read_b128 v[146:149], v155
	ds_read_b128 v[156:159], v155 offset:1024
	ds_read_b128 v[160:163], v155 offset:2048
	ds_read_b128 v[164:167], v155 offset:3072
	v_add_u32_e32 v155, s91, v150
	ds_read_b128 v[168:171], v155
	ds_read_b128 v[172:175], v155 offset:1024
	ds_read_b128 v[176:179], v155 offset:2048
	ds_read_b128 v[180:183], v155 offset:3072
	s_add_u32 s62, s62, 0x100000
	s_addc_u32 s63, s63, 0
	s_mov_b32 m0, s72
	v_lshl_add_u64 v[224:225], s[62:63], 0, v[128:129]
	ds_read_b128 v[184:187], v154 offset:32768
	ds_read_b128 v[188:191], v154 offset:33792
	ds_read_b128 v[192:195], v154 offset:34816
	ds_read_b128 v[196:199], v154 offset:35840
	ds_read_b128 v[200:203], v154 offset:36864
	ds_read_b128 v[204:207], v154 offset:37888
	ds_read_b128 v[208:211], v154 offset:38912
	ds_read_b128 v[212:215], v154 offset:39936
	global_load_lds_dwordx4 v[224:225], off
	v_lshl_add_u64 v[224:225], s[62:63], 0, v[132:133]
	s_mov_b32 m0, s73
	s_nop 0
	global_load_lds_dwordx4 v[224:225], off
	s_waitcnt vmcnt(8)
	s_waitcnt lgkmcnt(0)
	s_barrier
	s_setprio 2
	s_waitcnt lgkmcnt(0)
	v_mfma_f32_16x16x32_bf16 v[76:79], v[146:149], v[184:187], v[76:79]
	v_mfma_f32_16x16x32_bf16 v[72:75], v[160:163], v[184:187], v[72:75]
	v_mfma_f32_16x16x32_bf16 v[68:71], v[146:149], v[192:195], v[68:71]
	v_mfma_f32_16x16x32_bf16 v[64:67], v[160:163], v[192:195], v[64:67]
	v_mfma_f32_16x16x32_bf16 v[56:59], v[146:149], v[200:203], v[56:59]
	v_mfma_f32_16x16x32_bf16 v[52:55], v[160:163], v[200:203], v[52:55]
	v_mfma_f32_16x16x32_bf16 v[44:47], v[146:149], v[208:211], v[44:47]
	v_mfma_f32_16x16x32_bf16 v[40:43], v[160:163], v[208:211], v[40:43]
	v_mfma_f32_16x16x32_bf16 v[76:79], v[156:159], v[188:191], v[76:79]
	v_mfma_f32_16x16x32_bf16 v[72:75], v[164:167], v[188:191], v[72:75]
	v_mfma_f32_16x16x32_bf16 v[68:71], v[156:159], v[196:199], v[68:71]
	v_mfma_f32_16x16x32_bf16 v[64:67], v[164:167], v[196:199], v[64:67]
	v_mfma_f32_16x16x32_bf16 v[56:59], v[156:159], v[204:207], v[56:59]
	v_mfma_f32_16x16x32_bf16 v[52:55], v[164:167], v[204:207], v[52:55]
	v_mfma_f32_16x16x32_bf16 v[44:47], v[156:159], v[212:215], v[44:47]
	v_mfma_f32_16x16x32_bf16 v[40:43], v[164:167], v[212:215], v[40:43]
	s_setprio 0
	s_setprio 2
	v_mfma_f32_16x16x32_bf16 v[124:127], v[168:171], v[184:187], v[124:127]
	v_mfma_f32_16x16x32_bf16 v[120:123], v[176:179], v[184:187], v[120:123]
	v_mfma_f32_16x16x32_bf16 v[116:119], v[168:171], v[192:195], v[116:119]
	v_mfma_f32_16x16x32_bf16 v[112:115], v[176:179], v[192:195], v[112:115]
	v_mfma_f32_16x16x32_bf16 v[108:111], v[168:171], v[200:203], v[108:111]
	v_mfma_f32_16x16x32_bf16 v[104:107], v[176:179], v[200:203], v[104:107]
	v_mfma_f32_16x16x32_bf16 v[100:103], v[168:171], v[208:211], v[100:103]
	v_mfma_f32_16x16x32_bf16 v[96:99], v[176:179], v[208:211], v[96:99]
	v_mfma_f32_16x16x32_bf16 v[124:127], v[172:175], v[188:191], v[124:127]
	v_mfma_f32_16x16x32_bf16 v[120:123], v[180:183], v[188:191], v[120:123]
	v_mfma_f32_16x16x32_bf16 v[116:119], v[172:175], v[196:199], v[116:119]
	v_mfma_f32_16x16x32_bf16 v[112:115], v[180:183], v[196:199], v[112:115]
	v_mfma_f32_16x16x32_bf16 v[108:111], v[172:175], v[204:207], v[108:111]
	v_mfma_f32_16x16x32_bf16 v[104:107], v[180:183], v[204:207], v[104:107]
	v_mfma_f32_16x16x32_bf16 v[100:103], v[172:175], v[212:215], v[100:103]
	s_setprio 3
	s_barrier
; #define PG8_STAGE(bufoff, gbase, voff) do { _Pragma("unroll") for (int _i = 0; _i < 2; ++_i) \
;         __builtin_amdgcn_global_load_lds((const unsigned*)((const char*)(gbase) + (voff)[_i]), (PG8_LAS unsigned*)(lds + (bufoff) + ldsw + _i * 8192), 16, 0, 0); } while (0)
; #define PG8_LDA(dst, b, h) do { _Pragma("unroll") for (int m = 0; m < 4; ++m) _Pragma("unroll") for (int k = 0; k < 2; ++k) dst[m][k] = *(const PG8_LAS bf16x8*)(lds + PG8_SA(b, h) + aoff + m * 2048 + k * 1024); } while (0)
; #define PG8_MMA(ai, bj, At, Bt) do { __builtin_amdgcn_s_setprio(1); _Pragma("unroll") for (int m = 0; m < 4; ++m) _Pragma("unroll") for (int n = 0; n < 2; ++n) _Pragma("unroll") for (int k = 0; k < 2; ++k) \
;         acc[ai][bj][m][n] = __builtin_amdgcn_mfma_f32_16x16x32_bf16(Bt[n][k], At[m][k], acc[ai][bj][m][n], 0, 0, 0); __builtin_amdgcn_s_setprio(0); } while (0)
; #define PG8_WAIT_V(n) asm volatile("s_waitcnt vmcnt(" #n ")" ::: "memory")
; #define PG8_WAIT_L(n) asm volatile("s_waitcnt lgkmcnt(" #n ")" ::: "memory")
; #define PG8_BAR __builtin_amdgcn_s_barrier()
; #define PG8_SCHED __builtin_amdgcn_sched_barrier(0)
; template <class Epi, class Sched, bool ALIGN_EPI = false, bool SP2 = false>
; __device__ __forceinline__ void gemm_phase(PG8_LAS unsigned char* lds, const Gemm g, const Sched& S, const Epi& E, const int wv  ) {
;     ...
;             PG8_LDA(At, 1, 1); PG8_STAGE(PG8_SB(1, 0), b3, voffB); PG8_STAGE(PG8_SB(1, 1), b3 + hstepB, voffB); PG8_STAGE(PG8_SA(1, 0), a3, voffA);
;             PG8_WAIT_V(8); PG8_WAIT_L(0); PG8_BAR; PG8_MMA(1, 0, At, B0); PG8_MMA(1, 1, At, B1); PG8_BAR; PG8_SCHED;
;     ...
;         if constexpr (ALIGN_EPI) { if (wr == 0) PG8_BAR; }
	v_mfma_f32_16x16x32_bf16 v[96:99], v[180:183], v[212:215], v[96:99]
	s_setprio 0
	s_add_i32 s62, s90, s69
	v_lshl_add_u64 v[216:217], v[216:217], 0, s[10:11]
	s_mov_b32 m0, s62
	ds_read_b128 v[184:187], v154 offset:49152
	ds_read_b128 v[188:191], v154 offset:50176
	ds_read_b128 v[192:195], v154 offset:51200
	ds_read_b128 v[196:199], v154 offset:52224
	ds_read_b128 v[200:203], v154 offset:53248
	ds_read_b128 v[204:207], v154 offset:54272
	ds_read_b128 v[208:211], v154 offset:55296
	ds_read_b128 v[212:215], v154 offset:56320
	global_load_lds_dwordx4 v[216:217], off
	s_add_i32 m0, s62, 0x2000
	s_add_u32 s60, s60, 0x100080
	v_lshl_add_u64 v[216:217], v[218:219], 0, s[10:11]
	s_addc_u32 s61, s61, 0
	s_add_i32 s62, s91, s69
	global_load_lds_dwordx4 v[216:217], off
	v_lshl_add_u64 v[216:217], s[60:61], 0, v[130:131]
	s_mov_b32 m0, s62
	s_nop 0
	global_load_lds_dwordx4 v[216:217], off
	v_lshl_add_u64 v[216:217], s[60:61], 0, v[134:135]
	s_add_i32 m0, s62, 0x2000
	s_nop 0
	global_load_lds_dwordx4 v[216:217], off
	v_lshl_add_u64 v[216:217], v[220:221], 0, s[10:11]
	s_mov_b32 m0, s64
	s_nop 0
	global_load_lds_dwordx4 v[216:217], off
	v_lshl_add_u64 v[216:217], v[222:223], 0, s[10:11]
	s_mov_b32 m0, s65
	s_nop 0
	global_load_lds_dwordx4 v[216:217], off
	s_waitcnt vmcnt(8)
	s_waitcnt lgkmcnt(0)
	s_barrier
	s_setprio 2
	s_waitcnt lgkmcnt(0)
	v_mfma_f32_16x16x32_bf16 v[28:31], v[146:149], v[184:187], v[28:31]
	v_mfma_f32_16x16x32_bf16 v[24:27], v[160:163], v[184:187], v[24:27]
	v_mfma_f32_16x16x32_bf16 v[20:23], v[146:149], v[192:195], v[20:23]
	v_mfma_f32_16x16x32_bf16 v[16:19], v[160:163], v[192:195], v[16:19]
	v_mfma_f32_16x16x32_bf16 v[12:15], v[146:149], v[200:203], v[12:15]
	v_mfma_f32_16x16x32_bf16 v[8:11], v[160:163], v[200:203], v[8:11]
	v_mfma_f32_16x16x32_bf16 v[4:7], v[146:149], v[208:211], v[4:7]
	v_mfma_f32_16x16x32_bf16 v[0:3], v[160:163], v[208:211], v[0:3]
	v_mfma_f32_16x16x32_bf16 v[28:31], v[156:159], v[188:191], v[28:31]
	v_mfma_f32_16x16x32_bf16 v[24:27], v[164:167], v[188:191], v[24:27]
	v_mfma_f32_16x16x32_bf16 v[20:23], v[156:159], v[196:199], v[20:23]
	v_mfma_f32_16x16x32_bf16 v[16:19], v[164:167], v[196:199], v[16:19]
	v_mfma_f32_16x16x32_bf16 v[12:15], v[156:159], v[204:207], v[12:15]
	v_mfma_f32_16x16x32_bf16 v[8:11], v[164:167], v[204:207], v[8:11]
	v_mfma_f32_16x16x32_bf16 v[4:7], v[156:159], v[212:215], v[4:7]
	v_mfma_f32_16x16x32_bf16 v[0:3], v[164:167], v[212:215], v[0:3]
	s_setprio 0
	s_setprio 2
	v_mfma_f32_16x16x32_bf16 v[92:95], v[168:171], v[184:187], v[92:95]
	v_mfma_f32_16x16x32_bf16 v[88:91], v[176:179], v[184:187], v[88:91]
	v_mfma_f32_16x16x32_bf16 v[84:87], v[168:171], v[192:195], v[84:87]
	v_mfma_f32_16x16x32_bf16 v[80:83], v[176:179], v[192:195], v[80:83]
	v_mfma_f32_16x16x32_bf16 v[60:63], v[168:171], v[200:203], v[60:63]
	v_mfma_f32_16x16x32_bf16 v[48:51], v[176:179], v[200:203], v[48:51]
	v_mfma_f32_16x16x32_bf16 v[36:39], v[168:171], v[208:211], v[36:39]
	v_mfma_f32_16x16x32_bf16 v[32:35], v[176:179], v[208:211], v[32:35]
	v_mfma_f32_16x16x32_bf16 v[92:95], v[172:175], v[188:191], v[92:95]
	v_mfma_f32_16x16x32_bf16 v[88:91], v[180:183], v[188:191], v[88:91]
	v_mfma_f32_16x16x32_bf16 v[84:87], v[172:175], v[196:199], v[84:87]
	v_mfma_f32_16x16x32_bf16 v[80:83], v[180:183], v[196:199], v[80:83]
	v_mfma_f32_16x16x32_bf16 v[60:63], v[172:175], v[204:207], v[60:63]
	v_mfma_f32_16x16x32_bf16 v[48:51], v[180:183], v[204:207], v[48:51]
	v_mfma_f32_16x16x32_bf16 v[36:39], v[172:175], v[212:215], v[36:39]
	s_setprio 3
	s_barrier
	v_mfma_f32_16x16x32_bf16 v[32:35], v[180:183], v[212:215], v[32:35]
	s_setprio 0
	s_add_i32 s87, s87, 2
	s_add_u32 s58, s58, 0x100
	s_addc_u32 s59, s59, 0
	s_add_u32 s85, s85, 0x100
	s_addc_u32 s86, s86, 0
	s_cmp_gt_u32 s87, 61
	s_cbranch_scc0 .LBB0_1717
	s_and_b64 vcc, exec, s[12:13]
	s_cbranch_vccz .LBB0_1720
	s_barrier

; #define PG8_STAGE(bufoff, gbase, voff) do { _Pragma("unroll") for (int _i = 0; _i < 2; ++_i) \
;         __builtin_amdgcn_global_load_lds((const unsigned*)((const char*)(gbase) + (voff)[_i]), (PG8_LAS unsigned*)(lds + (bufoff) + ldsw + _i * 8192), 16, 0, 0); } while (0)
; #define PG8_LDA(dst, b, h) do { _Pragma("unroll") for (int m = 0; m < 4; ++m) _Pragma("unroll") for (int k = 0; k < 2; ++k) dst[m][k] = *(const PG8_LAS bf16x8*)(lds + PG8_SA(b, h) + aoff + m * 2048 + k * 1024); } while (0)
; #define PG8_LDB(dst, b, h) do { _Pragma("unroll") for (int n = 0; n < 2; ++n) _Pragma("unroll") for (int k = 0; k < 2; ++k) dst[n][k] = *(const PG8_LAS bf16x8*)(lds + PG8_SB(b, h) + boff + n * 2048 + k * 1024); } while (0)
; #define PG8_MMA(ai, bj, At, Bt) do { __builtin_amdgcn_s_setprio(1); _Pragma("unroll") for (int m = 0; m < 4; ++m) _Pragma("unroll") for (int n = 0; n < 2; ++n) _Pragma("unroll") for (int k = 0; k < 2; ++k) \
;         acc[ai][bj][m][n] = __builtin_amdgcn_mfma_f32_16x16x32_bf16(Bt[n][k], At[m][k], acc[ai][bj][m][n], 0, 0, 0); __builtin_amdgcn_s_setprio(0); } while (0)
; #define PG8_WAIT_V(n) asm volatile("s_waitcnt vmcnt(" #n ")" ::: "memory")
; #define PG8_WAIT_L(n) asm volatile("s_waitcnt lgkmcnt(" #n ")" ::: "memory")
; #define PG8_BAR __builtin_amdgcn_s_barrier()
; #define PG8_SCHED __builtin_amdgcn_sched_barrier(0)
; template <class Epi, class Sched, bool ALIGN_EPI = false, bool SP2 = false>
; __device__ __forceinline__ void gemm_phase(PG8_LAS unsigned char* lds, const Gemm g, const Sched& S, const Epi& E, const int wv  ) {
;     ...
;             const bool last = (t == nt - 2);
;             const char* a1 = cA + (size_t)(t + 1) * kstep;
;             const char* a2 = last ? nA : cA + (size_t)(t + 2) * kstep; const char* b2 = last ? nB : cB + (size_t)(t + 2) * kstep;
;             const char* a3 = a2 + kstep; const char* b3 = b2 + kstep;
;             if (last && has_next) S.a_ready(nxt);
;             if constexpr (SP2) {
;             PG8_LDB(B0, 0, 0); PG8_LDB(B1, 0, 1); PG8_SCHED; PG8_LDA(At, 0, 0); PG8_STAGE(PG8_SA(1, 1), a1 + hstepA, voffA);
;             PG8_WAIT_V(8); PG8_WAIT_L(0); PG8_BAR; PG8_MMA(0, 0, At, B0); PG8_MMA(0, 1, At, B1); PG8_BAR; PG8_SCHED;
;             PG8_LDA(At, 0, 1); PG8_STAGE(PG8_SB(0, 0), b2, voffB); PG8_STAGE(PG8_SB(0, 1), b2 + hstepB, voffB); PG8_STAGE(PG8_SA(0, 0), a2, voffA);
.LBB0_2399:
	ds_read_b128 v[44:47], v196
	ds_read_b128 v[48:51], v196 offset:1024
	ds_read_b128 v[52:55], v196 offset:2048
	ds_read_b128 v[56:59], v196 offset:3072
	ds_read_b128 v[60:63], v197
	ds_read_b128 v[68:71], v197 offset:1024
	ds_read_b128 v[72:75], v197 offset:2048
	ds_read_b128 v[76:79], v197 offset:3072
	s_add_u32 s68, s66, 0xfff00080
	s_addc_u32 s69, s67, -1
	s_cmp_eq_u32 s94, 60
	s_cselect_b32 s71, s57, s69
	s_cselect_b32 s70, s63, s68
	s_cselect_b32 s69, s55, s93
	s_cselect_b32 s68, s65, s92
	v_lshl_add_u64 v[224:225], s[66:67], 0, v[172:173]
	s_add_i32 m0, s75, 0xc000
	ds_read_b128 v[180:183], v198
	ds_read_b128 v[184:187], v198 offset:1024
	ds_read_b128 v[200:203], v198 offset:2048
	ds_read_b128 v[204:207], v198 offset:3072
	ds_read_b128 v[208:211], v198 offset:4096
	ds_read_b128 v[212:215], v198 offset:5120
	ds_read_b128 v[216:219], v198 offset:6144
	ds_read_b128 v[220:223], v198 offset:7168
	global_load_lds_dwordx4 v[224:225], off
	v_lshl_add_u64 v[224:225], s[66:67], 0, v[174:175]
	s_add_i32 m0, s75, 0xe000
	s_nop 0
	global_load_lds_dwordx4 v[224:225], off
	s_waitcnt vmcnt(8)
	s_waitcnt lgkmcnt(0)
	s_barrier
	s_setprio 2
	s_waitcnt lgkmcnt(0)
	v_mfma_f32_16x16x32_bf16 v[104:107], v[44:47], v[180:183], v[104:107]
	v_mfma_f32_16x16x32_bf16 v[100:103], v[52:55], v[180:183], v[100:103]
	v_mfma_f32_16x16x32_bf16 v[156:159], v[44:47], v[200:203], v[156:159]
	v_mfma_f32_16x16x32_bf16 v[148:151], v[52:55], v[200:203], v[148:151]
	v_mfma_f32_16x16x32_bf16 v[140:143], v[44:47], v[208:211], v[140:143]
	v_mfma_f32_16x16x32_bf16 v[132:135], v[52:55], v[208:211], v[132:135]
	v_mfma_f32_16x16x32_bf16 v[124:127], v[44:47], v[216:219], v[124:127]
	v_mfma_f32_16x16x32_bf16 v[120:123], v[52:55], v[216:219], v[120:123]
	v_mfma_f32_16x16x32_bf16 v[104:107], v[48:51], v[184:187], v[104:107]
	v_mfma_f32_16x16x32_bf16 v[100:103], v[56:59], v[184:187], v[100:103]
	v_mfma_f32_16x16x32_bf16 v[156:159], v[48:51], v[204:207], v[156:159]
	v_mfma_f32_16x16x32_bf16 v[148:151], v[56:59], v[204:207], v[148:151]
	v_mfma_f32_16x16x32_bf16 v[140:143], v[48:51], v[212:215], v[140:143]
	v_mfma_f32_16x16x32_bf16 v[132:135], v[56:59], v[212:215], v[132:135]
	v_mfma_f32_16x16x32_bf16 v[124:127], v[48:51], v[220:223], v[124:127]
	v_mfma_f32_16x16x32_bf16 v[120:123], v[56:59], v[220:223], v[120:123]
	s_setprio 0
	s_setprio 2
	v_mfma_f32_16x16x32_bf16 v[92:95], v[60:63], v[180:183], v[92:95]
	v_mfma_f32_16x16x32_bf16 v[88:91], v[72:75], v[180:183], v[88:91]
	v_mfma_f32_16x16x32_bf16 v[152:155], v[60:63], v[200:203], v[152:155]
	v_mfma_f32_16x16x32_bf16 v[144:147], v[72:75], v[200:203], v[144:147]
	v_mfma_f32_16x16x32_bf16 v[136:139], v[60:63], v[208:211], v[136:139]
	v_mfma_f32_16x16x32_bf16 v[128:131], v[72:75], v[208:211], v[128:131]
	v_mfma_f32_16x16x32_bf16 v[116:119], v[60:63], v[216:219], v[116:119]
	v_mfma_f32_16x16x32_bf16 v[112:115], v[72:75], v[216:219], v[112:115]
	v_mfma_f32_16x16x32_bf16 v[92:95], v[68:71], v[184:187], v[92:95]
	v_mfma_f32_16x16x32_bf16 v[88:91], v[76:79], v[184:187], v[88:91]
	v_mfma_f32_16x16x32_bf16 v[152:155], v[68:71], v[204:207], v[152:155]
	v_mfma_f32_16x16x32_bf16 v[144:147], v[76:79], v[204:207], v[144:147]
	v_mfma_f32_16x16x32_bf16 v[136:139], v[68:71], v[212:215], v[136:139]
	v_mfma_f32_16x16x32_bf16 v[128:131], v[76:79], v[212:215], v[128:131]
	v_mfma_f32_16x16x32_bf16 v[116:119], v[68:71], v[220:223], v[116:119]
	s_setprio 3
	s_barrier
	v_mfma_f32_16x16x32_bf16 v[112:115], v[76:79], v[220:223], v[112:115]
	s_setprio 0
	s_add_i32 s95, s87, s74
	v_lshl_add_u64 v[228:229], s[68:69], 0, v[162:163]
	s_mov_b32 m0, s95
	ds_read_b128 v[180:183], v198 offset:16384
	ds_read_b128 v[184:187], v198 offset:17408
	ds_read_b128 v[200:203], v198 offset:18432
	ds_read_b128 v[204:207], v198 offset:19456
	ds_read_b128 v[208:211], v198 offset:20480
	ds_read_b128 v[212:215], v198 offset:21504
	ds_read_b128 v[216:219], v198 offset:22528
	ds_read_b128 v[220:223], v198 offset:23552
	global_load_lds_dwordx4 v[228:229], off
	s_add_i32 m0, s95, 0x2000
	s_add_u32 s96, s68, 0x100000
	v_lshl_add_u64 v[230:231], s[68:69], 0, v[166:167]
	s_addc_u32 s97, s69, 0
	s_add_i32 s95, s90, s74
	global_load_lds_dwordx4 v[230:231], off
	v_lshl_add_u64 v[224:225], s[96:97], 0, v[162:163]
	s_mov_b32 m0, s95
	v_lshl_add_u64 v[232:233], s[70:71], 0, v[160:161]
	global_load_lds_dwordx4 v[224:225], off
	v_lshl_add_u64 v[224:225], s[96:97], 0, v[166:167]
	s_add_i32 m0, s95, 0x2000
	v_lshl_add_u64 v[234:235], s[70:71], 0, v[164:165]
	global_load_lds_dwordx4 v[224:225], off
	s_mov_b32 m0, s75
	s_nop 0
	global_load_lds_dwordx4 v[232:233], off
	s_mov_b32 m0, s76
	s_nop 0
	global_load_lds_dwordx4 v[234:235], off
	s_waitcnt vmcnt(8)
	s_waitcnt lgkmcnt(0)
	s_barrier
; #define PG8_STAGE(bufoff, gbase, voff) do { _Pragma("unroll") for (int _i = 0; _i < 2; ++_i) \
;         __builtin_amdgcn_global_load_lds((const unsigned*)((const char*)(gbase) + (voff)[_i]), (PG8_LAS unsigned*)(lds + (bufoff) + ldsw + _i * 8192), 16, 0, 0); } while (0)
; #define PG8_LDA(dst, b, h) do { _Pragma("unroll") for (int m = 0; m < 4; ++m) _Pragma("unroll") for (int k = 0; k < 2; ++k) dst[m][k] = *(const PG8_LAS bf16x8*)(lds + PG8_SA(b, h) + aoff + m * 2048 + k * 1024); } while (0)
; #define PG8_LDB(dst, b, h) do { _Pragma("unroll") for (int n = 0; n < 2; ++n) _Pragma("unroll") for (int k = 0; k < 2; ++k) dst[n][k] = *(const PG8_LAS bf16x8*)(lds + PG8_SB(b, h) + boff + n * 2048 + k * 1024); } while (0)
; #define PG8_MMA(ai, bj, At, Bt) do { __builtin_amdgcn_s_setprio(1); _Pragma("unroll") for (int m = 0; m < 4; ++m) _Pragma("unroll") for (int n = 0; n < 2; ++n) _Pragma("unroll") for (int k = 0; k < 2; ++k) \
;         acc[ai][bj][m][n] = __builtin_amdgcn_mfma_f32_16x16x32_bf16(Bt[n][k], At[m][k], acc[ai][bj][m][n], 0, 0, 0); __builtin_amdgcn_s_setprio(0); } while (0)
; #define PG8_WAIT_V(n) asm volatile("s_waitcnt vmcnt(" #n ")" ::: "memory")
; #define PG8_WAIT_L(n) asm volatile("s_waitcnt lgkmcnt(" #n ")" ::: "memory")
; #define PG8_BAR __builtin_amdgcn_s_barrier()
; #define PG8_SCHED __builtin_amdgcn_sched_barrier(0)
; template <class Epi, class Sched, bool ALIGN_EPI = false, bool SP2 = false>
; __device__ __forceinline__ void gemm_phase(PG8_LAS unsigned char* lds, const Gemm g, const Sched& S, const Epi& E, const int wv  ) {
;     ...
;             PG8_WAIT_V(8); PG8_WAIT_L(0); PG8_BAR; PG8_MMA(1, 0, At, B0); PG8_MMA(1, 1, At, B1); PG8_BAR; PG8_SCHED;
;             PG8_LDB(B0, 1, 0); PG8_LDB(B1, 1, 1); PG8_SCHED; PG8_LDA(At, 1, 0); PG8_STAGE(PG8_SA(0, 1), a2 + hstepA, voffA);
;             PG8_WAIT_V(8); PG8_WAIT_L(0); PG8_BAR; PG8_MMA(0, 0, At, B0); PG8_MMA(0, 1, At, B1); PG8_BAR; PG8_SCHED;
	s_setprio 2
	s_waitcnt lgkmcnt(0)
	v_mfma_f32_16x16x32_bf16 v[108:111], v[44:47], v[180:183], v[108:111]
	v_mfma_f32_16x16x32_bf16 v[96:99], v[52:55], v[180:183], v[96:99]
	v_mfma_f32_16x16x32_bf16 v[64:67], v[44:47], v[200:203], v[64:67]
	v_mfma_f32_16x16x32_bf16 v[36:39], v[52:55], v[200:203], v[36:39]
	v_mfma_f32_16x16x32_bf16 v[28:31], v[44:47], v[208:211], v[28:31]
	v_mfma_f32_16x16x32_bf16 v[20:23], v[52:55], v[208:211], v[20:23]
	v_mfma_f32_16x16x32_bf16 v[12:15], v[44:47], v[216:219], v[12:15]
	v_mfma_f32_16x16x32_bf16 v[4:7], v[52:55], v[216:219], v[4:7]
	v_mfma_f32_16x16x32_bf16 v[108:111], v[48:51], v[184:187], v[108:111]
	v_mfma_f32_16x16x32_bf16 v[96:99], v[56:59], v[184:187], v[96:99]
	v_mfma_f32_16x16x32_bf16 v[64:67], v[48:51], v[204:207], v[64:67]
	v_mfma_f32_16x16x32_bf16 v[36:39], v[56:59], v[204:207], v[36:39]
	v_mfma_f32_16x16x32_bf16 v[28:31], v[48:51], v[212:215], v[28:31]
	v_mfma_f32_16x16x32_bf16 v[20:23], v[56:59], v[212:215], v[20:23]
	v_mfma_f32_16x16x32_bf16 v[12:15], v[48:51], v[220:223], v[12:15]
	v_mfma_f32_16x16x32_bf16 v[4:7], v[56:59], v[220:223], v[4:7]
	s_setprio 0
	s_setprio 2
	v_mfma_f32_16x16x32_bf16 v[40:43], v[60:63], v[200:203], v[40:43]
	v_mfma_f32_16x16x32_bf16 v[32:35], v[72:75], v[200:203], v[32:35]
	v_mfma_f32_16x16x32_bf16 v[24:27], v[60:63], v[208:211], v[24:27]
	v_mfma_f32_16x16x32_bf16 v[16:19], v[72:75], v[208:211], v[16:19]
	v_mfma_f32_16x16x32_bf16 v[8:11], v[60:63], v[216:219], v[8:11]
	v_mfma_f32_16x16x32_bf16 v[0:3], v[72:75], v[216:219], v[0:3]
	v_mfma_f32_16x16x32_bf16 v[44:47], v[60:63], v[180:183], v[84:87]
	v_mfma_f32_16x16x32_bf16 v[48:51], v[72:75], v[180:183], v[80:83]
	v_mfma_f32_16x16x32_bf16 v[40:43], v[68:71], v[204:207], v[40:43]
	v_mfma_f32_16x16x32_bf16 v[32:35], v[76:79], v[204:207], v[32:35]
	v_mfma_f32_16x16x32_bf16 v[24:27], v[68:71], v[212:215], v[24:27]
	v_mfma_f32_16x16x32_bf16 v[16:19], v[76:79], v[212:215], v[16:19]
	v_mfma_f32_16x16x32_bf16 v[8:11], v[68:71], v[220:223], v[8:11]
	v_mfma_f32_16x16x32_bf16 v[0:3], v[76:79], v[220:223], v[0:3]
	v_mfma_f32_16x16x32_bf16 v[44:47], v[68:71], v[184:187], v[44:47]
	s_setprio 3
	s_barrier
	v_mfma_f32_16x16x32_bf16 v[48:51], v[76:79], v[184:187], v[48:51]
	s_setprio 0
	s_add_i32 s95, 0, 0x18000
	s_add_i32 s96, 0, 0x1c000
	v_add_u32_e32 v68, s95, v190
	v_add_u32_e32 v80, s96, v190
	ds_read_b128 v[52:55], v68
	ds_read_b128 v[56:59], v68 offset:1024
	ds_read_b128 v[60:63], v68 offset:2048
	ds_read_b128 v[68:71], v68 offset:3072
	ds_read_b128 v[72:75], v80
	ds_read_b128 v[76:79], v80 offset:1024
	ds_read_b128 v[180:183], v80 offset:2048
	ds_read_b128 v[184:187], v80 offset:3072
	s_add_u32 s70, s70, 0x100000
	s_addc_u32 s71, s71, 0
	s_mov_b32 m0, s77
	v_lshl_add_u64 v[224:225], s[70:71], 0, v[160:161]
	ds_read_b128 v[80:83], v198 offset:32768
	ds_read_b128 v[84:87], v198 offset:33792
	ds_read_b128 v[200:203], v198 offset:34816
	ds_read_b128 v[204:207], v198 offset:35840
	ds_read_b128 v[208:211], v198 offset:36864
	ds_read_b128 v[212:215], v198 offset:37888
	ds_read_b128 v[216:219], v198 offset:38912
	ds_read_b128 v[220:223], v198 offset:39936
	global_load_lds_dwordx4 v[224:225], off
	v_lshl_add_u64 v[224:225], s[70:71], 0, v[164:165]
	s_mov_b32 m0, s78
	s_nop 0
	global_load_lds_dwordx4 v[224:225], off
	s_waitcnt vmcnt(8)
	s_waitcnt lgkmcnt(0)
	s_barrier
	s_setprio 2
	s_waitcnt lgkmcnt(0)
	v_mfma_f32_16x16x32_bf16 v[104:107], v[52:55], v[80:83], v[104:107]
	v_mfma_f32_16x16x32_bf16 v[100:103], v[60:63], v[80:83], v[100:103]
	v_mfma_f32_16x16x32_bf16 v[156:159], v[52:55], v[200:203], v[156:159]
	v_mfma_f32_16x16x32_bf16 v[148:151], v[60:63], v[200:203], v[148:151]
	v_mfma_f32_16x16x32_bf16 v[140:143], v[52:55], v[208:211], v[140:143]
	v_mfma_f32_16x16x32_bf16 v[132:135], v[60:63], v[208:211], v[132:135]
	v_mfma_f32_16x16x32_bf16 v[124:127], v[52:55], v[216:219], v[124:127]
	v_mfma_f32_16x16x32_bf16 v[120:123], v[60:63], v[216:219], v[120:123]
	v_mfma_f32_16x16x32_bf16 v[104:107], v[56:59], v[84:87], v[104:107]
	v_mfma_f32_16x16x32_bf16 v[100:103], v[68:71], v[84:87], v[100:103]
	v_mfma_f32_16x16x32_bf16 v[156:159], v[56:59], v[204:207], v[156:159]
	v_mfma_f32_16x16x32_bf16 v[148:151], v[68:71], v[204:207], v[148:151]
	v_mfma_f32_16x16x32_bf16 v[140:143], v[56:59], v[212:215], v[140:143]
	v_mfma_f32_16x16x32_bf16 v[132:135], v[68:71], v[212:215], v[132:135]
	v_mfma_f32_16x16x32_bf16 v[124:127], v[56:59], v[220:223], v[124:127]
	v_mfma_f32_16x16x32_bf16 v[120:123], v[68:71], v[220:223], v[120:123]
	s_setprio 0
	s_setprio 2
	v_mfma_f32_16x16x32_bf16 v[92:95], v[72:75], v[80:83], v[92:95]
	v_mfma_f32_16x16x32_bf16 v[80:83], v[180:183], v[80:83], v[88:91]
	v_mfma_f32_16x16x32_bf16 v[88:91], v[184:187], v[84:87], v[80:83]
	v_mfma_f32_16x16x32_bf16 v[80:83], v[72:75], v[200:203], v[152:155]
	v_mfma_f32_16x16x32_bf16 v[152:155], v[76:79], v[204:207], v[80:83]
	v_mfma_f32_16x16x32_bf16 v[80:83], v[180:183], v[200:203], v[144:147]
	v_mfma_f32_16x16x32_bf16 v[144:147], v[184:187], v[204:207], v[80:83]
	v_mfma_f32_16x16x32_bf16 v[80:83], v[72:75], v[208:211], v[136:139]
	v_mfma_f32_16x16x32_bf16 v[136:139], v[76:79], v[212:215], v[80:83]
	v_mfma_f32_16x16x32_bf16 v[80:83], v[180:183], v[208:211], v[128:131]
	v_mfma_f32_16x16x32_bf16 v[128:131], v[184:187], v[212:215], v[80:83]
	v_mfma_f32_16x16x32_bf16 v[80:83], v[72:75], v[216:219], v[116:119]
	v_mfma_f32_16x16x32_bf16 v[116:119], v[76:79], v[220:223], v[80:83]
	v_mfma_f32_16x16x32_bf16 v[80:83], v[180:183], v[216:219], v[112:115]
	v_mfma_f32_16x16x32_bf16 v[92:95], v[76:79], v[84:87], v[92:95]
	s_setprio 3
	s_barrier
; #define PG8_STAGE(bufoff, gbase, voff) do { _Pragma("unroll") for (int _i = 0; _i < 2; ++_i) \
;         __builtin_amdgcn_global_load_lds((const unsigned*)((const char*)(gbase) + (voff)[_i]), (PG8_LAS unsigned*)(lds + (bufoff) + ldsw + _i * 8192), 16, 0, 0); } while (0)
; #define PG8_LDA(dst, b, h) do { _Pragma("unroll") for (int m = 0; m < 4; ++m) _Pragma("unroll") for (int k = 0; k < 2; ++k) dst[m][k] = *(const PG8_LAS bf16x8*)(lds + PG8_SA(b, h) + aoff + m * 2048 + k * 1024); } while (0)
; #define PG8_MMA(ai, bj, At, Bt) do { __builtin_amdgcn_s_setprio(1); _Pragma("unroll") for (int m = 0; m < 4; ++m) _Pragma("unroll") for (int n = 0; n < 2; ++n) _Pragma("unroll") for (int k = 0; k < 2; ++k) \
;         acc[ai][bj][m][n] = __builtin_amdgcn_mfma_f32_16x16x32_bf16(Bt[n][k], At[m][k], acc[ai][bj][m][n], 0, 0, 0); __builtin_amdgcn_s_setprio(0); } while (0)
; #define PG8_WAIT_V(n) asm volatile("s_waitcnt vmcnt(" #n ")" ::: "memory")
; #define PG8_WAIT_L(n) asm volatile("s_waitcnt lgkmcnt(" #n ")" ::: "memory")
; #define PG8_BAR __builtin_amdgcn_s_barrier()
; #define PG8_SCHED __builtin_amdgcn_sched_barrier(0)
; template <class Epi, class Sched, bool ALIGN_EPI = false, bool SP2 = false>
; __device__ __forceinline__ void gemm_phase(PG8_LAS unsigned char* lds, const Gemm g, const Sched& S, const Epi& E, const int wv  ) {
;     ...
;             PG8_LDA(At, 1, 1); PG8_STAGE(PG8_SB(1, 0), b3, voffB); PG8_STAGE(PG8_SB(1, 1), b3 + hstepB, voffB); PG8_STAGE(PG8_SA(1, 0), a3, voffA);
;             PG8_WAIT_V(8); PG8_WAIT_L(0); PG8_BAR; PG8_MMA(1, 0, At, B0); PG8_MMA(1, 1, At, B1); PG8_BAR; PG8_SCHED;
;     ...
;         if constexpr (ALIGN_EPI) { if (wr == 0) PG8_BAR; }
	v_mfma_f32_16x16x32_bf16 v[112:115], v[184:187], v[220:223], v[80:83]
	s_setprio 0
	s_add_i32 s70, s95, s74
	v_lshl_add_u64 v[84:85], v[228:229], 0, s[20:21]
	s_mov_b32 m0, s70
	s_nop 0
	ds_read_b128 v[80:83], v198 offset:49152
	ds_read_b128 v[200:203], v198 offset:50176
	ds_read_b128 v[204:207], v198 offset:51200
	ds_read_b128 v[208:211], v198 offset:52224
	ds_read_b128 v[212:215], v198 offset:53248
	ds_read_b128 v[216:219], v198 offset:54272
	ds_read_b128 v[220:223], v198 offset:55296
	ds_read_b128 v[224:227], v198 offset:56320
	global_load_lds_dwordx4 v[84:85], off
	s_add_i32 m0, s70, 0x2000
	s_add_u32 s68, s68, 0x100080
	v_lshl_add_u64 v[84:85], v[230:231], 0, s[20:21]
	s_addc_u32 s69, s69, 0
	s_add_i32 s70, s96, s74
	global_load_lds_dwordx4 v[84:85], off
	v_lshl_add_u64 v[84:85], s[68:69], 0, v[162:163]
	s_mov_b32 m0, s70
	s_nop 0
	global_load_lds_dwordx4 v[84:85], off
	v_lshl_add_u64 v[84:85], s[68:69], 0, v[166:167]
	s_add_i32 m0, s70, 0x2000
	s_nop 0
	global_load_lds_dwordx4 v[84:85], off
	v_lshl_add_u64 v[84:85], v[232:233], 0, s[20:21]
	s_mov_b32 m0, s82
	s_nop 0
	global_load_lds_dwordx4 v[84:85], off
	v_lshl_add_u64 v[84:85], v[234:235], 0, s[20:21]
	s_mov_b32 m0, s83
	s_nop 0
	global_load_lds_dwordx4 v[84:85], off
	s_waitcnt vmcnt(8)
	s_waitcnt lgkmcnt(0)
	s_barrier
	s_setprio 2
	s_waitcnt lgkmcnt(0)
	v_mfma_f32_16x16x32_bf16 v[84:87], v[52:55], v[80:83], v[108:111]
	v_mfma_f32_16x16x32_bf16 v[108:111], v[56:59], v[200:203], v[84:87]
	v_mfma_f32_16x16x32_bf16 v[84:87], v[60:63], v[80:83], v[96:99]
	v_mfma_f32_16x16x32_bf16 v[64:67], v[52:55], v[204:207], v[64:67]
	v_mfma_f32_16x16x32_bf16 v[36:39], v[60:63], v[204:207], v[36:39]
	v_mfma_f32_16x16x32_bf16 v[28:31], v[52:55], v[212:215], v[28:31]
	v_mfma_f32_16x16x32_bf16 v[20:23], v[60:63], v[212:215], v[20:23]
	v_mfma_f32_16x16x32_bf16 v[12:15], v[52:55], v[220:223], v[12:15]
	v_mfma_f32_16x16x32_bf16 v[4:7], v[60:63], v[220:223], v[4:7]
	v_mfma_f32_16x16x32_bf16 v[96:99], v[68:71], v[200:203], v[84:87]
	v_mfma_f32_16x16x32_bf16 v[64:67], v[56:59], v[208:211], v[64:67]
	v_mfma_f32_16x16x32_bf16 v[36:39], v[68:71], v[208:211], v[36:39]
	v_mfma_f32_16x16x32_bf16 v[28:31], v[56:59], v[216:219], v[28:31]
	v_mfma_f32_16x16x32_bf16 v[20:23], v[68:71], v[216:219], v[20:23]
	v_mfma_f32_16x16x32_bf16 v[12:15], v[56:59], v[224:227], v[12:15]
	v_mfma_f32_16x16x32_bf16 v[4:7], v[68:71], v[224:227], v[4:7]
	s_setprio 0
	s_setprio 2
	v_mfma_f32_16x16x32_bf16 v[44:47], v[72:75], v[80:83], v[44:47]
	v_mfma_f32_16x16x32_bf16 v[84:87], v[76:79], v[200:203], v[44:47]
	v_mfma_f32_16x16x32_bf16 v[44:47], v[180:183], v[80:83], v[48:51]
	v_mfma_f32_16x16x32_bf16 v[40:43], v[72:75], v[204:207], v[40:43]
	v_mfma_f32_16x16x32_bf16 v[32:35], v[180:183], v[204:207], v[32:35]
	v_mfma_f32_16x16x32_bf16 v[24:27], v[72:75], v[212:215], v[24:27]
	v_mfma_f32_16x16x32_bf16 v[16:19], v[180:183], v[212:215], v[16:19]
	v_mfma_f32_16x16x32_bf16 v[8:11], v[72:75], v[220:223], v[8:11]
	v_mfma_f32_16x16x32_bf16 v[0:3], v[180:183], v[220:223], v[0:3]
	v_mfma_f32_16x16x32_bf16 v[80:83], v[184:187], v[200:203], v[44:47]
	v_mfma_f32_16x16x32_bf16 v[40:43], v[76:79], v[208:211], v[40:43]
	v_mfma_f32_16x16x32_bf16 v[32:35], v[184:187], v[208:211], v[32:35]
	v_mfma_f32_16x16x32_bf16 v[24:27], v[76:79], v[216:219], v[24:27]
	v_mfma_f32_16x16x32_bf16 v[16:19], v[184:187], v[216:219], v[16:19]
	v_mfma_f32_16x16x32_bf16 v[8:11], v[76:79], v[224:227], v[8:11]
	s_setprio 3
	s_barrier
	v_mfma_f32_16x16x32_bf16 v[0:3], v[184:187], v[224:227], v[0:3]
	s_setprio 0
	s_add_i32 s94, s94, 2
	s_add_u32 s66, s66, 0x100
	s_addc_u32 s67, s67, 0
	s_add_u32 s92, s92, 0x100
	s_addc_u32 s93, s93, 0
	s_cmp_gt_u32 s94, 61
	s_cbranch_scc0 .LBB0_2399
	s_and_b64 vcc, exec, s[22:23]
	s_cbranch_vccz .LBB0_2402
	s_barrier

; #define PG8_STAGE(bufoff, gbase, voff) do { _Pragma("unroll") for (int _i = 0; _i < 2; ++_i) \
;         __builtin_amdgcn_global_load_lds((const unsigned*)((const char*)(gbase) + (voff)[_i]), (PG8_LAS unsigned*)(lds + (bufoff) + ldsw + _i * 8192), 16, 0, 0); } while (0)
; #define PG8_LDA(dst, b, h) do { _Pragma("unroll") for (int m = 0; m < 4; ++m) _Pragma("unroll") for (int k = 0; k < 2; ++k) dst[m][k] = *(const PG8_LAS bf16x8*)(lds + PG8_SA(b, h) + aoff + m * 2048 + k * 1024); } while (0)
; #define PG8_LDB(dst, b, h) do { _Pragma("unroll") for (int n = 0; n < 2; ++n) _Pragma("unroll") for (int k = 0; k < 2; ++k) dst[n][k] = *(const PG8_LAS bf16x8*)(lds + PG8_SB(b, h) + boff + n * 2048 + k * 1024); } while (0)
; #define PG8_MMA(ai, bj, At, Bt) do { __builtin_amdgcn_s_setprio(1); _Pragma("unroll") for (int m = 0; m < 4; ++m) _Pragma("unroll") for (int n = 0; n < 2; ++n) _Pragma("unroll") for (int k = 0; k < 2; ++k) \
;         acc[ai][bj][m][n] = __builtin_amdgcn_mfma_f32_16x16x32_bf16(Bt[n][k], At[m][k], acc[ai][bj][m][n], 0, 0, 0); __builtin_amdgcn_s_setprio(0); } while (0)
; #define PG8_WAIT_V(n) asm volatile("s_waitcnt vmcnt(" #n ")" ::: "memory")
; #define PG8_WAIT_L(n) asm volatile("s_waitcnt lgkmcnt(" #n ")" ::: "memory")
; #define PG8_BAR __builtin_amdgcn_s_barrier()
; #define PG8_SCHED __builtin_amdgcn_sched_barrier(0)
; template <class Epi, class Sched, bool ALIGN_EPI = false, bool SP2 = false>
; __device__ __forceinline__ void gemm_phase(PG8_LAS unsigned char* lds, const Gemm g, const Sched& S, const Epi& E, const int wv  ) {
;     ...
;             const bool last = (t == nt - 2);
;             const char* a1 = cA + (size_t)(t + 1) * kstep;
;             const char* a2 = last ? nA : cA + (size_t)(t + 2) * kstep; const char* b2 = last ? nB : cB + (size_t)(t + 2) * kstep;
;             const char* a3 = a2 + kstep; const char* b3 = b2 + kstep;
;             if (last && has_next) S.a_ready(nxt);
;             if constexpr (SP2) {
;             PG8_LDB(B0, 0, 0); PG8_LDB(B1, 0, 1); PG8_SCHED; PG8_LDA(At, 0, 0); PG8_STAGE(PG8_SA(1, 1), a1 + hstepA, voffA);
;             PG8_WAIT_V(8); PG8_WAIT_L(0); PG8_BAR; PG8_MMA(0, 0, At, B0); PG8_MMA(0, 1, At, B1); PG8_BAR; PG8_SCHED;
;             PG8_LDA(At, 0, 1); PG8_STAGE(PG8_SB(0, 0), b2, voffB); PG8_STAGE(PG8_SB(0, 1), b2 + hstepB, voffB); PG8_STAGE(PG8_SA(0, 0), a2, voffA);
.LBB0_2756:
	ds_read_b128 v[146:149], v152
	ds_read_b128 v[156:159], v152 offset:1024
	ds_read_b128 v[160:163], v152 offset:2048
	ds_read_b128 v[164:167], v152 offset:3072
	ds_read_b128 v[168:171], v153
	ds_read_b128 v[172:175], v153 offset:1024
	ds_read_b128 v[176:179], v153 offset:2048
	ds_read_b128 v[180:183], v153 offset:3072
	s_add_u32 s54, s52, 0x100
	s_addc_u32 s55, s53, 0
	s_cmpk_eq_i32 s84, 0xa8
	s_cselect_b32 s59, s7, s55
	s_cselect_b32 s58, s6, s54
	s_cselect_b32 s57, s51, s83
	s_cselect_b32 s56, s50, s82
	v_lshl_add_u64 v[216:217], s[52:53], 0, v[138:139]
	s_add_i32 m0, s63, 0xc000
	ds_read_b128 v[184:187], v154
	ds_read_b128 v[188:191], v154 offset:1024
	ds_read_b128 v[192:195], v154 offset:2048
	ds_read_b128 v[196:199], v154 offset:3072
	ds_read_b128 v[200:203], v154 offset:4096
	ds_read_b128 v[204:207], v154 offset:5120
	ds_read_b128 v[208:211], v154 offset:6144
	ds_read_b128 v[212:215], v154 offset:7168
	global_load_lds_dwordx4 v[216:217], off
	v_lshl_add_u64 v[216:217], s[52:53], 0, v[140:141]
	s_add_i32 m0, s63, 0xe000
	s_nop 0
	global_load_lds_dwordx4 v[216:217], off
	s_waitcnt vmcnt(8)
	s_waitcnt lgkmcnt(0)
	s_barrier
	s_setprio 2
	s_waitcnt lgkmcnt(0)
	v_mfma_f32_16x16x32_bf16 v[76:79], v[146:149], v[184:187], v[76:79]
	v_mfma_f32_16x16x32_bf16 v[72:75], v[160:163], v[184:187], v[72:75]
	v_mfma_f32_16x16x32_bf16 v[68:71], v[146:149], v[192:195], v[68:71]
	v_mfma_f32_16x16x32_bf16 v[64:67], v[160:163], v[192:195], v[64:67]
	v_mfma_f32_16x16x32_bf16 v[56:59], v[146:149], v[200:203], v[56:59]
	v_mfma_f32_16x16x32_bf16 v[52:55], v[160:163], v[200:203], v[52:55]
	v_mfma_f32_16x16x32_bf16 v[44:47], v[146:149], v[208:211], v[44:47]
	v_mfma_f32_16x16x32_bf16 v[40:43], v[160:163], v[208:211], v[40:43]
	v_mfma_f32_16x16x32_bf16 v[76:79], v[156:159], v[188:191], v[76:79]
	v_mfma_f32_16x16x32_bf16 v[72:75], v[164:167], v[188:191], v[72:75]
	v_mfma_f32_16x16x32_bf16 v[68:71], v[156:159], v[196:199], v[68:71]
	v_mfma_f32_16x16x32_bf16 v[64:67], v[164:167], v[196:199], v[64:67]
	v_mfma_f32_16x16x32_bf16 v[56:59], v[156:159], v[204:207], v[56:59]
	v_mfma_f32_16x16x32_bf16 v[52:55], v[164:167], v[204:207], v[52:55]
	v_mfma_f32_16x16x32_bf16 v[44:47], v[156:159], v[212:215], v[44:47]
	v_mfma_f32_16x16x32_bf16 v[40:43], v[164:167], v[212:215], v[40:43]
	s_setprio 0
	s_setprio 2
	v_mfma_f32_16x16x32_bf16 v[124:127], v[168:171], v[184:187], v[124:127]
	v_mfma_f32_16x16x32_bf16 v[120:123], v[176:179], v[184:187], v[120:123]
	v_mfma_f32_16x16x32_bf16 v[116:119], v[168:171], v[192:195], v[116:119]
	v_mfma_f32_16x16x32_bf16 v[112:115], v[176:179], v[192:195], v[112:115]
	v_mfma_f32_16x16x32_bf16 v[108:111], v[168:171], v[200:203], v[108:111]
	v_mfma_f32_16x16x32_bf16 v[104:107], v[176:179], v[200:203], v[104:107]
	v_mfma_f32_16x16x32_bf16 v[100:103], v[168:171], v[208:211], v[100:103]
	v_mfma_f32_16x16x32_bf16 v[96:99], v[176:179], v[208:211], v[96:99]
	v_mfma_f32_16x16x32_bf16 v[124:127], v[172:175], v[188:191], v[124:127]
	v_mfma_f32_16x16x32_bf16 v[120:123], v[180:183], v[188:191], v[120:123]
	v_mfma_f32_16x16x32_bf16 v[116:119], v[172:175], v[196:199], v[116:119]
	v_mfma_f32_16x16x32_bf16 v[112:115], v[180:183], v[196:199], v[112:115]
	v_mfma_f32_16x16x32_bf16 v[108:111], v[172:175], v[204:207], v[108:111]
	v_mfma_f32_16x16x32_bf16 v[104:107], v[180:183], v[204:207], v[104:107]
	v_mfma_f32_16x16x32_bf16 v[100:103], v[172:175], v[212:215], v[100:103]
	s_setprio 3
	s_barrier
	v_mfma_f32_16x16x32_bf16 v[96:99], v[180:183], v[212:215], v[96:99]
	s_setprio 0
	s_add_i32 s52, s72, s62
	v_lshl_add_u64 v[216:217], s[56:57], 0, v[130:131]
	s_mov_b32 m0, s52
	ds_read_b128 v[184:187], v154 offset:16384
	ds_read_b128 v[188:191], v154 offset:17408
	ds_read_b128 v[192:195], v154 offset:18432
	ds_read_b128 v[196:199], v154 offset:19456
	ds_read_b128 v[200:203], v154 offset:20480
	ds_read_b128 v[204:207], v154 offset:21504
	ds_read_b128 v[208:211], v154 offset:22528
	ds_read_b128 v[212:215], v154 offset:23552
	global_load_lds_dwordx4 v[216:217], off
	s_add_i32 m0, s52, 0x2000
	s_add_u32 s52, s56, 0x2b0000
	v_lshl_add_u64 v[218:219], s[56:57], 0, v[134:135]
	s_addc_u32 s53, s57, 0
	s_add_i32 s85, s73, s62
	global_load_lds_dwordx4 v[218:219], off
	v_lshl_add_u64 v[220:221], s[52:53], 0, v[130:131]
	s_mov_b32 m0, s85
	v_lshl_add_u64 v[222:223], s[58:59], 0, v[132:133]
	global_load_lds_dwordx4 v[220:221], off
	v_lshl_add_u64 v[220:221], s[52:53], 0, v[134:135]
	s_add_i32 m0, s85, 0x2000
	s_nop 0
	global_load_lds_dwordx4 v[220:221], off
	v_lshl_add_u64 v[220:221], s[58:59], 0, v[128:129]
	s_mov_b32 m0, s63
	s_nop 0
	global_load_lds_dwordx4 v[220:221], off
	s_mov_b32 m0, s64
	s_nop 0
	global_load_lds_dwordx4 v[222:223], off
	s_waitcnt vmcnt(8)
	s_waitcnt lgkmcnt(0)
	s_barrier
; #define PG8_STAGE(bufoff, gbase, voff) do { _Pragma("unroll") for (int _i = 0; _i < 2; ++_i) \
;         __builtin_amdgcn_global_load_lds((const unsigned*)((const char*)(gbase) + (voff)[_i]), (PG8_LAS unsigned*)(lds + (bufoff) + ldsw + _i * 8192), 16, 0, 0); } while (0)
; #define PG8_LDA(dst, b, h) do { _Pragma("unroll") for (int m = 0; m < 4; ++m) _Pragma("unroll") for (int k = 0; k < 2; ++k) dst[m][k] = *(const PG8_LAS bf16x8*)(lds + PG8_SA(b, h) + aoff + m * 2048 + k * 1024); } while (0)
; #define PG8_LDB(dst, b, h) do { _Pragma("unroll") for (int n = 0; n < 2; ++n) _Pragma("unroll") for (int k = 0; k < 2; ++k) dst[n][k] = *(const PG8_LAS bf16x8*)(lds + PG8_SB(b, h) + boff + n * 2048 + k * 1024); } while (0)
; #define PG8_MMA(ai, bj, At, Bt) do { __builtin_amdgcn_s_setprio(1); _Pragma("unroll") for (int m = 0; m < 4; ++m) _Pragma("unroll") for (int n = 0; n < 2; ++n) _Pragma("unroll") for (int k = 0; k < 2; ++k) \
;         acc[ai][bj][m][n] = __builtin_amdgcn_mfma_f32_16x16x32_bf16(Bt[n][k], At[m][k], acc[ai][bj][m][n], 0, 0, 0); __builtin_amdgcn_s_setprio(0); } while (0)
; #define PG8_WAIT_V(n) asm volatile("s_waitcnt vmcnt(" #n ")" ::: "memory")
; #define PG8_WAIT_L(n) asm volatile("s_waitcnt lgkmcnt(" #n ")" ::: "memory")
; #define PG8_BAR __builtin_amdgcn_s_barrier()
; #define PG8_SCHED __builtin_amdgcn_sched_barrier(0)
; template <class Epi, class Sched, bool ALIGN_EPI = false, bool SP2 = false>
; __device__ __forceinline__ void gemm_phase(PG8_LAS unsigned char* lds, const Gemm g, const Sched& S, const Epi& E, const int wv  ) {
;     ...
;             PG8_WAIT_V(8); PG8_WAIT_L(0); PG8_BAR; PG8_MMA(1, 0, At, B0); PG8_MMA(1, 1, At, B1); PG8_BAR; PG8_SCHED;
;             PG8_LDB(B0, 1, 0); PG8_LDB(B1, 1, 1); PG8_SCHED; PG8_LDA(At, 1, 0); PG8_STAGE(PG8_SA(0, 1), a2 + hstepA, voffA);
;             PG8_WAIT_V(8); PG8_WAIT_L(0); PG8_BAR; PG8_MMA(0, 0, At, B0); PG8_MMA(0, 1, At, B1); PG8_BAR; PG8_SCHED;
	s_setprio 2
	s_waitcnt lgkmcnt(0)
	v_mfma_f32_16x16x32_bf16 v[28:31], v[146:149], v[184:187], v[28:31]
	v_mfma_f32_16x16x32_bf16 v[24:27], v[160:163], v[184:187], v[24:27]
	v_mfma_f32_16x16x32_bf16 v[20:23], v[146:149], v[192:195], v[20:23]
	v_mfma_f32_16x16x32_bf16 v[16:19], v[160:163], v[192:195], v[16:19]
	v_mfma_f32_16x16x32_bf16 v[12:15], v[146:149], v[200:203], v[12:15]
	v_mfma_f32_16x16x32_bf16 v[8:11], v[160:163], v[200:203], v[8:11]
	v_mfma_f32_16x16x32_bf16 v[4:7], v[146:149], v[208:211], v[4:7]
	v_mfma_f32_16x16x32_bf16 v[0:3], v[160:163], v[208:211], v[0:3]
	v_mfma_f32_16x16x32_bf16 v[28:31], v[156:159], v[188:191], v[28:31]
	v_mfma_f32_16x16x32_bf16 v[24:27], v[164:167], v[188:191], v[24:27]
	v_mfma_f32_16x16x32_bf16 v[20:23], v[156:159], v[196:199], v[20:23]
	v_mfma_f32_16x16x32_bf16 v[16:19], v[164:167], v[196:199], v[16:19]
	v_mfma_f32_16x16x32_bf16 v[12:15], v[156:159], v[204:207], v[12:15]
	v_mfma_f32_16x16x32_bf16 v[8:11], v[164:167], v[204:207], v[8:11]
	v_mfma_f32_16x16x32_bf16 v[4:7], v[156:159], v[212:215], v[4:7]
	v_mfma_f32_16x16x32_bf16 v[0:3], v[164:167], v[212:215], v[0:3]
	s_setprio 0
	s_setprio 2
	v_mfma_f32_16x16x32_bf16 v[92:95], v[168:171], v[184:187], v[92:95]
	v_mfma_f32_16x16x32_bf16 v[88:91], v[176:179], v[184:187], v[88:91]
	v_mfma_f32_16x16x32_bf16 v[84:87], v[168:171], v[192:195], v[84:87]
	v_mfma_f32_16x16x32_bf16 v[80:83], v[176:179], v[192:195], v[80:83]
	v_mfma_f32_16x16x32_bf16 v[60:63], v[168:171], v[200:203], v[60:63]
	v_mfma_f32_16x16x32_bf16 v[48:51], v[176:179], v[200:203], v[48:51]
	v_mfma_f32_16x16x32_bf16 v[36:39], v[168:171], v[208:211], v[36:39]
	v_mfma_f32_16x16x32_bf16 v[32:35], v[176:179], v[208:211], v[32:35]
	v_mfma_f32_16x16x32_bf16 v[92:95], v[172:175], v[188:191], v[92:95]
	v_mfma_f32_16x16x32_bf16 v[88:91], v[180:183], v[188:191], v[88:91]
	v_mfma_f32_16x16x32_bf16 v[84:87], v[172:175], v[196:199], v[84:87]
	v_mfma_f32_16x16x32_bf16 v[80:83], v[180:183], v[196:199], v[80:83]
	v_mfma_f32_16x16x32_bf16 v[60:63], v[172:175], v[204:207], v[60:63]
	v_mfma_f32_16x16x32_bf16 v[48:51], v[180:183], v[204:207], v[48:51]
	v_mfma_f32_16x16x32_bf16 v[36:39], v[172:175], v[212:215], v[36:39]
	s_setprio 3
	s_barrier
	v_mfma_f32_16x16x32_bf16 v[32:35], v[180:183], v[212:215], v[32:35]
	s_setprio 0
	s_add_i32 s85, 0, 0x18000
	v_add_u32_e32 v155, s85, v150
	s_add_i32 s86, 0, 0x1c000
	ds_read_b128 v[146:149], v155
	ds_read_b128 v[156:159], v155 offset:1024
	ds_read_b128 v[160:163], v155 offset:2048
	ds_read_b128 v[164:167], v155 offset:3072
	v_add_u32_e32 v155, s86, v150
	ds_read_b128 v[168:171], v155
	ds_read_b128 v[172:175], v155 offset:1024
	ds_read_b128 v[176:179], v155 offset:2048
	ds_read_b128 v[180:183], v155 offset:3072
	s_add_u32 s52, s58, 0x2b0000
	s_addc_u32 s53, s59, 0
	s_mov_b32 m0, s65
	v_lshl_add_u64 v[224:225], s[52:53], 0, v[128:129]
	ds_read_b128 v[184:187], v154 offset:32768
	ds_read_b128 v[188:191], v154 offset:33792
	ds_read_b128 v[192:195], v154 offset:34816
	ds_read_b128 v[196:199], v154 offset:35840
	ds_read_b128 v[200:203], v154 offset:36864
	ds_read_b128 v[204:207], v154 offset:37888
	ds_read_b128 v[208:211], v154 offset:38912
	ds_read_b128 v[212:215], v154 offset:39936
	global_load_lds_dwordx4 v[224:225], off
	v_lshl_add_u64 v[224:225], s[52:53], 0, v[132:133]
	s_mov_b32 m0, s66
	s_nop 0
	global_load_lds_dwordx4 v[224:225], off
	s_waitcnt vmcnt(8)
	s_waitcnt lgkmcnt(0)
	s_barrier
	s_setprio 2
	s_waitcnt lgkmcnt(0)
	v_mfma_f32_16x16x32_bf16 v[76:79], v[146:149], v[184:187], v[76:79]
	v_mfma_f32_16x16x32_bf16 v[72:75], v[160:163], v[184:187], v[72:75]
	v_mfma_f32_16x16x32_bf16 v[68:71], v[146:149], v[192:195], v[68:71]
	v_mfma_f32_16x16x32_bf16 v[64:67], v[160:163], v[192:195], v[64:67]
	v_mfma_f32_16x16x32_bf16 v[56:59], v[146:149], v[200:203], v[56:59]
	v_mfma_f32_16x16x32_bf16 v[52:55], v[160:163], v[200:203], v[52:55]
	v_mfma_f32_16x16x32_bf16 v[44:47], v[146:149], v[208:211], v[44:47]
	v_mfma_f32_16x16x32_bf16 v[40:43], v[160:163], v[208:211], v[40:43]
	v_mfma_f32_16x16x32_bf16 v[76:79], v[156:159], v[188:191], v[76:79]
	v_mfma_f32_16x16x32_bf16 v[72:75], v[164:167], v[188:191], v[72:75]
	v_mfma_f32_16x16x32_bf16 v[68:71], v[156:159], v[196:199], v[68:71]
	v_mfma_f32_16x16x32_bf16 v[64:67], v[164:167], v[196:199], v[64:67]
	v_mfma_f32_16x16x32_bf16 v[56:59], v[156:159], v[204:207], v[56:59]
	v_mfma_f32_16x16x32_bf16 v[52:55], v[164:167], v[204:207], v[52:55]
	v_mfma_f32_16x16x32_bf16 v[44:47], v[156:159], v[212:215], v[44:47]
	v_mfma_f32_16x16x32_bf16 v[40:43], v[164:167], v[212:215], v[40:43]
	s_setprio 0
	s_setprio 2
	v_mfma_f32_16x16x32_bf16 v[124:127], v[168:171], v[184:187], v[124:127]
	v_mfma_f32_16x16x32_bf16 v[120:123], v[176:179], v[184:187], v[120:123]
	v_mfma_f32_16x16x32_bf16 v[116:119], v[168:171], v[192:195], v[116:119]
	v_mfma_f32_16x16x32_bf16 v[112:115], v[176:179], v[192:195], v[112:115]
	v_mfma_f32_16x16x32_bf16 v[108:111], v[168:171], v[200:203], v[108:111]
	v_mfma_f32_16x16x32_bf16 v[104:107], v[176:179], v[200:203], v[104:107]
	v_mfma_f32_16x16x32_bf16 v[100:103], v[168:171], v[208:211], v[100:103]
	v_mfma_f32_16x16x32_bf16 v[96:99], v[176:179], v[208:211], v[96:99]
	v_mfma_f32_16x16x32_bf16 v[124:127], v[172:175], v[188:191], v[124:127]
	v_mfma_f32_16x16x32_bf16 v[120:123], v[180:183], v[188:191], v[120:123]
	v_mfma_f32_16x16x32_bf16 v[116:119], v[172:175], v[196:199], v[116:119]
	v_mfma_f32_16x16x32_bf16 v[112:115], v[180:183], v[196:199], v[112:115]
	v_mfma_f32_16x16x32_bf16 v[108:111], v[172:175], v[204:207], v[108:111]
	v_mfma_f32_16x16x32_bf16 v[104:107], v[180:183], v[204:207], v[104:107]
	v_mfma_f32_16x16x32_bf16 v[100:103], v[172:175], v[212:215], v[100:103]
	s_setprio 3
	s_barrier
; #define PG8_STAGE(bufoff, gbase, voff) do { _Pragma("unroll") for (int _i = 0; _i < 2; ++_i) \
;         __builtin_amdgcn_global_load_lds((const unsigned*)((const char*)(gbase) + (voff)[_i]), (PG8_LAS unsigned*)(lds + (bufoff) + ldsw + _i * 8192), 16, 0, 0); } while (0)
; #define PG8_LDA(dst, b, h) do { _Pragma("unroll") for (int m = 0; m < 4; ++m) _Pragma("unroll") for (int k = 0; k < 2; ++k) dst[m][k] = *(const PG8_LAS bf16x8*)(lds + PG8_SA(b, h) + aoff + m * 2048 + k * 1024); } while (0)
; #define PG8_MMA(ai, bj, At, Bt) do { __builtin_amdgcn_s_setprio(1); _Pragma("unroll") for (int m = 0; m < 4; ++m) _Pragma("unroll") for (int n = 0; n < 2; ++n) _Pragma("unroll") for (int k = 0; k < 2; ++k) \
;         acc[ai][bj][m][n] = __builtin_amdgcn_mfma_f32_16x16x32_bf16(Bt[n][k], At[m][k], acc[ai][bj][m][n], 0, 0, 0); __builtin_amdgcn_s_setprio(0); } while (0)
; #define PG8_WAIT_V(n) asm volatile("s_waitcnt vmcnt(" #n ")" ::: "memory")
; #define PG8_WAIT_L(n) asm volatile("s_waitcnt lgkmcnt(" #n ")" ::: "memory")
; #define PG8_BAR __builtin_amdgcn_s_barrier()
; #define PG8_SCHED __builtin_amdgcn_sched_barrier(0)
; template <class Epi, class Sched, bool ALIGN_EPI = false, bool SP2 = false>
; __device__ __forceinline__ void gemm_phase(PG8_LAS unsigned char* lds, const Gemm g, const Sched& S, const Epi& E, const int wv  ) {
;     ...
;             PG8_LDA(At, 1, 1); PG8_STAGE(PG8_SB(1, 0), b3, voffB); PG8_STAGE(PG8_SB(1, 1), b3 + hstepB, voffB); PG8_STAGE(PG8_SA(1, 0), a3, voffA);
;             PG8_WAIT_V(8); PG8_WAIT_L(0); PG8_BAR; PG8_MMA(1, 0, At, B0); PG8_MMA(1, 1, At, B1); PG8_BAR; PG8_SCHED;
;     ...
;         if constexpr (ALIGN_EPI) { if (wr == 0) PG8_BAR; }
	v_mfma_f32_16x16x32_bf16 v[96:99], v[180:183], v[212:215], v[96:99]
	s_setprio 0
	s_add_i32 s52, s85, s62
	v_lshl_add_u64 v[216:217], v[216:217], 0, s[12:13]
	s_mov_b32 m0, s52
	ds_read_b128 v[184:187], v154 offset:49152
	ds_read_b128 v[188:191], v154 offset:50176
	ds_read_b128 v[192:195], v154 offset:51200
	ds_read_b128 v[196:199], v154 offset:52224
	ds_read_b128 v[200:203], v154 offset:53248
	ds_read_b128 v[204:207], v154 offset:54272
	ds_read_b128 v[208:211], v154 offset:55296
	ds_read_b128 v[212:215], v154 offset:56320
	global_load_lds_dwordx4 v[216:217], off
	s_add_i32 m0, s52, 0x2000
	s_add_u32 s52, s56, 0x2b0080
	v_lshl_add_u64 v[216:217], v[218:219], 0, s[12:13]
	s_addc_u32 s53, s57, 0
	s_add_i32 s56, s86, s62
	global_load_lds_dwordx4 v[216:217], off
	v_lshl_add_u64 v[216:217], s[52:53], 0, v[130:131]
	s_mov_b32 m0, s56
	s_nop 0
	global_load_lds_dwordx4 v[216:217], off
	v_lshl_add_u64 v[216:217], s[52:53], 0, v[134:135]
	s_add_i32 m0, s56, 0x2000
	s_nop 0
	global_load_lds_dwordx4 v[216:217], off
	v_lshl_add_u64 v[216:217], v[220:221], 0, s[12:13]
	s_mov_b32 m0, s69
	s_nop 0
	global_load_lds_dwordx4 v[216:217], off
	v_lshl_add_u64 v[216:217], v[222:223], 0, s[12:13]
	s_mov_b32 m0, s70
	s_nop 0
	global_load_lds_dwordx4 v[216:217], off
	s_waitcnt vmcnt(8)
	s_waitcnt lgkmcnt(0)
	s_barrier
	s_setprio 2
	s_waitcnt lgkmcnt(0)
	v_mfma_f32_16x16x32_bf16 v[28:31], v[146:149], v[184:187], v[28:31]
	v_mfma_f32_16x16x32_bf16 v[24:27], v[160:163], v[184:187], v[24:27]
	v_mfma_f32_16x16x32_bf16 v[20:23], v[146:149], v[192:195], v[20:23]
	v_mfma_f32_16x16x32_bf16 v[16:19], v[160:163], v[192:195], v[16:19]
	v_mfma_f32_16x16x32_bf16 v[12:15], v[146:149], v[200:203], v[12:15]
	v_mfma_f32_16x16x32_bf16 v[8:11], v[160:163], v[200:203], v[8:11]
	v_mfma_f32_16x16x32_bf16 v[4:7], v[146:149], v[208:211], v[4:7]
	v_mfma_f32_16x16x32_bf16 v[0:3], v[160:163], v[208:211], v[0:3]
	v_mfma_f32_16x16x32_bf16 v[28:31], v[156:159], v[188:191], v[28:31]
	v_mfma_f32_16x16x32_bf16 v[24:27], v[164:167], v[188:191], v[24:27]
	v_mfma_f32_16x16x32_bf16 v[20:23], v[156:159], v[196:199], v[20:23]
	v_mfma_f32_16x16x32_bf16 v[16:19], v[164:167], v[196:199], v[16:19]
	v_mfma_f32_16x16x32_bf16 v[12:15], v[156:159], v[204:207], v[12:15]
	v_mfma_f32_16x16x32_bf16 v[8:11], v[164:167], v[204:207], v[8:11]
	v_mfma_f32_16x16x32_bf16 v[4:7], v[156:159], v[212:215], v[4:7]
	v_mfma_f32_16x16x32_bf16 v[0:3], v[164:167], v[212:215], v[0:3]
	s_setprio 0
	s_setprio 2
	v_mfma_f32_16x16x32_bf16 v[92:95], v[168:171], v[184:187], v[92:95]
	v_mfma_f32_16x16x32_bf16 v[88:91], v[176:179], v[184:187], v[88:91]
	v_mfma_f32_16x16x32_bf16 v[84:87], v[168:171], v[192:195], v[84:87]
	v_mfma_f32_16x16x32_bf16 v[80:83], v[176:179], v[192:195], v[80:83]
	v_mfma_f32_16x16x32_bf16 v[60:63], v[168:171], v[200:203], v[60:63]
	v_mfma_f32_16x16x32_bf16 v[48:51], v[176:179], v[200:203], v[48:51]
	v_mfma_f32_16x16x32_bf16 v[36:39], v[168:171], v[208:211], v[36:39]
	v_mfma_f32_16x16x32_bf16 v[32:35], v[176:179], v[208:211], v[32:35]
	v_mfma_f32_16x16x32_bf16 v[92:95], v[172:175], v[188:191], v[92:95]
	v_mfma_f32_16x16x32_bf16 v[88:91], v[180:183], v[188:191], v[88:91]
	v_mfma_f32_16x16x32_bf16 v[84:87], v[172:175], v[196:199], v[84:87]
	v_mfma_f32_16x16x32_bf16 v[80:83], v[180:183], v[196:199], v[80:83]
	v_mfma_f32_16x16x32_bf16 v[60:63], v[172:175], v[204:207], v[60:63]
	v_mfma_f32_16x16x32_bf16 v[48:51], v[180:183], v[204:207], v[48:51]
	v_mfma_f32_16x16x32_bf16 v[36:39], v[172:175], v[212:215], v[36:39]
	s_setprio 3
	s_barrier
	v_mfma_f32_16x16x32_bf16 v[32:35], v[180:183], v[212:215], v[32:35]
	s_setprio 0
	s_add_i32 s84, s84, 2
	s_add_u32 s82, s82, 0x100
	s_addc_u32 s83, s83, 0
	s_cmpk_gt_u32 s84, 0xa9
	s_mov_b64 s[52:53], s[54:55]
	s_cbranch_scc0 .LBB0_2756
	s_and_b64 vcc, exec, s[14:15]
	s_cbranch_vccz .LBB0_2759
	s_barrier
